# first sample-pool claim issued at the start of pass-2 tile 7 (lever: prologue de-serialisation); on top of v67
# baseline (speedup 1.0000x reference)
.LBB0_1063:
	v_lshl_add_u64 v[2:3], s[58:59], 0, v[2:3]
	v_lshl_add_u64 v[4:5], s[58:59], 0, v[4:5]
	global_load_dwordx4 v[94:97], v[2:3], off
	global_load_dwordx4 v[90:93], v[4:5], off
	v_lshl_add_u64 v[2:3], s[58:59], 0, v[6:7]
	v_lshl_add_u64 v[4:5], s[58:59], 0, v[8:9]
	global_load_dwordx4 v[86:89], v[2:3], off
	global_load_dwordx4 v[82:85], v[4:5], off
	s_lshl_b32 s0, s2, 4
	s_lshl_b32 s1, s0, 2
	v_readlane_b32 s4, v252, 48
	v_readlane_b32 s5, v252, 49
	v_lshrrev_b32_e32 v1, 4, v148
	s_add_u32 s4, s4, s1
	s_addc_u32 s5, s5, 0
	v_lshlrev_b32_e32 v178, 4, v1
	v_and_b32_e32 v176, 15, v148
	v_lshlrev_b32_e32 v176, 10, v176
	global_load_dwordx4 v[98:101], v178, s[4:5]
	v_lshl_or_b32 v176, v1, 3, v176
	v_add_u32_e32 v177, 0x4000, v176
	s_lshl_b64 s[8:9], s[56:57], 10
	s_add_u32 s6, s66, s8
	s_addc_u32 s7, s67, s9
	s_lshl_b32 s1, s0, 1
	s_add_u32 s10, s74, s1
	s_addc_u32 s11, s75, 0
	s_add_u32 s10, s10, s8
	s_addc_u32 s11, s11, s9
	v_and_b32_e32 v1, 31, v148
	v_mul_u32_u24_e32 v174, 0x1100, v149
	v_lshlrev_b32_e32 v1, 2, v1
	v_add3_u32 v174, s3, v174, v1
	v_and_b32_e32 v1, 15, v148
	v_mul_u32_u24_e32 v175, 0x110, v1
	v_add3_u32 v175, s3, v175, v178
	v_cmp_lt_u32_e32 vcc, 31, v148
	s_waitcnt vmcnt(12)
	v_mfma_f32_32x32x16_bf16 v[50:65], v[18:21], v[114:117], 0
	v_mfma_f32_32x32x16_bf16 v[2:17], v[18:21], v[110:113], 0
	v_mfma_f32_32x32x16_bf16 v[34:49], v[18:21], v[106:109], 0
	v_mfma_f32_32x32x16_bf16 v[18:33], v[18:21], v[102:105], 0
	global_load_dwordx2 v[160:161], v176, s[6:7]
	global_load_dwordx2 v[162:163], v177, s[6:7]
	v_mov_b32_e32 v1, v79
	v_mov_b32_e32 v79, v80
	v_mov_b32_e32 v80, v1
	v_mov_b32_e32 v1, v71
	v_mov_b32_e32 v71, v72
	v_mov_b32_e32 v72, v1
	v_mov_b32_e32 v1, v75
	v_mov_b32_e32 v75, v76
	v_mov_b32_e32 v76, v1
	v_mov_b32_e32 v1, v67
	v_mov_b32_e32 v67, v68
	v_mov_b32_e32 v68, v1
	v_mul_f32_e32 v156, v71, v71
	v_mul_f32_e32 v157, v71, v73
	v_fma_f32 v156, -v73, v73, v156
	v_add_f32_e32 v157, v157, v157
	v_mul_f32_e32 v152, v156, v156
	v_mul_f32_e32 v153, v156, v157
	v_fma_f32 v152, -v157, v157, v152
	v_add_f32_e32 v153, v153, v153
	v_mul_f32_e32 v156, v67, v67
	v_mul_f32_e32 v157, v67, v69
	v_fma_f32 v156, -v69, v69, v156
	v_add_f32_e32 v157, v157, v157
	v_mul_f32_e32 v154, v156, v156
	v_mul_f32_e32 v155, v156, v157
	v_fma_f32 v154, -v157, v157, v154
	v_add_f32_e32 v155, v155, v155
	v_fmac_f32_e32 v51, v78, v50
	v_fmac_f32_e32 v35, v74, v34
	v_fmac_f32_e32 v3, v80, v50
	v_fmac_f32_e32 v19, v76, v34
	v_fma_f32 v51, -v80, v2, v51
	v_fma_f32 v35, -v76, v18, v35
	v_fmac_f32_e32 v3, v78, v2
	v_fmac_f32_e32 v19, v74, v18
	v_fmac_f32_e32 v52, v78, v51
	v_fmac_f32_e32 v36, v74, v35
	v_fmac_f32_e32 v4, v80, v51
	v_fmac_f32_e32 v20, v76, v35
	v_fma_f32 v52, -v80, v3, v52
	v_fma_f32 v36, -v76, v19, v36
	v_fmac_f32_e32 v4, v78, v3
	v_fmac_f32_e32 v20, v74, v19
	v_fmac_f32_e32 v53, v78, v52
	v_fmac_f32_e32 v37, v74, v36
	v_fmac_f32_e32 v5, v80, v52
	v_fmac_f32_e32 v21, v76, v36
	v_fma_f32 v53, -v80, v4, v53
	v_fma_f32 v37, -v76, v20, v37
	v_fmac_f32_e32 v5, v78, v4
	v_fmac_f32_e32 v21, v74, v20
	v_fmac_f32_e32 v54, v78, v53
	v_fmac_f32_e32 v38, v74, v37
	v_fmac_f32_e32 v6, v80, v53
	v_fmac_f32_e32 v22, v76, v37
	v_fma_f32 v54, -v80, v5, v54
	v_fma_f32 v38, -v76, v21, v38
	v_fmac_f32_e32 v6, v78, v5
	v_fmac_f32_e32 v22, v74, v21
	v_fmac_f32_e32 v55, v78, v54
	v_fmac_f32_e32 v39, v74, v38
	v_fmac_f32_e32 v7, v80, v54
	v_fmac_f32_e32 v23, v76, v38
	v_fma_f32 v55, -v80, v6, v55
	v_fma_f32 v39, -v76, v22, v39
	v_fmac_f32_e32 v7, v78, v6
	v_fmac_f32_e32 v23, v74, v22
	v_fmac_f32_e32 v56, v78, v55
	v_fmac_f32_e32 v40, v74, v39
	v_fmac_f32_e32 v8, v80, v55
	v_fmac_f32_e32 v24, v76, v39
	v_fma_f32 v56, -v80, v7, v56
	v_fma_f32 v40, -v76, v23, v40
	v_fmac_f32_e32 v8, v78, v7
	v_fmac_f32_e32 v24, v74, v23
	v_fmac_f32_e32 v57, v78, v56
	v_fmac_f32_e32 v41, v74, v40
	v_fmac_f32_e32 v9, v80, v56
	v_fmac_f32_e32 v25, v76, v40
	v_fma_f32 v57, -v80, v8, v57
	v_fma_f32 v41, -v76, v24, v41
	v_fmac_f32_e32 v9, v78, v8
	v_fmac_f32_e32 v25, v74, v24
	v_fmac_f32_e32 v58, v78, v57
	v_fmac_f32_e32 v42, v74, v41
	v_fmac_f32_e32 v10, v80, v57
	v_fmac_f32_e32 v26, v76, v41
	v_fma_f32 v58, -v80, v9, v58
	v_fma_f32 v42, -v76, v25, v42
	v_fmac_f32_e32 v10, v78, v9
	v_fmac_f32_e32 v26, v74, v25
	v_fmac_f32_e32 v59, v78, v58
	v_fmac_f32_e32 v43, v74, v42
	v_fmac_f32_e32 v11, v80, v58
	v_fmac_f32_e32 v27, v76, v42
	v_fma_f32 v59, -v80, v10, v59
	v_fma_f32 v43, -v76, v26, v43
	v_fmac_f32_e32 v11, v78, v10
	v_fmac_f32_e32 v27, v74, v26
	v_fmac_f32_e32 v60, v78, v59
	v_fmac_f32_e32 v44, v74, v43
	v_fmac_f32_e32 v12, v80, v59
	v_fmac_f32_e32 v28, v76, v43
	v_fma_f32 v60, -v80, v11, v60
	v_fma_f32 v44, -v76, v27, v44
	v_fmac_f32_e32 v12, v78, v11
	v_fmac_f32_e32 v28, v74, v27
	v_fmac_f32_e32 v61, v78, v60
	v_fmac_f32_e32 v45, v74, v44
	v_fmac_f32_e32 v13, v80, v60
	v_fmac_f32_e32 v29, v76, v44
	v_fma_f32 v61, -v80, v12, v61
	v_fma_f32 v45, -v76, v28, v45
	v_fmac_f32_e32 v13, v78, v12
	v_fmac_f32_e32 v29, v74, v28
	v_fmac_f32_e32 v62, v78, v61
	v_fmac_f32_e32 v46, v74, v45
	v_fmac_f32_e32 v14, v80, v61
	v_fmac_f32_e32 v30, v76, v45
	v_fma_f32 v62, -v80, v13, v62
	v_fma_f32 v46, -v76, v29, v46
	v_fmac_f32_e32 v14, v78, v13
	v_fmac_f32_e32 v30, v74, v29
	v_fmac_f32_e32 v63, v78, v62
	v_fmac_f32_e32 v47, v74, v46
	v_fmac_f32_e32 v15, v80, v62
	v_fmac_f32_e32 v31, v76, v46
	v_fma_f32 v63, -v80, v14, v63
	v_fma_f32 v47, -v76, v30, v47
	v_fmac_f32_e32 v15, v78, v14
	v_fmac_f32_e32 v31, v74, v30
	v_fmac_f32_e32 v64, v78, v63
	v_fmac_f32_e32 v48, v74, v47
	v_fmac_f32_e32 v16, v80, v63
	v_fmac_f32_e32 v32, v76, v47
	v_fma_f32 v64, -v80, v15, v64
	v_fma_f32 v48, -v76, v31, v48
	v_fmac_f32_e32 v16, v78, v15
	v_fmac_f32_e32 v32, v74, v31
	v_fmac_f32_e32 v65, v78, v64
	v_fmac_f32_e32 v49, v74, v48
	v_fmac_f32_e32 v17, v80, v64
	v_fmac_f32_e32 v33, v76, v48
	v_fma_f32 v65, -v80, v16, v65
	v_fma_f32 v49, -v76, v32, v49
	v_fmac_f32_e32 v17, v78, v16
	v_fmac_f32_e32 v33, v74, v32
	v_mov_b32_e32 v156, v65
	v_mov_b32_e32 v157, v17
	v_mov_b32_e32 v158, v65
	v_mov_b32_e32 v159, v17
	s_nop 1
	v_permlane32_swap_b32_e32 v156, v158
	v_permlane32_swap_b32_e32 v157, v159
	v_pk_fma_f32 v[164:165], v[166:167], v[152:153], v[156:157] op_sel_hi:[1,0,1]
	v_pk_fma_f32 v[164:165], v[166:167], v[152:153], v[164:165] op_sel:[1,1,0] op_sel_hi:[0,1,1] neg_lo:[0,1,0]
	v_cndmask_b32_e32 v164, v166, v164, vcc
	v_cndmask_b32_e32 v165, v167, v165, vcc
	v_mov_b32_e32 v156, v49
	v_mov_b32_e32 v157, v33
	v_mov_b32_e32 v158, v49
	v_mov_b32_e32 v159, v33
	s_nop 1
	v_permlane32_swap_b32_e32 v156, v158
	v_permlane32_swap_b32_e32 v157, v159
	v_pk_fma_f32 v[170:171], v[150:151], v[154:155], v[156:157] op_sel_hi:[1,0,1]
	v_pk_fma_f32 v[170:171], v[150:151], v[154:155], v[170:171] op_sel:[1,1,0] op_sel_hi:[0,1,1] neg_lo:[0,1,0]
	v_cndmask_b32_e32 v170, v150, v170, vcc
	v_cndmask_b32_e32 v171, v151, v171, vcc
	v_pk_mul_f32 v[168:169], v[164:165], v[70:71] op_sel:[0,1] op_sel_hi:[1,1]
	v_pk_mul_f32 v[172:173], v[170:171], v[66:67] op_sel:[0,1] op_sel_hi:[1,1]
	v_pk_fma_f32 v[168:169], v[164:165], v[72:73], v[168:169] op_sel:[1,1,0] op_sel_hi:[0,1,1] neg_lo:[0,1,0]
	v_pk_fma_f32 v[172:173], v[170:171], v[68:69], v[172:173] op_sel:[1,1,0] op_sel_hi:[0,1,1] neg_lo:[0,1,0]
	v_pk_fma_f32 v[50:51], v[78:79], v[164:165], v[50:51] op_sel_hi:[1,0,1]
	v_pk_fma_f32 v[34:35], v[74:75], v[170:171], v[34:35] op_sel_hi:[1,0,1]
	v_pk_fma_f32 v[52:53], v[70:71], v[164:165], v[52:53] op_sel_hi:[1,0,1]
	v_pk_fma_f32 v[36:37], v[66:67], v[170:171], v[36:37] op_sel_hi:[1,0,1]
	v_pk_fma_f32 v[2:3], v[80:81], v[164:165], v[2:3] op_sel_hi:[1,0,1]
	v_pk_fma_f32 v[18:19], v[76:77], v[170:171], v[18:19] op_sel_hi:[1,0,1]
	v_pk_fma_f32 v[4:5], v[72:73], v[164:165], v[4:5] op_sel_hi:[1,0,1]
	v_pk_fma_f32 v[20:21], v[68:69], v[170:171], v[20:21] op_sel_hi:[1,0,1]
	v_pk_fma_f32 v[50:51], v[80:81], v[164:165], v[50:51] op_sel:[0,1,0] op_sel_hi:[1,1,1] neg_lo:[0,1,0] neg_hi:[0,1,0]
	v_pk_fma_f32 v[34:35], v[76:77], v[170:171], v[34:35] op_sel:[0,1,0] op_sel_hi:[1,1,1] neg_lo:[0,1,0] neg_hi:[0,1,0]
	v_pk_fma_f32 v[52:53], v[72:73], v[164:165], v[52:53] op_sel:[0,1,0] op_sel_hi:[1,1,1] neg_lo:[0,1,0] neg_hi:[0,1,0]
	v_pk_fma_f32 v[36:37], v[68:69], v[170:171], v[36:37] op_sel:[0,1,0] op_sel_hi:[1,1,1] neg_lo:[0,1,0] neg_hi:[0,1,0]
	v_pk_fma_f32 v[2:3], v[78:79], v[164:165], v[2:3] op_sel:[0,1,0] op_sel_hi:[1,1,1]
	v_pk_fma_f32 v[18:19], v[74:75], v[170:171], v[18:19] op_sel:[0,1,0] op_sel_hi:[1,1,1]
	v_pk_fma_f32 v[4:5], v[70:71], v[164:165], v[4:5] op_sel:[0,1,0] op_sel_hi:[1,1,1]
	v_pk_fma_f32 v[20:21], v[66:67], v[170:171], v[20:21] op_sel:[0,1,0] op_sel_hi:[1,1,1]
	v_pk_mul_f32 v[164:165], v[168:169], v[70:71] op_sel:[0,1] op_sel_hi:[1,1]
	v_pk_mul_f32 v[170:171], v[172:173], v[66:67] op_sel:[0,1] op_sel_hi:[1,1]
	v_pk_fma_f32 v[164:165], v[168:169], v[72:73], v[164:165] op_sel:[1,1,0] op_sel_hi:[0,1,1] neg_lo:[0,1,0]
	v_pk_fma_f32 v[170:171], v[172:173], v[68:69], v[170:171] op_sel:[1,1,0] op_sel_hi:[0,1,1] neg_lo:[0,1,0]
	v_pk_fma_f32 v[54:55], v[78:79], v[168:169], v[54:55] op_sel_hi:[1,0,1]
	v_pk_fma_f32 v[38:39], v[74:75], v[172:173], v[38:39] op_sel_hi:[1,0,1]
	v_pk_fma_f32 v[56:57], v[70:71], v[168:169], v[56:57] op_sel_hi:[1,0,1]
	v_pk_fma_f32 v[40:41], v[66:67], v[172:173], v[40:41] op_sel_hi:[1,0,1]
	v_pk_fma_f32 v[6:7], v[80:81], v[168:169], v[6:7] op_sel_hi:[1,0,1]
	v_pk_fma_f32 v[22:23], v[76:77], v[172:173], v[22:23] op_sel_hi:[1,0,1]
	v_pk_fma_f32 v[8:9], v[72:73], v[168:169], v[8:9] op_sel_hi:[1,0,1]
	v_pk_fma_f32 v[24:25], v[68:69], v[172:173], v[24:25] op_sel_hi:[1,0,1]
	v_pk_fma_f32 v[54:55], v[80:81], v[168:169], v[54:55] op_sel:[0,1,0] op_sel_hi:[1,1,1] neg_lo:[0,1,0] neg_hi:[0,1,0]
	v_pk_fma_f32 v[38:39], v[76:77], v[172:173], v[38:39] op_sel:[0,1,0] op_sel_hi:[1,1,1] neg_lo:[0,1,0] neg_hi:[0,1,0]
	v_pk_fma_f32 v[56:57], v[72:73], v[168:169], v[56:57] op_sel:[0,1,0] op_sel_hi:[1,1,1] neg_lo:[0,1,0] neg_hi:[0,1,0]
	v_pk_fma_f32 v[40:41], v[68:69], v[172:173], v[40:41] op_sel:[0,1,0] op_sel_hi:[1,1,1] neg_lo:[0,1,0] neg_hi:[0,1,0]
	v_pk_fma_f32 v[6:7], v[78:79], v[168:169], v[6:7] op_sel:[0,1,0] op_sel_hi:[1,1,1]
	v_pk_fma_f32 v[22:23], v[74:75], v[172:173], v[22:23] op_sel:[0,1,0] op_sel_hi:[1,1,1]
	v_pk_fma_f32 v[8:9], v[70:71], v[168:169], v[8:9] op_sel:[0,1,0] op_sel_hi:[1,1,1]
	v_pk_fma_f32 v[24:25], v[66:67], v[172:173], v[24:25] op_sel:[0,1,0] op_sel_hi:[1,1,1]
	v_pk_mul_f32 v[168:169], v[164:165], v[70:71] op_sel:[0,1] op_sel_hi:[1,1]
	v_pk_mul_f32 v[172:173], v[170:171], v[66:67] op_sel:[0,1] op_sel_hi:[1,1]
	v_pk_fma_f32 v[168:169], v[164:165], v[72:73], v[168:169] op_sel:[1,1,0] op_sel_hi:[0,1,1] neg_lo:[0,1,0]
	v_pk_fma_f32 v[172:173], v[170:171], v[68:69], v[172:173] op_sel:[1,1,0] op_sel_hi:[0,1,1] neg_lo:[0,1,0]
	v_pk_fma_f32 v[58:59], v[78:79], v[164:165], v[58:59] op_sel_hi:[1,0,1]
	v_pk_fma_f32 v[42:43], v[74:75], v[170:171], v[42:43] op_sel_hi:[1,0,1]
	v_pk_fma_f32 v[60:61], v[70:71], v[164:165], v[60:61] op_sel_hi:[1,0,1]
	v_pk_fma_f32 v[44:45], v[66:67], v[170:171], v[44:45] op_sel_hi:[1,0,1]
	v_pk_fma_f32 v[10:11], v[80:81], v[164:165], v[10:11] op_sel_hi:[1,0,1]
	v_pk_fma_f32 v[26:27], v[76:77], v[170:171], v[26:27] op_sel_hi:[1,0,1]
	v_pk_fma_f32 v[12:13], v[72:73], v[164:165], v[12:13] op_sel_hi:[1,0,1]
	v_pk_fma_f32 v[28:29], v[68:69], v[170:171], v[28:29] op_sel_hi:[1,0,1]
	v_pk_fma_f32 v[58:59], v[80:81], v[164:165], v[58:59] op_sel:[0,1,0] op_sel_hi:[1,1,1] neg_lo:[0,1,0] neg_hi:[0,1,0]
	v_pk_fma_f32 v[42:43], v[76:77], v[170:171], v[42:43] op_sel:[0,1,0] op_sel_hi:[1,1,1] neg_lo:[0,1,0] neg_hi:[0,1,0]
	v_pk_fma_f32 v[60:61], v[72:73], v[164:165], v[60:61] op_sel:[0,1,0] op_sel_hi:[1,1,1] neg_lo:[0,1,0] neg_hi:[0,1,0]
	v_pk_fma_f32 v[44:45], v[68:69], v[170:171], v[44:45] op_sel:[0,1,0] op_sel_hi:[1,1,1] neg_lo:[0,1,0] neg_hi:[0,1,0]
	v_pk_fma_f32 v[10:11], v[78:79], v[164:165], v[10:11] op_sel:[0,1,0] op_sel_hi:[1,1,1]
	v_pk_fma_f32 v[26:27], v[74:75], v[170:171], v[26:27] op_sel:[0,1,0] op_sel_hi:[1,1,1]
	v_pk_fma_f32 v[12:13], v[70:71], v[164:165], v[12:13] op_sel:[0,1,0] op_sel_hi:[1,1,1]
	v_pk_fma_f32 v[28:29], v[66:67], v[170:171], v[28:29] op_sel:[0,1,0] op_sel_hi:[1,1,1]
	v_pk_fma_f32 v[62:63], v[78:79], v[168:169], v[62:63] op_sel_hi:[1,0,1]
	v_pk_fma_f32 v[46:47], v[74:75], v[172:173], v[46:47] op_sel_hi:[1,0,1]
	v_pk_fma_f32 v[64:65], v[70:71], v[168:169], v[64:65] op_sel_hi:[1,0,1]
	v_pk_fma_f32 v[48:49], v[66:67], v[172:173], v[48:49] op_sel_hi:[1,0,1]
	v_pk_fma_f32 v[14:15], v[80:81], v[168:169], v[14:15] op_sel_hi:[1,0,1]
	v_pk_fma_f32 v[30:31], v[76:77], v[172:173], v[30:31] op_sel_hi:[1,0,1]
	v_pk_fma_f32 v[16:17], v[72:73], v[168:169], v[16:17] op_sel_hi:[1,0,1]
	v_pk_fma_f32 v[32:33], v[68:69], v[172:173], v[32:33] op_sel_hi:[1,0,1]
	v_pk_fma_f32 v[62:63], v[80:81], v[168:169], v[62:63] op_sel:[0,1,0] op_sel_hi:[1,1,1] neg_lo:[0,1,0] neg_hi:[0,1,0]
	v_pk_fma_f32 v[46:47], v[76:77], v[172:173], v[46:47] op_sel:[0,1,0] op_sel_hi:[1,1,1] neg_lo:[0,1,0] neg_hi:[0,1,0]
	v_pk_fma_f32 v[64:65], v[72:73], v[168:169], v[64:65] op_sel:[0,1,0] op_sel_hi:[1,1,1] neg_lo:[0,1,0] neg_hi:[0,1,0]
	v_pk_fma_f32 v[48:49], v[68:69], v[172:173], v[48:49] op_sel:[0,1,0] op_sel_hi:[1,1,1] neg_lo:[0,1,0] neg_hi:[0,1,0]
	v_pk_fma_f32 v[14:15], v[78:79], v[168:169], v[14:15] op_sel:[0,1,0] op_sel_hi:[1,1,1]
	v_pk_fma_f32 v[30:31], v[74:75], v[172:173], v[30:31] op_sel:[0,1,0] op_sel_hi:[1,1,1]
	v_pk_fma_f32 v[16:17], v[70:71], v[168:169], v[16:17] op_sel:[0,1,0] op_sel_hi:[1,1,1]
	v_pk_fma_f32 v[32:33], v[66:67], v[172:173], v[32:33] op_sel:[0,1,0] op_sel_hi:[1,1,1]
	v_mov_b32_e32 v156, v65
	v_mov_b32_e32 v157, v17
	v_mov_b32_e32 v166, v65
	v_mov_b32_e32 v167, v17
	s_nop 1
	v_permlane32_swap_b32_e32 v156, v166
	v_permlane32_swap_b32_e32 v157, v167
	v_mov_b32_e32 v156, v49
	v_mov_b32_e32 v157, v33
	v_mov_b32_e32 v150, v49
	v_mov_b32_e32 v151, v33
	s_nop 1
	v_permlane32_swap_b32_e32 v156, v150
	v_permlane32_swap_b32_e32 v157, v151
	v_cvt_pk_bf16_f32 v1, v50, v2
	ds_write_b32 v174, v1
	v_cvt_pk_bf16_f32 v146, v34, v18
	ds_write_b32 v174, v146 offset:128
	v_cvt_pk_bf16_f32 v178, v51, v3
	ds_write_b32 v174, v178 offset:272
	v_cvt_pk_bf16_f32 v1, v35, v19
	ds_write_b32 v174, v1 offset:400
	v_cvt_pk_bf16_f32 v146, v52, v4
	ds_write_b32 v174, v146 offset:544
	v_cvt_pk_bf16_f32 v178, v36, v20
	ds_write_b32 v174, v178 offset:672
	v_cvt_pk_bf16_f32 v1, v53, v5
	ds_write_b32 v174, v1 offset:816
	v_cvt_pk_bf16_f32 v146, v37, v21
	ds_write_b32 v174, v146 offset:944
	v_cvt_pk_bf16_f32 v178, v54, v6
	ds_write_b32 v174, v178 offset:1088
	v_cvt_pk_bf16_f32 v1, v38, v22
	ds_write_b32 v174, v1 offset:1216
	v_cvt_pk_bf16_f32 v146, v55, v7
	ds_write_b32 v174, v146 offset:1360
	v_cvt_pk_bf16_f32 v178, v39, v23
	ds_write_b32 v174, v178 offset:1488
	v_cvt_pk_bf16_f32 v1, v56, v8
	ds_write_b32 v174, v1 offset:1632
	v_cvt_pk_bf16_f32 v146, v40, v24
	ds_write_b32 v174, v146 offset:1760
	v_cvt_pk_bf16_f32 v178, v57, v9
	ds_write_b32 v174, v178 offset:1904
	v_cvt_pk_bf16_f32 v1, v41, v25
	ds_write_b32 v174, v1 offset:2032
	v_cvt_pk_bf16_f32 v146, v58, v10
	ds_write_b32 v174, v146 offset:2176
	v_cvt_pk_bf16_f32 v178, v42, v26
	ds_write_b32 v174, v178 offset:2304
	v_cvt_pk_bf16_f32 v1, v59, v11
	ds_write_b32 v174, v1 offset:2448
	v_cvt_pk_bf16_f32 v146, v43, v27
	ds_write_b32 v174, v146 offset:2576
	v_cvt_pk_bf16_f32 v178, v60, v12
	ds_write_b32 v174, v178 offset:2720
	v_cvt_pk_bf16_f32 v1, v44, v28
	ds_write_b32 v174, v1 offset:2848
	v_cvt_pk_bf16_f32 v146, v61, v13
	ds_write_b32 v174, v146 offset:2992
	v_cvt_pk_bf16_f32 v178, v45, v29
	ds_write_b32 v174, v178 offset:3120
	v_cvt_pk_bf16_f32 v1, v62, v14
	ds_write_b32 v174, v1 offset:3264
	v_cvt_pk_bf16_f32 v146, v46, v30
	ds_write_b32 v174, v146 offset:3392
	v_cvt_pk_bf16_f32 v178, v63, v15
	ds_write_b32 v174, v178 offset:3536
	v_cvt_pk_bf16_f32 v1, v47, v31
	ds_write_b32 v174, v1 offset:3664
	v_cvt_pk_bf16_f32 v146, v64, v16
	ds_write_b32 v174, v146 offset:3808
	v_cvt_pk_bf16_f32 v178, v48, v32
	ds_write_b32 v174, v178 offset:3936
	v_cvt_pk_bf16_f32 v1, v65, v17
	ds_write_b32 v174, v1 offset:4080
	v_cvt_pk_bf16_f32 v146, v49, v33
	ds_write_b32 v174, v146 offset:4208
	s_waitcnt lgkmcnt(0)
	ds_read_b128 v[2:5], v175
	ds_read_b128 v[6:9], v175 offset:64
	ds_read_b128 v[10:13], v175 offset:128
	ds_read_b128 v[14:17], v175 offset:192
	ds_read_b128 v[18:21], v175 offset:4352
	ds_read_b128 v[22:25], v175 offset:4416
	ds_read_b128 v[26:29], v175 offset:4480
	ds_read_b128 v[30:33], v175 offset:4544
	s_waitcnt vmcnt(0)
	s_waitcnt lgkmcnt(7)
	v_mfma_f32_16x16x32_bf16 v[34:37], v[94:97], v[2:5], 0
	s_waitcnt lgkmcnt(6)
	v_mfma_f32_16x16x32_bf16 v[34:37], v[90:93], v[6:9], v[34:37]
	s_waitcnt lgkmcnt(5)
	v_mfma_f32_16x16x32_bf16 v[34:37], v[86:89], v[10:13], v[34:37]
	s_waitcnt lgkmcnt(4)
	v_mfma_f32_16x16x32_bf16 v[34:37], v[82:85], v[14:17], v[34:37]
	s_waitcnt lgkmcnt(3)
	v_mfma_f32_16x16x32_bf16 v[38:41], v[94:97], v[18:21], 0
	s_waitcnt lgkmcnt(2)
	v_mfma_f32_16x16x32_bf16 v[38:41], v[90:93], v[22:25], v[38:41]
	s_waitcnt lgkmcnt(1)
	v_mfma_f32_16x16x32_bf16 v[38:41], v[86:89], v[26:29], v[38:41]
	s_waitcnt lgkmcnt(0)
	v_mfma_f32_16x16x32_bf16 v[38:41], v[82:85], v[30:33], v[38:41]
	s_add_u32 s6, s6, 0x8000
	s_addc_u32 s7, s7, 0
	v_lshlrev_b32_e32 v42, 16, v160
	v_and_b32_e32 v43, 0xffff0000, v160
	v_lshlrev_b32_e32 v44, 16, v161
	v_and_b32_e32 v45, 0xffff0000, v161
	v_lshlrev_b32_e32 v46, 16, v162
	v_and_b32_e32 v47, 0xffff0000, v162
	v_lshlrev_b32_e32 v48, 16, v163
	v_and_b32_e32 v49, 0xffff0000, v163
	s_nop 1
	v_mov_b32_e32 v156, 0x3d372713
	v_mov_b32_e32 v158, 0xbfcc422a
	v_mov_b32_e32 v164, 0x3fb8aa3b
	v_mov_b32_e32 v168, 1.0
	v_pk_fma_f32 v[50:51], v[98:99], v[42:43], v[34:35]
	v_pk_fma_f32 v[52:53], v[100:101], v[44:45], v[36:37]
	v_pk_fma_f32 v[54:55], v[98:99], v[46:47], v[38:39]
	v_pk_fma_f32 v[56:57], v[100:101], v[48:49], v[40:41]
	v_pk_mul_f32 v[2:3], v[50:51], v[156:157] op_sel_hi:[1,0]
	v_pk_mul_f32 v[4:5], v[52:53], v[156:157] op_sel_hi:[1,0]
	v_pk_mul_f32 v[6:7], v[54:55], v[156:157] op_sel_hi:[1,0]
	v_pk_mul_f32 v[8:9], v[56:57], v[156:157] op_sel_hi:[1,0]
	v_pk_mul_f32 v[2:3], v[50:51], v[2:3]
	v_pk_mul_f32 v[4:5], v[52:53], v[4:5]
	v_pk_mul_f32 v[6:7], v[54:55], v[6:7]
	v_pk_mul_f32 v[8:9], v[56:57], v[8:9]
	v_pk_fma_f32 v[2:3], v[50:51], v[2:3], v[50:51]
	v_pk_fma_f32 v[4:5], v[52:53], v[4:5], v[52:53]
	v_pk_fma_f32 v[6:7], v[54:55], v[6:7], v[54:55]
	v_pk_fma_f32 v[8:9], v[56:57], v[8:9], v[56:57]
	v_pk_mul_f32 v[2:3], v[2:3], v[158:159] op_sel_hi:[1,0]
	v_pk_mul_f32 v[4:5], v[4:5], v[158:159] op_sel_hi:[1,0]
	v_pk_mul_f32 v[6:7], v[6:7], v[158:159] op_sel_hi:[1,0]
	v_pk_mul_f32 v[8:9], v[8:9], v[158:159] op_sel_hi:[1,0]
	v_pk_mul_f32 v[2:3], v[2:3], v[164:165] op_sel_hi:[1,0]
	v_pk_mul_f32 v[4:5], v[4:5], v[164:165] op_sel_hi:[1,0]
	v_pk_mul_f32 v[6:7], v[6:7], v[164:165] op_sel_hi:[1,0]
	v_pk_mul_f32 v[8:9], v[8:9], v[164:165] op_sel_hi:[1,0]
	v_exp_f32_e32 v2, v2
	v_exp_f32_e32 v3, v3
	v_exp_f32_e32 v4, v4
	v_exp_f32_e32 v5, v5
	v_exp_f32_e32 v6, v6
	v_exp_f32_e32 v7, v7
	v_exp_f32_e32 v8, v8
	v_exp_f32_e32 v9, v9
	v_pk_add_f32 v[2:3], v[2:3], v[168:169] op_sel_hi:[1,0]
	v_pk_add_f32 v[4:5], v[4:5], v[168:169] op_sel_hi:[1,0]
	v_pk_add_f32 v[6:7], v[6:7], v[168:169] op_sel_hi:[1,0]
	v_pk_add_f32 v[8:9], v[8:9], v[168:169] op_sel_hi:[1,0]
	v_rcp_f32_e32 v2, v2
	v_rcp_f32_e32 v3, v3
	v_rcp_f32_e32 v4, v4
	v_rcp_f32_e32 v5, v5
	v_rcp_f32_e32 v6, v6
	v_rcp_f32_e32 v7, v7
	v_rcp_f32_e32 v8, v8
	v_rcp_f32_e32 v9, v9
	v_pk_mul_f32 v[50:51], v[50:51], v[2:3]
	v_pk_mul_f32 v[52:53], v[52:53], v[4:5]
	v_pk_mul_f32 v[54:55], v[54:55], v[6:7]
	v_pk_mul_f32 v[56:57], v[56:57], v[8:9]
	v_cvt_pk_bf16_f32 v10, v50, v51
	v_cvt_pk_bf16_f32 v11, v52, v53
	v_cvt_pk_bf16_f32 v12, v54, v55
	v_cvt_pk_bf16_f32 v13, v56, v57
	global_store_dwordx2 v176, v[10:11], s[10:11]
	global_store_dwordx2 v177, v[12:13], s[10:11]
	s_add_u32 s10, s10, 0x8000
	s_addc_u32 s11, s11, 0
	s_nop 0
	v_mfma_f32_32x32x16_bf16 v[50:65], v[142:145], v[114:117], 0
	v_mfma_f32_32x32x16_bf16 v[2:17], v[142:145], v[110:113], 0
	v_mfma_f32_32x32x16_bf16 v[34:49], v[142:145], v[106:109], 0
	v_mfma_f32_32x32x16_bf16 v[18:33], v[142:145], v[102:105], 0
	global_load_dwordx2 v[160:161], v176, s[6:7]
	global_load_dwordx2 v[162:163], v177, s[6:7]
	s_nop 9
	v_fmac_f32_e32 v51, v78, v50
	v_fmac_f32_e32 v35, v74, v34
	v_fmac_f32_e32 v3, v80, v50
	v_fmac_f32_e32 v19, v76, v34
	v_fma_f32 v51, -v80, v2, v51
	v_fma_f32 v35, -v76, v18, v35
	v_fmac_f32_e32 v3, v78, v2
	v_fmac_f32_e32 v19, v74, v18
	v_fmac_f32_e32 v52, v78, v51
	v_fmac_f32_e32 v36, v74, v35
	v_fmac_f32_e32 v4, v80, v51
	v_fmac_f32_e32 v20, v76, v35
	v_fma_f32 v52, -v80, v3, v52
	v_fma_f32 v36, -v76, v19, v36
	v_fmac_f32_e32 v4, v78, v3
	v_fmac_f32_e32 v20, v74, v19
	v_fmac_f32_e32 v53, v78, v52
	v_fmac_f32_e32 v37, v74, v36
	v_fmac_f32_e32 v5, v80, v52
	v_fmac_f32_e32 v21, v76, v36
	v_fma_f32 v53, -v80, v4, v53
	v_fma_f32 v37, -v76, v20, v37
	v_fmac_f32_e32 v5, v78, v4
	v_fmac_f32_e32 v21, v74, v20
	v_fmac_f32_e32 v54, v78, v53
	v_fmac_f32_e32 v38, v74, v37
	v_fmac_f32_e32 v6, v80, v53
	v_fmac_f32_e32 v22, v76, v37
	v_fma_f32 v54, -v80, v5, v54
	v_fma_f32 v38, -v76, v21, v38
	v_fmac_f32_e32 v6, v78, v5
	v_fmac_f32_e32 v22, v74, v21
	v_fmac_f32_e32 v55, v78, v54
	v_fmac_f32_e32 v39, v74, v38
	v_fmac_f32_e32 v7, v80, v54
	v_fmac_f32_e32 v23, v76, v38
	v_fma_f32 v55, -v80, v6, v55
	v_fma_f32 v39, -v76, v22, v39
	v_fmac_f32_e32 v7, v78, v6
	v_fmac_f32_e32 v23, v74, v22
	v_fmac_f32_e32 v56, v78, v55
	v_fmac_f32_e32 v40, v74, v39
	v_fmac_f32_e32 v8, v80, v55
	v_fmac_f32_e32 v24, v76, v39
	v_fma_f32 v56, -v80, v7, v56
	v_fma_f32 v40, -v76, v23, v40
	v_fmac_f32_e32 v8, v78, v7
	v_fmac_f32_e32 v24, v74, v23
	v_fmac_f32_e32 v57, v78, v56
	v_fmac_f32_e32 v41, v74, v40
	v_fmac_f32_e32 v9, v80, v56
	v_fmac_f32_e32 v25, v76, v40
	v_fma_f32 v57, -v80, v8, v57
	v_fma_f32 v41, -v76, v24, v41
	v_fmac_f32_e32 v9, v78, v8
	v_fmac_f32_e32 v25, v74, v24
	v_fmac_f32_e32 v58, v78, v57
	v_fmac_f32_e32 v42, v74, v41
	v_fmac_f32_e32 v10, v80, v57
	v_fmac_f32_e32 v26, v76, v41
	v_fma_f32 v58, -v80, v9, v58
	v_fma_f32 v42, -v76, v25, v42
	v_fmac_f32_e32 v10, v78, v9
	v_fmac_f32_e32 v26, v74, v25
	v_fmac_f32_e32 v59, v78, v58
	v_fmac_f32_e32 v43, v74, v42
	v_fmac_f32_e32 v11, v80, v58
	v_fmac_f32_e32 v27, v76, v42
	v_fma_f32 v59, -v80, v10, v59
	v_fma_f32 v43, -v76, v26, v43
	v_fmac_f32_e32 v11, v78, v10
	v_fmac_f32_e32 v27, v74, v26
	v_fmac_f32_e32 v60, v78, v59
	v_fmac_f32_e32 v44, v74, v43
	v_fmac_f32_e32 v12, v80, v59
	v_fmac_f32_e32 v28, v76, v43
	v_fma_f32 v60, -v80, v11, v60
	v_fma_f32 v44, -v76, v27, v44
	v_fmac_f32_e32 v12, v78, v11
	v_fmac_f32_e32 v28, v74, v27
	v_fmac_f32_e32 v61, v78, v60
	v_fmac_f32_e32 v45, v74, v44
	v_fmac_f32_e32 v13, v80, v60
	v_fmac_f32_e32 v29, v76, v44
	v_fma_f32 v61, -v80, v12, v61
	v_fma_f32 v45, -v76, v28, v45
	v_fmac_f32_e32 v13, v78, v12
	v_fmac_f32_e32 v29, v74, v28
	v_fmac_f32_e32 v62, v78, v61
	v_fmac_f32_e32 v46, v74, v45
	v_fmac_f32_e32 v14, v80, v61
	v_fmac_f32_e32 v30, v76, v45
	v_fma_f32 v62, -v80, v13, v62
	v_fma_f32 v46, -v76, v29, v46
	v_fmac_f32_e32 v14, v78, v13
	v_fmac_f32_e32 v30, v74, v29
	v_fmac_f32_e32 v63, v78, v62
	v_fmac_f32_e32 v47, v74, v46
	v_fmac_f32_e32 v15, v80, v62
	v_fmac_f32_e32 v31, v76, v46
	v_fma_f32 v63, -v80, v14, v63
	v_fma_f32 v47, -v76, v30, v47
	v_fmac_f32_e32 v15, v78, v14
	v_fmac_f32_e32 v31, v74, v30
	v_fmac_f32_e32 v64, v78, v63
	v_fmac_f32_e32 v48, v74, v47
	v_fmac_f32_e32 v16, v80, v63
	v_fmac_f32_e32 v32, v76, v47
	v_fma_f32 v64, -v80, v15, v64
	v_fma_f32 v48, -v76, v31, v48
	v_fmac_f32_e32 v16, v78, v15
	v_fmac_f32_e32 v32, v74, v31
	v_fmac_f32_e32 v65, v78, v64
	v_fmac_f32_e32 v49, v74, v48
	v_fmac_f32_e32 v17, v80, v64
	v_fmac_f32_e32 v33, v76, v48
	v_fma_f32 v65, -v80, v16, v65
	v_fma_f32 v49, -v76, v32, v49
	v_fmac_f32_e32 v17, v78, v16
	v_fmac_f32_e32 v33, v74, v32
	v_mov_b32_e32 v156, v65
	v_mov_b32_e32 v157, v17
	v_mov_b32_e32 v158, v65
	v_mov_b32_e32 v159, v17
	s_nop 1
	v_permlane32_swap_b32_e32 v156, v158
	v_permlane32_swap_b32_e32 v157, v159
	v_pk_fma_f32 v[164:165], v[166:167], v[152:153], v[156:157] op_sel_hi:[1,0,1]
	v_pk_fma_f32 v[164:165], v[166:167], v[152:153], v[164:165] op_sel:[1,1,0] op_sel_hi:[0,1,1] neg_lo:[0,1,0]
	v_cndmask_b32_e32 v164, v166, v164, vcc
	v_cndmask_b32_e32 v165, v167, v165, vcc
	v_mov_b32_e32 v156, v49
	v_mov_b32_e32 v157, v33
	v_mov_b32_e32 v158, v49
	v_mov_b32_e32 v159, v33
	s_nop 1
	v_permlane32_swap_b32_e32 v156, v158
	v_permlane32_swap_b32_e32 v157, v159
	v_pk_fma_f32 v[170:171], v[150:151], v[154:155], v[156:157] op_sel_hi:[1,0,1]
	v_pk_fma_f32 v[170:171], v[150:151], v[154:155], v[170:171] op_sel:[1,1,0] op_sel_hi:[0,1,1] neg_lo:[0,1,0]
	v_cndmask_b32_e32 v170, v150, v170, vcc
	v_cndmask_b32_e32 v171, v151, v171, vcc
	v_pk_mul_f32 v[168:169], v[164:165], v[70:71] op_sel:[0,1] op_sel_hi:[1,1]
	v_pk_mul_f32 v[172:173], v[170:171], v[66:67] op_sel:[0,1] op_sel_hi:[1,1]
	v_pk_fma_f32 v[168:169], v[164:165], v[72:73], v[168:169] op_sel:[1,1,0] op_sel_hi:[0,1,1] neg_lo:[0,1,0]
	v_pk_fma_f32 v[172:173], v[170:171], v[68:69], v[172:173] op_sel:[1,1,0] op_sel_hi:[0,1,1] neg_lo:[0,1,0]
	v_pk_fma_f32 v[50:51], v[78:79], v[164:165], v[50:51] op_sel_hi:[1,0,1]
	v_pk_fma_f32 v[34:35], v[74:75], v[170:171], v[34:35] op_sel_hi:[1,0,1]
	v_pk_fma_f32 v[52:53], v[70:71], v[164:165], v[52:53] op_sel_hi:[1,0,1]
	v_pk_fma_f32 v[36:37], v[66:67], v[170:171], v[36:37] op_sel_hi:[1,0,1]
	v_pk_fma_f32 v[2:3], v[80:81], v[164:165], v[2:3] op_sel_hi:[1,0,1]
	v_pk_fma_f32 v[18:19], v[76:77], v[170:171], v[18:19] op_sel_hi:[1,0,1]
	v_pk_fma_f32 v[4:5], v[72:73], v[164:165], v[4:5] op_sel_hi:[1,0,1]
	v_pk_fma_f32 v[20:21], v[68:69], v[170:171], v[20:21] op_sel_hi:[1,0,1]
	v_pk_fma_f32 v[50:51], v[80:81], v[164:165], v[50:51] op_sel:[0,1,0] op_sel_hi:[1,1,1] neg_lo:[0,1,0] neg_hi:[0,1,0]
	v_pk_fma_f32 v[34:35], v[76:77], v[170:171], v[34:35] op_sel:[0,1,0] op_sel_hi:[1,1,1] neg_lo:[0,1,0] neg_hi:[0,1,0]
	v_pk_fma_f32 v[52:53], v[72:73], v[164:165], v[52:53] op_sel:[0,1,0] op_sel_hi:[1,1,1] neg_lo:[0,1,0] neg_hi:[0,1,0]
	v_pk_fma_f32 v[36:37], v[68:69], v[170:171], v[36:37] op_sel:[0,1,0] op_sel_hi:[1,1,1] neg_lo:[0,1,0] neg_hi:[0,1,0]
	v_pk_fma_f32 v[2:3], v[78:79], v[164:165], v[2:3] op_sel:[0,1,0] op_sel_hi:[1,1,1]
	v_pk_fma_f32 v[18:19], v[74:75], v[170:171], v[18:19] op_sel:[0,1,0] op_sel_hi:[1,1,1]
	v_pk_fma_f32 v[4:5], v[70:71], v[164:165], v[4:5] op_sel:[0,1,0] op_sel_hi:[1,1,1]
	v_pk_fma_f32 v[20:21], v[66:67], v[170:171], v[20:21] op_sel:[0,1,0] op_sel_hi:[1,1,1]
	v_pk_mul_f32 v[164:165], v[168:169], v[70:71] op_sel:[0,1] op_sel_hi:[1,1]
	v_pk_mul_f32 v[170:171], v[172:173], v[66:67] op_sel:[0,1] op_sel_hi:[1,1]
	v_pk_fma_f32 v[164:165], v[168:169], v[72:73], v[164:165] op_sel:[1,1,0] op_sel_hi:[0,1,1] neg_lo:[0,1,0]
	v_pk_fma_f32 v[170:171], v[172:173], v[68:69], v[170:171] op_sel:[1,1,0] op_sel_hi:[0,1,1] neg_lo:[0,1,0]
	v_pk_fma_f32 v[54:55], v[78:79], v[168:169], v[54:55] op_sel_hi:[1,0,1]
	v_pk_fma_f32 v[38:39], v[74:75], v[172:173], v[38:39] op_sel_hi:[1,0,1]
	v_pk_fma_f32 v[56:57], v[70:71], v[168:169], v[56:57] op_sel_hi:[1,0,1]
	v_pk_fma_f32 v[40:41], v[66:67], v[172:173], v[40:41] op_sel_hi:[1,0,1]
	v_pk_fma_f32 v[6:7], v[80:81], v[168:169], v[6:7] op_sel_hi:[1,0,1]
	v_pk_fma_f32 v[22:23], v[76:77], v[172:173], v[22:23] op_sel_hi:[1,0,1]
	v_pk_fma_f32 v[8:9], v[72:73], v[168:169], v[8:9] op_sel_hi:[1,0,1]
	v_pk_fma_f32 v[24:25], v[68:69], v[172:173], v[24:25] op_sel_hi:[1,0,1]
	v_pk_fma_f32 v[54:55], v[80:81], v[168:169], v[54:55] op_sel:[0,1,0] op_sel_hi:[1,1,1] neg_lo:[0,1,0] neg_hi:[0,1,0]
	v_pk_fma_f32 v[38:39], v[76:77], v[172:173], v[38:39] op_sel:[0,1,0] op_sel_hi:[1,1,1] neg_lo:[0,1,0] neg_hi:[0,1,0]
	v_pk_fma_f32 v[56:57], v[72:73], v[168:169], v[56:57] op_sel:[0,1,0] op_sel_hi:[1,1,1] neg_lo:[0,1,0] neg_hi:[0,1,0]
	v_pk_fma_f32 v[40:41], v[68:69], v[172:173], v[40:41] op_sel:[0,1,0] op_sel_hi:[1,1,1] neg_lo:[0,1,0] neg_hi:[0,1,0]
	v_pk_fma_f32 v[6:7], v[78:79], v[168:169], v[6:7] op_sel:[0,1,0] op_sel_hi:[1,1,1]
	v_pk_fma_f32 v[22:23], v[74:75], v[172:173], v[22:23] op_sel:[0,1,0] op_sel_hi:[1,1,1]
	v_pk_fma_f32 v[8:9], v[70:71], v[168:169], v[8:9] op_sel:[0,1,0] op_sel_hi:[1,1,1]
	v_pk_fma_f32 v[24:25], v[66:67], v[172:173], v[24:25] op_sel:[0,1,0] op_sel_hi:[1,1,1]
	v_pk_mul_f32 v[168:169], v[164:165], v[70:71] op_sel:[0,1] op_sel_hi:[1,1]
	v_pk_mul_f32 v[172:173], v[170:171], v[66:67] op_sel:[0,1] op_sel_hi:[1,1]
	v_pk_fma_f32 v[168:169], v[164:165], v[72:73], v[168:169] op_sel:[1,1,0] op_sel_hi:[0,1,1] neg_lo:[0,1,0]
	v_pk_fma_f32 v[172:173], v[170:171], v[68:69], v[172:173] op_sel:[1,1,0] op_sel_hi:[0,1,1] neg_lo:[0,1,0]
	v_pk_fma_f32 v[58:59], v[78:79], v[164:165], v[58:59] op_sel_hi:[1,0,1]
	v_pk_fma_f32 v[42:43], v[74:75], v[170:171], v[42:43] op_sel_hi:[1,0,1]
	v_pk_fma_f32 v[60:61], v[70:71], v[164:165], v[60:61] op_sel_hi:[1,0,1]
	v_pk_fma_f32 v[44:45], v[66:67], v[170:171], v[44:45] op_sel_hi:[1,0,1]
	v_pk_fma_f32 v[10:11], v[80:81], v[164:165], v[10:11] op_sel_hi:[1,0,1]
	v_pk_fma_f32 v[26:27], v[76:77], v[170:171], v[26:27] op_sel_hi:[1,0,1]
	v_pk_fma_f32 v[12:13], v[72:73], v[164:165], v[12:13] op_sel_hi:[1,0,1]
	v_pk_fma_f32 v[28:29], v[68:69], v[170:171], v[28:29] op_sel_hi:[1,0,1]
	v_pk_fma_f32 v[58:59], v[80:81], v[164:165], v[58:59] op_sel:[0,1,0] op_sel_hi:[1,1,1] neg_lo:[0,1,0] neg_hi:[0,1,0]
	v_pk_fma_f32 v[42:43], v[76:77], v[170:171], v[42:43] op_sel:[0,1,0] op_sel_hi:[1,1,1] neg_lo:[0,1,0] neg_hi:[0,1,0]
	v_pk_fma_f32 v[60:61], v[72:73], v[164:165], v[60:61] op_sel:[0,1,0] op_sel_hi:[1,1,1] neg_lo:[0,1,0] neg_hi:[0,1,0]
	v_pk_fma_f32 v[44:45], v[68:69], v[170:171], v[44:45] op_sel:[0,1,0] op_sel_hi:[1,1,1] neg_lo:[0,1,0] neg_hi:[0,1,0]
	v_pk_fma_f32 v[10:11], v[78:79], v[164:165], v[10:11] op_sel:[0,1,0] op_sel_hi:[1,1,1]
	v_pk_fma_f32 v[26:27], v[74:75], v[170:171], v[26:27] op_sel:[0,1,0] op_sel_hi:[1,1,1]
	v_pk_fma_f32 v[12:13], v[70:71], v[164:165], v[12:13] op_sel:[0,1,0] op_sel_hi:[1,1,1]
	v_pk_fma_f32 v[28:29], v[66:67], v[170:171], v[28:29] op_sel:[0,1,0] op_sel_hi:[1,1,1]
	v_pk_fma_f32 v[62:63], v[78:79], v[168:169], v[62:63] op_sel_hi:[1,0,1]
	v_pk_fma_f32 v[46:47], v[74:75], v[172:173], v[46:47] op_sel_hi:[1,0,1]
	v_pk_fma_f32 v[64:65], v[70:71], v[168:169], v[64:65] op_sel_hi:[1,0,1]
	v_pk_fma_f32 v[48:49], v[66:67], v[172:173], v[48:49] op_sel_hi:[1,0,1]
	v_pk_fma_f32 v[14:15], v[80:81], v[168:169], v[14:15] op_sel_hi:[1,0,1]
	v_pk_fma_f32 v[30:31], v[76:77], v[172:173], v[30:31] op_sel_hi:[1,0,1]
	v_pk_fma_f32 v[16:17], v[72:73], v[168:169], v[16:17] op_sel_hi:[1,0,1]
	v_pk_fma_f32 v[32:33], v[68:69], v[172:173], v[32:33] op_sel_hi:[1,0,1]
	v_pk_fma_f32 v[62:63], v[80:81], v[168:169], v[62:63] op_sel:[0,1,0] op_sel_hi:[1,1,1] neg_lo:[0,1,0] neg_hi:[0,1,0]
	v_pk_fma_f32 v[46:47], v[76:77], v[172:173], v[46:47] op_sel:[0,1,0] op_sel_hi:[1,1,1] neg_lo:[0,1,0] neg_hi:[0,1,0]
	v_pk_fma_f32 v[64:65], v[72:73], v[168:169], v[64:65] op_sel:[0,1,0] op_sel_hi:[1,1,1] neg_lo:[0,1,0] neg_hi:[0,1,0]
	v_pk_fma_f32 v[48:49], v[68:69], v[172:173], v[48:49] op_sel:[0,1,0] op_sel_hi:[1,1,1] neg_lo:[0,1,0] neg_hi:[0,1,0]
	v_pk_fma_f32 v[14:15], v[78:79], v[168:169], v[14:15] op_sel:[0,1,0] op_sel_hi:[1,1,1]
	v_pk_fma_f32 v[30:31], v[74:75], v[172:173], v[30:31] op_sel:[0,1,0] op_sel_hi:[1,1,1]
	v_pk_fma_f32 v[16:17], v[70:71], v[168:169], v[16:17] op_sel:[0,1,0] op_sel_hi:[1,1,1]
	v_pk_fma_f32 v[32:33], v[66:67], v[172:173], v[32:33] op_sel:[0,1,0] op_sel_hi:[1,1,1]
	v_mov_b32_e32 v156, v65
	v_mov_b32_e32 v157, v17
	v_mov_b32_e32 v166, v65
	v_mov_b32_e32 v167, v17
	s_nop 1
	v_permlane32_swap_b32_e32 v156, v166
	v_permlane32_swap_b32_e32 v157, v167
	v_mov_b32_e32 v156, v49
	v_mov_b32_e32 v157, v33
	v_mov_b32_e32 v150, v49
	v_mov_b32_e32 v151, v33
	s_nop 1
	v_permlane32_swap_b32_e32 v156, v150
	v_permlane32_swap_b32_e32 v157, v151
	v_cvt_pk_bf16_f32 v1, v50, v2
	ds_write_b32 v174, v1
	v_cvt_pk_bf16_f32 v146, v34, v18
	ds_write_b32 v174, v146 offset:128
	v_cvt_pk_bf16_f32 v178, v51, v3
	ds_write_b32 v174, v178 offset:272
	v_cvt_pk_bf16_f32 v1, v35, v19
	ds_write_b32 v174, v1 offset:400
	v_cvt_pk_bf16_f32 v146, v52, v4
	ds_write_b32 v174, v146 offset:544
	v_cvt_pk_bf16_f32 v178, v36, v20
	ds_write_b32 v174, v178 offset:672
	v_cvt_pk_bf16_f32 v1, v53, v5
	ds_write_b32 v174, v1 offset:816
	v_cvt_pk_bf16_f32 v146, v37, v21
	ds_write_b32 v174, v146 offset:944
	v_cvt_pk_bf16_f32 v178, v54, v6
	ds_write_b32 v174, v178 offset:1088
	v_cvt_pk_bf16_f32 v1, v38, v22
	ds_write_b32 v174, v1 offset:1216
	v_cvt_pk_bf16_f32 v146, v55, v7
	ds_write_b32 v174, v146 offset:1360
	v_cvt_pk_bf16_f32 v178, v39, v23
	ds_write_b32 v174, v178 offset:1488
	v_cvt_pk_bf16_f32 v1, v56, v8
	ds_write_b32 v174, v1 offset:1632
	v_cvt_pk_bf16_f32 v146, v40, v24
	ds_write_b32 v174, v146 offset:1760
	v_cvt_pk_bf16_f32 v178, v57, v9
	ds_write_b32 v174, v178 offset:1904
	v_cvt_pk_bf16_f32 v1, v41, v25
	ds_write_b32 v174, v1 offset:2032
	v_cvt_pk_bf16_f32 v146, v58, v10
	ds_write_b32 v174, v146 offset:2176
	v_cvt_pk_bf16_f32 v178, v42, v26
	ds_write_b32 v174, v178 offset:2304
	v_cvt_pk_bf16_f32 v1, v59, v11
	ds_write_b32 v174, v1 offset:2448
	v_cvt_pk_bf16_f32 v146, v43, v27
	ds_write_b32 v174, v146 offset:2576
	v_cvt_pk_bf16_f32 v178, v60, v12
	ds_write_b32 v174, v178 offset:2720
	v_cvt_pk_bf16_f32 v1, v44, v28
	ds_write_b32 v174, v1 offset:2848
	v_cvt_pk_bf16_f32 v146, v61, v13
	ds_write_b32 v174, v146 offset:2992
	v_cvt_pk_bf16_f32 v178, v45, v29
	ds_write_b32 v174, v178 offset:3120
	v_cvt_pk_bf16_f32 v1, v62, v14
	ds_write_b32 v174, v1 offset:3264
	v_cvt_pk_bf16_f32 v146, v46, v30
	ds_write_b32 v174, v146 offset:3392
	v_cvt_pk_bf16_f32 v178, v63, v15
	ds_write_b32 v174, v178 offset:3536
	v_cvt_pk_bf16_f32 v1, v47, v31
	ds_write_b32 v174, v1 offset:3664
	v_cvt_pk_bf16_f32 v146, v64, v16
	ds_write_b32 v174, v146 offset:3808
	v_cvt_pk_bf16_f32 v178, v48, v32
	ds_write_b32 v174, v178 offset:3936
	v_cvt_pk_bf16_f32 v1, v65, v17
	ds_write_b32 v174, v1 offset:4080
	v_cvt_pk_bf16_f32 v146, v49, v33
	ds_write_b32 v174, v146 offset:4208
	s_waitcnt lgkmcnt(0)
	ds_read_b128 v[2:5], v175
	ds_read_b128 v[6:9], v175 offset:64
	ds_read_b128 v[10:13], v175 offset:128
	ds_read_b128 v[14:17], v175 offset:192
	ds_read_b128 v[18:21], v175 offset:4352
	ds_read_b128 v[22:25], v175 offset:4416
	ds_read_b128 v[26:29], v175 offset:4480
	ds_read_b128 v[30:33], v175 offset:4544
	s_waitcnt vmcnt(0)
	s_waitcnt lgkmcnt(7)
	v_mfma_f32_16x16x32_bf16 v[34:37], v[94:97], v[2:5], 0
	s_waitcnt lgkmcnt(6)
	v_mfma_f32_16x16x32_bf16 v[34:37], v[90:93], v[6:9], v[34:37]
	s_waitcnt lgkmcnt(5)
	v_mfma_f32_16x16x32_bf16 v[34:37], v[86:89], v[10:13], v[34:37]
	s_waitcnt lgkmcnt(4)
	v_mfma_f32_16x16x32_bf16 v[34:37], v[82:85], v[14:17], v[34:37]
	s_waitcnt lgkmcnt(3)
	v_mfma_f32_16x16x32_bf16 v[38:41], v[94:97], v[18:21], 0
	s_waitcnt lgkmcnt(2)
	v_mfma_f32_16x16x32_bf16 v[38:41], v[90:93], v[22:25], v[38:41]
	s_waitcnt lgkmcnt(1)
	v_mfma_f32_16x16x32_bf16 v[38:41], v[86:89], v[26:29], v[38:41]
	s_waitcnt lgkmcnt(0)
	v_mfma_f32_16x16x32_bf16 v[38:41], v[82:85], v[30:33], v[38:41]
	s_add_u32 s6, s6, 0x8000
	s_addc_u32 s7, s7, 0
	v_lshlrev_b32_e32 v42, 16, v160
	v_and_b32_e32 v43, 0xffff0000, v160
	v_lshlrev_b32_e32 v44, 16, v161
	v_and_b32_e32 v45, 0xffff0000, v161
	v_lshlrev_b32_e32 v46, 16, v162
	v_and_b32_e32 v47, 0xffff0000, v162
	v_lshlrev_b32_e32 v48, 16, v163
	v_and_b32_e32 v49, 0xffff0000, v163
	s_nop 1
	v_mov_b32_e32 v156, 0x3d372713
	v_mov_b32_e32 v158, 0xbfcc422a
	v_mov_b32_e32 v164, 0x3fb8aa3b
	v_mov_b32_e32 v168, 1.0
	v_pk_fma_f32 v[50:51], v[98:99], v[42:43], v[34:35]
	v_pk_fma_f32 v[52:53], v[100:101], v[44:45], v[36:37]
	v_pk_fma_f32 v[54:55], v[98:99], v[46:47], v[38:39]
	v_pk_fma_f32 v[56:57], v[100:101], v[48:49], v[40:41]
	v_pk_mul_f32 v[2:3], v[50:51], v[156:157] op_sel_hi:[1,0]
	v_pk_mul_f32 v[4:5], v[52:53], v[156:157] op_sel_hi:[1,0]
	v_pk_mul_f32 v[6:7], v[54:55], v[156:157] op_sel_hi:[1,0]
	v_pk_mul_f32 v[8:9], v[56:57], v[156:157] op_sel_hi:[1,0]
	v_pk_mul_f32 v[2:3], v[50:51], v[2:3]
	v_pk_mul_f32 v[4:5], v[52:53], v[4:5]
	v_pk_mul_f32 v[6:7], v[54:55], v[6:7]
	v_pk_mul_f32 v[8:9], v[56:57], v[8:9]
	v_pk_fma_f32 v[2:3], v[50:51], v[2:3], v[50:51]
	v_pk_fma_f32 v[4:5], v[52:53], v[4:5], v[52:53]
	v_pk_fma_f32 v[6:7], v[54:55], v[6:7], v[54:55]
	v_pk_fma_f32 v[8:9], v[56:57], v[8:9], v[56:57]
	v_pk_mul_f32 v[2:3], v[2:3], v[158:159] op_sel_hi:[1,0]
	v_pk_mul_f32 v[4:5], v[4:5], v[158:159] op_sel_hi:[1,0]
	v_pk_mul_f32 v[6:7], v[6:7], v[158:159] op_sel_hi:[1,0]
	v_pk_mul_f32 v[8:9], v[8:9], v[158:159] op_sel_hi:[1,0]
	v_pk_mul_f32 v[2:3], v[2:3], v[164:165] op_sel_hi:[1,0]
	v_pk_mul_f32 v[4:5], v[4:5], v[164:165] op_sel_hi:[1,0]
	v_pk_mul_f32 v[6:7], v[6:7], v[164:165] op_sel_hi:[1,0]
	v_pk_mul_f32 v[8:9], v[8:9], v[164:165] op_sel_hi:[1,0]
	v_exp_f32_e32 v2, v2
	v_exp_f32_e32 v3, v3
	v_exp_f32_e32 v4, v4
	v_exp_f32_e32 v5, v5
	v_exp_f32_e32 v6, v6
	v_exp_f32_e32 v7, v7
	v_exp_f32_e32 v8, v8
	v_exp_f32_e32 v9, v9
	v_pk_add_f32 v[2:3], v[2:3], v[168:169] op_sel_hi:[1,0]
	v_pk_add_f32 v[4:5], v[4:5], v[168:169] op_sel_hi:[1,0]
	v_pk_add_f32 v[6:7], v[6:7], v[168:169] op_sel_hi:[1,0]
	v_pk_add_f32 v[8:9], v[8:9], v[168:169] op_sel_hi:[1,0]
	v_rcp_f32_e32 v2, v2
	v_rcp_f32_e32 v3, v3
	v_rcp_f32_e32 v4, v4
	v_rcp_f32_e32 v5, v5
	v_rcp_f32_e32 v6, v6
	v_rcp_f32_e32 v7, v7
	v_rcp_f32_e32 v8, v8
	v_rcp_f32_e32 v9, v9
	v_pk_mul_f32 v[50:51], v[50:51], v[2:3]
	v_pk_mul_f32 v[52:53], v[52:53], v[4:5]
	v_pk_mul_f32 v[54:55], v[54:55], v[6:7]
	v_pk_mul_f32 v[56:57], v[56:57], v[8:9]
	v_cvt_pk_bf16_f32 v10, v50, v51
	v_cvt_pk_bf16_f32 v11, v52, v53
	v_cvt_pk_bf16_f32 v12, v54, v55
	v_cvt_pk_bf16_f32 v13, v56, v57
	global_store_dwordx2 v176, v[10:11], s[10:11]
	global_store_dwordx2 v177, v[12:13], s[10:11]
	s_add_u32 s10, s10, 0x8000
	s_addc_u32 s11, s11, 0
	s_nop 0
	v_mfma_f32_32x32x16_bf16 v[50:65], v[138:141], v[114:117], 0
	v_mfma_f32_32x32x16_bf16 v[2:17], v[138:141], v[110:113], 0
	v_mfma_f32_32x32x16_bf16 v[34:49], v[138:141], v[106:109], 0
	v_mfma_f32_32x32x16_bf16 v[18:33], v[138:141], v[102:105], 0
	global_load_dwordx2 v[160:161], v176, s[6:7]
	global_load_dwordx2 v[162:163], v177, s[6:7]
	s_nop 9
	v_fmac_f32_e32 v51, v78, v50
	v_fmac_f32_e32 v35, v74, v34
	v_fmac_f32_e32 v3, v80, v50
	v_fmac_f32_e32 v19, v76, v34
	v_fma_f32 v51, -v80, v2, v51
	v_fma_f32 v35, -v76, v18, v35
	v_fmac_f32_e32 v3, v78, v2
	v_fmac_f32_e32 v19, v74, v18
	v_fmac_f32_e32 v52, v78, v51
	v_fmac_f32_e32 v36, v74, v35
	v_fmac_f32_e32 v4, v80, v51
	v_fmac_f32_e32 v20, v76, v35
	v_fma_f32 v52, -v80, v3, v52
	v_fma_f32 v36, -v76, v19, v36
	v_fmac_f32_e32 v4, v78, v3
	v_fmac_f32_e32 v20, v74, v19
	v_fmac_f32_e32 v53, v78, v52
	v_fmac_f32_e32 v37, v74, v36
	v_fmac_f32_e32 v5, v80, v52
	v_fmac_f32_e32 v21, v76, v36
	v_fma_f32 v53, -v80, v4, v53
	v_fma_f32 v37, -v76, v20, v37
	v_fmac_f32_e32 v5, v78, v4
	v_fmac_f32_e32 v21, v74, v20
	v_fmac_f32_e32 v54, v78, v53
	v_fmac_f32_e32 v38, v74, v37
	v_fmac_f32_e32 v6, v80, v53
	v_fmac_f32_e32 v22, v76, v37
	v_fma_f32 v54, -v80, v5, v54
	v_fma_f32 v38, -v76, v21, v38
	v_fmac_f32_e32 v6, v78, v5
	v_fmac_f32_e32 v22, v74, v21
	v_fmac_f32_e32 v55, v78, v54
	v_fmac_f32_e32 v39, v74, v38
	v_fmac_f32_e32 v7, v80, v54
	v_fmac_f32_e32 v23, v76, v38
	v_fma_f32 v55, -v80, v6, v55
	v_fma_f32 v39, -v76, v22, v39
	v_fmac_f32_e32 v7, v78, v6
	v_fmac_f32_e32 v23, v74, v22
	v_fmac_f32_e32 v56, v78, v55
	v_fmac_f32_e32 v40, v74, v39
	v_fmac_f32_e32 v8, v80, v55
	v_fmac_f32_e32 v24, v76, v39
	v_fma_f32 v56, -v80, v7, v56
	v_fma_f32 v40, -v76, v23, v40
	v_fmac_f32_e32 v8, v78, v7
	v_fmac_f32_e32 v24, v74, v23
	v_fmac_f32_e32 v57, v78, v56
	v_fmac_f32_e32 v41, v74, v40
	v_fmac_f32_e32 v9, v80, v56
	v_fmac_f32_e32 v25, v76, v40
	v_fma_f32 v57, -v80, v8, v57
	v_fma_f32 v41, -v76, v24, v41
	v_fmac_f32_e32 v9, v78, v8
	v_fmac_f32_e32 v25, v74, v24
	v_fmac_f32_e32 v58, v78, v57
	v_fmac_f32_e32 v42, v74, v41
	v_fmac_f32_e32 v10, v80, v57
	v_fmac_f32_e32 v26, v76, v41
	v_fma_f32 v58, -v80, v9, v58
	v_fma_f32 v42, -v76, v25, v42
	v_fmac_f32_e32 v10, v78, v9
	v_fmac_f32_e32 v26, v74, v25
	v_fmac_f32_e32 v59, v78, v58
	v_fmac_f32_e32 v43, v74, v42
	v_fmac_f32_e32 v11, v80, v58
	v_fmac_f32_e32 v27, v76, v42
	v_fma_f32 v59, -v80, v10, v59
	v_fma_f32 v43, -v76, v26, v43
	v_fmac_f32_e32 v11, v78, v10
	v_fmac_f32_e32 v27, v74, v26
	v_fmac_f32_e32 v60, v78, v59
	v_fmac_f32_e32 v44, v74, v43
	v_fmac_f32_e32 v12, v80, v59
	v_fmac_f32_e32 v28, v76, v43
	v_fma_f32 v60, -v80, v11, v60
	v_fma_f32 v44, -v76, v27, v44
	v_fmac_f32_e32 v12, v78, v11
	v_fmac_f32_e32 v28, v74, v27
	v_fmac_f32_e32 v61, v78, v60
	v_fmac_f32_e32 v45, v74, v44
	v_fmac_f32_e32 v13, v80, v60
	v_fmac_f32_e32 v29, v76, v44
	v_fma_f32 v61, -v80, v12, v61
	v_fma_f32 v45, -v76, v28, v45
	v_fmac_f32_e32 v13, v78, v12
	v_fmac_f32_e32 v29, v74, v28
	v_fmac_f32_e32 v62, v78, v61
	v_fmac_f32_e32 v46, v74, v45
	v_fmac_f32_e32 v14, v80, v61
	v_fmac_f32_e32 v30, v76, v45
	v_fma_f32 v62, -v80, v13, v62
	v_fma_f32 v46, -v76, v29, v46
	v_fmac_f32_e32 v14, v78, v13
	v_fmac_f32_e32 v30, v74, v29
	v_fmac_f32_e32 v63, v78, v62
	v_fmac_f32_e32 v47, v74, v46
	v_fmac_f32_e32 v15, v80, v62
	v_fmac_f32_e32 v31, v76, v46
	v_fma_f32 v63, -v80, v14, v63
	v_fma_f32 v47, -v76, v30, v47
	v_fmac_f32_e32 v15, v78, v14
	v_fmac_f32_e32 v31, v74, v30
	v_fmac_f32_e32 v64, v78, v63
	v_fmac_f32_e32 v48, v74, v47
	v_fmac_f32_e32 v16, v80, v63
	v_fmac_f32_e32 v32, v76, v47
	v_fma_f32 v64, -v80, v15, v64
	v_fma_f32 v48, -v76, v31, v48
	v_fmac_f32_e32 v16, v78, v15
	v_fmac_f32_e32 v32, v74, v31
	v_fmac_f32_e32 v65, v78, v64
	v_fmac_f32_e32 v49, v74, v48
	v_fmac_f32_e32 v17, v80, v64
	v_fmac_f32_e32 v33, v76, v48
	v_fma_f32 v65, -v80, v16, v65
	v_fma_f32 v49, -v76, v32, v49
	v_fmac_f32_e32 v17, v78, v16
	v_fmac_f32_e32 v33, v74, v32
	v_mov_b32_e32 v156, v65
	v_mov_b32_e32 v157, v17
	v_mov_b32_e32 v158, v65
	v_mov_b32_e32 v159, v17
	s_nop 1
	v_permlane32_swap_b32_e32 v156, v158
	v_permlane32_swap_b32_e32 v157, v159
	v_pk_fma_f32 v[164:165], v[166:167], v[152:153], v[156:157] op_sel_hi:[1,0,1]
	v_pk_fma_f32 v[164:165], v[166:167], v[152:153], v[164:165] op_sel:[1,1,0] op_sel_hi:[0,1,1] neg_lo:[0,1,0]
	v_cndmask_b32_e32 v164, v166, v164, vcc
	v_cndmask_b32_e32 v165, v167, v165, vcc
	v_mov_b32_e32 v156, v49
	v_mov_b32_e32 v157, v33
	v_mov_b32_e32 v158, v49
	v_mov_b32_e32 v159, v33
	s_nop 1
	v_permlane32_swap_b32_e32 v156, v158
	v_permlane32_swap_b32_e32 v157, v159
	v_pk_fma_f32 v[170:171], v[150:151], v[154:155], v[156:157] op_sel_hi:[1,0,1]
	v_pk_fma_f32 v[170:171], v[150:151], v[154:155], v[170:171] op_sel:[1,1,0] op_sel_hi:[0,1,1] neg_lo:[0,1,0]
	v_cndmask_b32_e32 v170, v150, v170, vcc
	v_cndmask_b32_e32 v171, v151, v171, vcc
	v_pk_mul_f32 v[168:169], v[164:165], v[70:71] op_sel:[0,1] op_sel_hi:[1,1]
	v_pk_mul_f32 v[172:173], v[170:171], v[66:67] op_sel:[0,1] op_sel_hi:[1,1]
	v_pk_fma_f32 v[168:169], v[164:165], v[72:73], v[168:169] op_sel:[1,1,0] op_sel_hi:[0,1,1] neg_lo:[0,1,0]
	v_pk_fma_f32 v[172:173], v[170:171], v[68:69], v[172:173] op_sel:[1,1,0] op_sel_hi:[0,1,1] neg_lo:[0,1,0]
	v_pk_fma_f32 v[50:51], v[78:79], v[164:165], v[50:51] op_sel_hi:[1,0,1]
	v_pk_fma_f32 v[34:35], v[74:75], v[170:171], v[34:35] op_sel_hi:[1,0,1]
	v_pk_fma_f32 v[52:53], v[70:71], v[164:165], v[52:53] op_sel_hi:[1,0,1]
	v_pk_fma_f32 v[36:37], v[66:67], v[170:171], v[36:37] op_sel_hi:[1,0,1]
	v_pk_fma_f32 v[2:3], v[80:81], v[164:165], v[2:3] op_sel_hi:[1,0,1]
	v_pk_fma_f32 v[18:19], v[76:77], v[170:171], v[18:19] op_sel_hi:[1,0,1]
	v_pk_fma_f32 v[4:5], v[72:73], v[164:165], v[4:5] op_sel_hi:[1,0,1]
	v_pk_fma_f32 v[20:21], v[68:69], v[170:171], v[20:21] op_sel_hi:[1,0,1]
	v_pk_fma_f32 v[50:51], v[80:81], v[164:165], v[50:51] op_sel:[0,1,0] op_sel_hi:[1,1,1] neg_lo:[0,1,0] neg_hi:[0,1,0]
	v_pk_fma_f32 v[34:35], v[76:77], v[170:171], v[34:35] op_sel:[0,1,0] op_sel_hi:[1,1,1] neg_lo:[0,1,0] neg_hi:[0,1,0]
	v_pk_fma_f32 v[52:53], v[72:73], v[164:165], v[52:53] op_sel:[0,1,0] op_sel_hi:[1,1,1] neg_lo:[0,1,0] neg_hi:[0,1,0]
	v_pk_fma_f32 v[36:37], v[68:69], v[170:171], v[36:37] op_sel:[0,1,0] op_sel_hi:[1,1,1] neg_lo:[0,1,0] neg_hi:[0,1,0]
	v_pk_fma_f32 v[2:3], v[78:79], v[164:165], v[2:3] op_sel:[0,1,0] op_sel_hi:[1,1,1]
	v_pk_fma_f32 v[18:19], v[74:75], v[170:171], v[18:19] op_sel:[0,1,0] op_sel_hi:[1,1,1]
	v_pk_fma_f32 v[4:5], v[70:71], v[164:165], v[4:5] op_sel:[0,1,0] op_sel_hi:[1,1,1]
	v_pk_fma_f32 v[20:21], v[66:67], v[170:171], v[20:21] op_sel:[0,1,0] op_sel_hi:[1,1,1]
	v_pk_mul_f32 v[164:165], v[168:169], v[70:71] op_sel:[0,1] op_sel_hi:[1,1]
	v_pk_mul_f32 v[170:171], v[172:173], v[66:67] op_sel:[0,1] op_sel_hi:[1,1]
	v_pk_fma_f32 v[164:165], v[168:169], v[72:73], v[164:165] op_sel:[1,1,0] op_sel_hi:[0,1,1] neg_lo:[0,1,0]
	v_pk_fma_f32 v[170:171], v[172:173], v[68:69], v[170:171] op_sel:[1,1,0] op_sel_hi:[0,1,1] neg_lo:[0,1,0]
	v_pk_fma_f32 v[54:55], v[78:79], v[168:169], v[54:55] op_sel_hi:[1,0,1]
	v_pk_fma_f32 v[38:39], v[74:75], v[172:173], v[38:39] op_sel_hi:[1,0,1]
	v_pk_fma_f32 v[56:57], v[70:71], v[168:169], v[56:57] op_sel_hi:[1,0,1]
	v_pk_fma_f32 v[40:41], v[66:67], v[172:173], v[40:41] op_sel_hi:[1,0,1]
	v_pk_fma_f32 v[6:7], v[80:81], v[168:169], v[6:7] op_sel_hi:[1,0,1]
	v_pk_fma_f32 v[22:23], v[76:77], v[172:173], v[22:23] op_sel_hi:[1,0,1]
	v_pk_fma_f32 v[8:9], v[72:73], v[168:169], v[8:9] op_sel_hi:[1,0,1]
	v_pk_fma_f32 v[24:25], v[68:69], v[172:173], v[24:25] op_sel_hi:[1,0,1]
	v_pk_fma_f32 v[54:55], v[80:81], v[168:169], v[54:55] op_sel:[0,1,0] op_sel_hi:[1,1,1] neg_lo:[0,1,0] neg_hi:[0,1,0]
	v_pk_fma_f32 v[38:39], v[76:77], v[172:173], v[38:39] op_sel:[0,1,0] op_sel_hi:[1,1,1] neg_lo:[0,1,0] neg_hi:[0,1,0]
	v_pk_fma_f32 v[56:57], v[72:73], v[168:169], v[56:57] op_sel:[0,1,0] op_sel_hi:[1,1,1] neg_lo:[0,1,0] neg_hi:[0,1,0]
	v_pk_fma_f32 v[40:41], v[68:69], v[172:173], v[40:41] op_sel:[0,1,0] op_sel_hi:[1,1,1] neg_lo:[0,1,0] neg_hi:[0,1,0]
	v_pk_fma_f32 v[6:7], v[78:79], v[168:169], v[6:7] op_sel:[0,1,0] op_sel_hi:[1,1,1]
	v_pk_fma_f32 v[22:23], v[74:75], v[172:173], v[22:23] op_sel:[0,1,0] op_sel_hi:[1,1,1]
	v_pk_fma_f32 v[8:9], v[70:71], v[168:169], v[8:9] op_sel:[0,1,0] op_sel_hi:[1,1,1]
	v_pk_fma_f32 v[24:25], v[66:67], v[172:173], v[24:25] op_sel:[0,1,0] op_sel_hi:[1,1,1]
	v_pk_mul_f32 v[168:169], v[164:165], v[70:71] op_sel:[0,1] op_sel_hi:[1,1]
	v_pk_mul_f32 v[172:173], v[170:171], v[66:67] op_sel:[0,1] op_sel_hi:[1,1]
	v_pk_fma_f32 v[168:169], v[164:165], v[72:73], v[168:169] op_sel:[1,1,0] op_sel_hi:[0,1,1] neg_lo:[0,1,0]
	v_pk_fma_f32 v[172:173], v[170:171], v[68:69], v[172:173] op_sel:[1,1,0] op_sel_hi:[0,1,1] neg_lo:[0,1,0]
	v_pk_fma_f32 v[58:59], v[78:79], v[164:165], v[58:59] op_sel_hi:[1,0,1]
	v_pk_fma_f32 v[42:43], v[74:75], v[170:171], v[42:43] op_sel_hi:[1,0,1]
	v_pk_fma_f32 v[60:61], v[70:71], v[164:165], v[60:61] op_sel_hi:[1,0,1]
	v_pk_fma_f32 v[44:45], v[66:67], v[170:171], v[44:45] op_sel_hi:[1,0,1]
	v_pk_fma_f32 v[10:11], v[80:81], v[164:165], v[10:11] op_sel_hi:[1,0,1]
	v_pk_fma_f32 v[26:27], v[76:77], v[170:171], v[26:27] op_sel_hi:[1,0,1]
	v_pk_fma_f32 v[12:13], v[72:73], v[164:165], v[12:13] op_sel_hi:[1,0,1]
	v_pk_fma_f32 v[28:29], v[68:69], v[170:171], v[28:29] op_sel_hi:[1,0,1]
	v_pk_fma_f32 v[58:59], v[80:81], v[164:165], v[58:59] op_sel:[0,1,0] op_sel_hi:[1,1,1] neg_lo:[0,1,0] neg_hi:[0,1,0]
	v_pk_fma_f32 v[42:43], v[76:77], v[170:171], v[42:43] op_sel:[0,1,0] op_sel_hi:[1,1,1] neg_lo:[0,1,0] neg_hi:[0,1,0]
	v_pk_fma_f32 v[60:61], v[72:73], v[164:165], v[60:61] op_sel:[0,1,0] op_sel_hi:[1,1,1] neg_lo:[0,1,0] neg_hi:[0,1,0]
	v_pk_fma_f32 v[44:45], v[68:69], v[170:171], v[44:45] op_sel:[0,1,0] op_sel_hi:[1,1,1] neg_lo:[0,1,0] neg_hi:[0,1,0]
	v_pk_fma_f32 v[10:11], v[78:79], v[164:165], v[10:11] op_sel:[0,1,0] op_sel_hi:[1,1,1]
	v_pk_fma_f32 v[26:27], v[74:75], v[170:171], v[26:27] op_sel:[0,1,0] op_sel_hi:[1,1,1]
	v_pk_fma_f32 v[12:13], v[70:71], v[164:165], v[12:13] op_sel:[0,1,0] op_sel_hi:[1,1,1]
	v_pk_fma_f32 v[28:29], v[66:67], v[170:171], v[28:29] op_sel:[0,1,0] op_sel_hi:[1,1,1]
	v_pk_fma_f32 v[62:63], v[78:79], v[168:169], v[62:63] op_sel_hi:[1,0,1]
	v_pk_fma_f32 v[46:47], v[74:75], v[172:173], v[46:47] op_sel_hi:[1,0,1]
	v_pk_fma_f32 v[64:65], v[70:71], v[168:169], v[64:65] op_sel_hi:[1,0,1]
	v_pk_fma_f32 v[48:49], v[66:67], v[172:173], v[48:49] op_sel_hi:[1,0,1]
	v_pk_fma_f32 v[14:15], v[80:81], v[168:169], v[14:15] op_sel_hi:[1,0,1]
	v_pk_fma_f32 v[30:31], v[76:77], v[172:173], v[30:31] op_sel_hi:[1,0,1]
	v_pk_fma_f32 v[16:17], v[72:73], v[168:169], v[16:17] op_sel_hi:[1,0,1]
	v_pk_fma_f32 v[32:33], v[68:69], v[172:173], v[32:33] op_sel_hi:[1,0,1]
	v_pk_fma_f32 v[62:63], v[80:81], v[168:169], v[62:63] op_sel:[0,1,0] op_sel_hi:[1,1,1] neg_lo:[0,1,0] neg_hi:[0,1,0]
	v_pk_fma_f32 v[46:47], v[76:77], v[172:173], v[46:47] op_sel:[0,1,0] op_sel_hi:[1,1,1] neg_lo:[0,1,0] neg_hi:[0,1,0]
	v_pk_fma_f32 v[64:65], v[72:73], v[168:169], v[64:65] op_sel:[0,1,0] op_sel_hi:[1,1,1] neg_lo:[0,1,0] neg_hi:[0,1,0]
	v_pk_fma_f32 v[48:49], v[68:69], v[172:173], v[48:49] op_sel:[0,1,0] op_sel_hi:[1,1,1] neg_lo:[0,1,0] neg_hi:[0,1,0]
	v_pk_fma_f32 v[14:15], v[78:79], v[168:169], v[14:15] op_sel:[0,1,0] op_sel_hi:[1,1,1]
	v_pk_fma_f32 v[30:31], v[74:75], v[172:173], v[30:31] op_sel:[0,1,0] op_sel_hi:[1,1,1]
	v_pk_fma_f32 v[16:17], v[70:71], v[168:169], v[16:17] op_sel:[0,1,0] op_sel_hi:[1,1,1]
	v_pk_fma_f32 v[32:33], v[66:67], v[172:173], v[32:33] op_sel:[0,1,0] op_sel_hi:[1,1,1]
	v_mov_b32_e32 v156, v65
	v_mov_b32_e32 v157, v17
	v_mov_b32_e32 v166, v65
	v_mov_b32_e32 v167, v17
	s_nop 1
	v_permlane32_swap_b32_e32 v156, v166
	v_permlane32_swap_b32_e32 v157, v167
	v_mov_b32_e32 v156, v49
	v_mov_b32_e32 v157, v33
	v_mov_b32_e32 v150, v49
	v_mov_b32_e32 v151, v33
	s_nop 1
	v_permlane32_swap_b32_e32 v156, v150
	v_permlane32_swap_b32_e32 v157, v151
	v_cvt_pk_bf16_f32 v1, v50, v2
	ds_write_b32 v174, v1
	v_cvt_pk_bf16_f32 v146, v34, v18
	ds_write_b32 v174, v146 offset:128
	v_cvt_pk_bf16_f32 v178, v51, v3
	ds_write_b32 v174, v178 offset:272
	v_cvt_pk_bf16_f32 v1, v35, v19
	ds_write_b32 v174, v1 offset:400
	v_cvt_pk_bf16_f32 v146, v52, v4
	ds_write_b32 v174, v146 offset:544
	v_cvt_pk_bf16_f32 v178, v36, v20
	ds_write_b32 v174, v178 offset:672
	v_cvt_pk_bf16_f32 v1, v53, v5
	ds_write_b32 v174, v1 offset:816
	v_cvt_pk_bf16_f32 v146, v37, v21
	ds_write_b32 v174, v146 offset:944
	v_cvt_pk_bf16_f32 v178, v54, v6
	ds_write_b32 v174, v178 offset:1088
	v_cvt_pk_bf16_f32 v1, v38, v22
	ds_write_b32 v174, v1 offset:1216
	v_cvt_pk_bf16_f32 v146, v55, v7
	ds_write_b32 v174, v146 offset:1360
	v_cvt_pk_bf16_f32 v178, v39, v23
	ds_write_b32 v174, v178 offset:1488
	v_cvt_pk_bf16_f32 v1, v56, v8
	ds_write_b32 v174, v1 offset:1632
	v_cvt_pk_bf16_f32 v146, v40, v24
	ds_write_b32 v174, v146 offset:1760
	v_cvt_pk_bf16_f32 v178, v57, v9
	ds_write_b32 v174, v178 offset:1904
	v_cvt_pk_bf16_f32 v1, v41, v25
	ds_write_b32 v174, v1 offset:2032
	v_cvt_pk_bf16_f32 v146, v58, v10
	ds_write_b32 v174, v146 offset:2176
	v_cvt_pk_bf16_f32 v178, v42, v26
	ds_write_b32 v174, v178 offset:2304
	v_cvt_pk_bf16_f32 v1, v59, v11
	ds_write_b32 v174, v1 offset:2448
	v_cvt_pk_bf16_f32 v146, v43, v27
	ds_write_b32 v174, v146 offset:2576
	v_cvt_pk_bf16_f32 v178, v60, v12
	ds_write_b32 v174, v178 offset:2720
	v_cvt_pk_bf16_f32 v1, v44, v28
	ds_write_b32 v174, v1 offset:2848
	v_cvt_pk_bf16_f32 v146, v61, v13
	ds_write_b32 v174, v146 offset:2992
	v_cvt_pk_bf16_f32 v178, v45, v29
	ds_write_b32 v174, v178 offset:3120
	v_cvt_pk_bf16_f32 v1, v62, v14
	ds_write_b32 v174, v1 offset:3264
	v_cvt_pk_bf16_f32 v146, v46, v30
	ds_write_b32 v174, v146 offset:3392
	v_cvt_pk_bf16_f32 v178, v63, v15
	ds_write_b32 v174, v178 offset:3536
	v_cvt_pk_bf16_f32 v1, v47, v31
	ds_write_b32 v174, v1 offset:3664
	v_cvt_pk_bf16_f32 v146, v64, v16
	ds_write_b32 v174, v146 offset:3808
	v_cvt_pk_bf16_f32 v178, v48, v32
	ds_write_b32 v174, v178 offset:3936
	v_cvt_pk_bf16_f32 v1, v65, v17
	ds_write_b32 v174, v1 offset:4080
	v_cvt_pk_bf16_f32 v146, v49, v33
	ds_write_b32 v174, v146 offset:4208
	s_waitcnt lgkmcnt(0)
	ds_read_b128 v[2:5], v175
	ds_read_b128 v[6:9], v175 offset:64
	ds_read_b128 v[10:13], v175 offset:128
	ds_read_b128 v[14:17], v175 offset:192
	ds_read_b128 v[18:21], v175 offset:4352
	ds_read_b128 v[22:25], v175 offset:4416
	ds_read_b128 v[26:29], v175 offset:4480
	ds_read_b128 v[30:33], v175 offset:4544
	s_waitcnt vmcnt(0)
	s_waitcnt lgkmcnt(7)
	v_mfma_f32_16x16x32_bf16 v[34:37], v[94:97], v[2:5], 0
	s_waitcnt lgkmcnt(6)
	v_mfma_f32_16x16x32_bf16 v[34:37], v[90:93], v[6:9], v[34:37]
	s_waitcnt lgkmcnt(5)
	v_mfma_f32_16x16x32_bf16 v[34:37], v[86:89], v[10:13], v[34:37]
	s_waitcnt lgkmcnt(4)
	v_mfma_f32_16x16x32_bf16 v[34:37], v[82:85], v[14:17], v[34:37]
	s_waitcnt lgkmcnt(3)
	v_mfma_f32_16x16x32_bf16 v[38:41], v[94:97], v[18:21], 0
	s_waitcnt lgkmcnt(2)
	v_mfma_f32_16x16x32_bf16 v[38:41], v[90:93], v[22:25], v[38:41]
	s_waitcnt lgkmcnt(1)
	v_mfma_f32_16x16x32_bf16 v[38:41], v[86:89], v[26:29], v[38:41]
	s_waitcnt lgkmcnt(0)
	v_mfma_f32_16x16x32_bf16 v[38:41], v[82:85], v[30:33], v[38:41]
	s_add_u32 s6, s6, 0x8000
	s_addc_u32 s7, s7, 0
	v_lshlrev_b32_e32 v42, 16, v160
	v_and_b32_e32 v43, 0xffff0000, v160
	v_lshlrev_b32_e32 v44, 16, v161
	v_and_b32_e32 v45, 0xffff0000, v161
	v_lshlrev_b32_e32 v46, 16, v162
	v_and_b32_e32 v47, 0xffff0000, v162
	v_lshlrev_b32_e32 v48, 16, v163
	v_and_b32_e32 v49, 0xffff0000, v163
	s_nop 1
	v_mov_b32_e32 v156, 0x3d372713
	v_mov_b32_e32 v158, 0xbfcc422a
	v_mov_b32_e32 v164, 0x3fb8aa3b
	v_mov_b32_e32 v168, 1.0
	v_pk_fma_f32 v[50:51], v[98:99], v[42:43], v[34:35]
	v_pk_fma_f32 v[52:53], v[100:101], v[44:45], v[36:37]
	v_pk_fma_f32 v[54:55], v[98:99], v[46:47], v[38:39]
	v_pk_fma_f32 v[56:57], v[100:101], v[48:49], v[40:41]
	v_pk_mul_f32 v[2:3], v[50:51], v[156:157] op_sel_hi:[1,0]
	v_pk_mul_f32 v[4:5], v[52:53], v[156:157] op_sel_hi:[1,0]
	v_pk_mul_f32 v[6:7], v[54:55], v[156:157] op_sel_hi:[1,0]
	v_pk_mul_f32 v[8:9], v[56:57], v[156:157] op_sel_hi:[1,0]
	v_pk_mul_f32 v[2:3], v[50:51], v[2:3]
	v_pk_mul_f32 v[4:5], v[52:53], v[4:5]
	v_pk_mul_f32 v[6:7], v[54:55], v[6:7]
	v_pk_mul_f32 v[8:9], v[56:57], v[8:9]
	v_pk_fma_f32 v[2:3], v[50:51], v[2:3], v[50:51]
	v_pk_fma_f32 v[4:5], v[52:53], v[4:5], v[52:53]
	v_pk_fma_f32 v[6:7], v[54:55], v[6:7], v[54:55]
	v_pk_fma_f32 v[8:9], v[56:57], v[8:9], v[56:57]
	v_pk_mul_f32 v[2:3], v[2:3], v[158:159] op_sel_hi:[1,0]
	v_pk_mul_f32 v[4:5], v[4:5], v[158:159] op_sel_hi:[1,0]
	v_pk_mul_f32 v[6:7], v[6:7], v[158:159] op_sel_hi:[1,0]
	v_pk_mul_f32 v[8:9], v[8:9], v[158:159] op_sel_hi:[1,0]
	v_pk_mul_f32 v[2:3], v[2:3], v[164:165] op_sel_hi:[1,0]
	v_pk_mul_f32 v[4:5], v[4:5], v[164:165] op_sel_hi:[1,0]
	v_pk_mul_f32 v[6:7], v[6:7], v[164:165] op_sel_hi:[1,0]
	v_pk_mul_f32 v[8:9], v[8:9], v[164:165] op_sel_hi:[1,0]
	v_exp_f32_e32 v2, v2
	v_exp_f32_e32 v3, v3
	v_exp_f32_e32 v4, v4
	v_exp_f32_e32 v5, v5
	v_exp_f32_e32 v6, v6
	v_exp_f32_e32 v7, v7
	v_exp_f32_e32 v8, v8
	v_exp_f32_e32 v9, v9
	v_pk_add_f32 v[2:3], v[2:3], v[168:169] op_sel_hi:[1,0]
	v_pk_add_f32 v[4:5], v[4:5], v[168:169] op_sel_hi:[1,0]
	v_pk_add_f32 v[6:7], v[6:7], v[168:169] op_sel_hi:[1,0]
	v_pk_add_f32 v[8:9], v[8:9], v[168:169] op_sel_hi:[1,0]
	v_rcp_f32_e32 v2, v2
	v_rcp_f32_e32 v3, v3
	v_rcp_f32_e32 v4, v4
	v_rcp_f32_e32 v5, v5
	v_rcp_f32_e32 v6, v6
	v_rcp_f32_e32 v7, v7
	v_rcp_f32_e32 v8, v8
	v_rcp_f32_e32 v9, v9
	v_pk_mul_f32 v[50:51], v[50:51], v[2:3]
	v_pk_mul_f32 v[52:53], v[52:53], v[4:5]
	v_pk_mul_f32 v[54:55], v[54:55], v[6:7]
	v_pk_mul_f32 v[56:57], v[56:57], v[8:9]
	v_cvt_pk_bf16_f32 v10, v50, v51
	v_cvt_pk_bf16_f32 v11, v52, v53
	v_cvt_pk_bf16_f32 v12, v54, v55
	v_cvt_pk_bf16_f32 v13, v56, v57
	global_store_dwordx2 v176, v[10:11], s[10:11]
	global_store_dwordx2 v177, v[12:13], s[10:11]
	s_add_u32 s10, s10, 0x8000
	s_addc_u32 s11, s11, 0
	s_nop 0
	v_mfma_f32_32x32x16_bf16 v[50:65], v[134:137], v[114:117], 0
	v_mfma_f32_32x32x16_bf16 v[2:17], v[134:137], v[110:113], 0
	v_mfma_f32_32x32x16_bf16 v[34:49], v[134:137], v[106:109], 0
	v_mfma_f32_32x32x16_bf16 v[18:33], v[134:137], v[102:105], 0
	global_load_dwordx2 v[160:161], v176, s[6:7]
	global_load_dwordx2 v[162:163], v177, s[6:7]
	s_nop 9
	v_fmac_f32_e32 v51, v78, v50
	v_fmac_f32_e32 v35, v74, v34
	v_fmac_f32_e32 v3, v80, v50
	v_fmac_f32_e32 v19, v76, v34
	v_fma_f32 v51, -v80, v2, v51
	v_fma_f32 v35, -v76, v18, v35
	v_fmac_f32_e32 v3, v78, v2
	v_fmac_f32_e32 v19, v74, v18
	v_fmac_f32_e32 v52, v78, v51
	v_fmac_f32_e32 v36, v74, v35
	v_fmac_f32_e32 v4, v80, v51
	v_fmac_f32_e32 v20, v76, v35
	v_fma_f32 v52, -v80, v3, v52
	v_fma_f32 v36, -v76, v19, v36
	v_fmac_f32_e32 v4, v78, v3
	v_fmac_f32_e32 v20, v74, v19
	v_fmac_f32_e32 v53, v78, v52
	v_fmac_f32_e32 v37, v74, v36
	v_fmac_f32_e32 v5, v80, v52
	v_fmac_f32_e32 v21, v76, v36
	v_fma_f32 v53, -v80, v4, v53
	v_fma_f32 v37, -v76, v20, v37
	v_fmac_f32_e32 v5, v78, v4
	v_fmac_f32_e32 v21, v74, v20
	v_fmac_f32_e32 v54, v78, v53
	v_fmac_f32_e32 v38, v74, v37
	v_fmac_f32_e32 v6, v80, v53
	v_fmac_f32_e32 v22, v76, v37
	v_fma_f32 v54, -v80, v5, v54
	v_fma_f32 v38, -v76, v21, v38
	v_fmac_f32_e32 v6, v78, v5
	v_fmac_f32_e32 v22, v74, v21
	v_fmac_f32_e32 v55, v78, v54
	v_fmac_f32_e32 v39, v74, v38
	v_fmac_f32_e32 v7, v80, v54
	v_fmac_f32_e32 v23, v76, v38
	v_fma_f32 v55, -v80, v6, v55
	v_fma_f32 v39, -v76, v22, v39
	v_fmac_f32_e32 v7, v78, v6
	v_fmac_f32_e32 v23, v74, v22
	v_fmac_f32_e32 v56, v78, v55
	v_fmac_f32_e32 v40, v74, v39
	v_fmac_f32_e32 v8, v80, v55
	v_fmac_f32_e32 v24, v76, v39
	v_fma_f32 v56, -v80, v7, v56
	v_fma_f32 v40, -v76, v23, v40
	v_fmac_f32_e32 v8, v78, v7
	v_fmac_f32_e32 v24, v74, v23
	v_fmac_f32_e32 v57, v78, v56
	v_fmac_f32_e32 v41, v74, v40
	v_fmac_f32_e32 v9, v80, v56
	v_fmac_f32_e32 v25, v76, v40
	v_fma_f32 v57, -v80, v8, v57
	v_fma_f32 v41, -v76, v24, v41
	v_fmac_f32_e32 v9, v78, v8
	v_fmac_f32_e32 v25, v74, v24
	v_fmac_f32_e32 v58, v78, v57
	v_fmac_f32_e32 v42, v74, v41
	v_fmac_f32_e32 v10, v80, v57
	v_fmac_f32_e32 v26, v76, v41
	v_fma_f32 v58, -v80, v9, v58
	v_fma_f32 v42, -v76, v25, v42
	v_fmac_f32_e32 v10, v78, v9
	v_fmac_f32_e32 v26, v74, v25
	v_fmac_f32_e32 v59, v78, v58
	v_fmac_f32_e32 v43, v74, v42
	v_fmac_f32_e32 v11, v80, v58
	v_fmac_f32_e32 v27, v76, v42
	v_fma_f32 v59, -v80, v10, v59
	v_fma_f32 v43, -v76, v26, v43
	v_fmac_f32_e32 v11, v78, v10
	v_fmac_f32_e32 v27, v74, v26
	v_fmac_f32_e32 v60, v78, v59
	v_fmac_f32_e32 v44, v74, v43
	v_fmac_f32_e32 v12, v80, v59
	v_fmac_f32_e32 v28, v76, v43
	v_fma_f32 v60, -v80, v11, v60
	v_fma_f32 v44, -v76, v27, v44
	v_fmac_f32_e32 v12, v78, v11
	v_fmac_f32_e32 v28, v74, v27
	v_fmac_f32_e32 v61, v78, v60
	v_fmac_f32_e32 v45, v74, v44
	v_fmac_f32_e32 v13, v80, v60
	v_fmac_f32_e32 v29, v76, v44
	v_fma_f32 v61, -v80, v12, v61
	v_fma_f32 v45, -v76, v28, v45
	v_fmac_f32_e32 v13, v78, v12
	v_fmac_f32_e32 v29, v74, v28
	v_fmac_f32_e32 v62, v78, v61
	v_fmac_f32_e32 v46, v74, v45
	v_fmac_f32_e32 v14, v80, v61
	v_fmac_f32_e32 v30, v76, v45
	v_fma_f32 v62, -v80, v13, v62
	v_fma_f32 v46, -v76, v29, v46
	v_fmac_f32_e32 v14, v78, v13
	v_fmac_f32_e32 v30, v74, v29
	v_fmac_f32_e32 v63, v78, v62
	v_fmac_f32_e32 v47, v74, v46
	v_fmac_f32_e32 v15, v80, v62
	v_fmac_f32_e32 v31, v76, v46
	v_fma_f32 v63, -v80, v14, v63
	v_fma_f32 v47, -v76, v30, v47
	v_fmac_f32_e32 v15, v78, v14
	v_fmac_f32_e32 v31, v74, v30
	v_fmac_f32_e32 v64, v78, v63
	v_fmac_f32_e32 v48, v74, v47
	v_fmac_f32_e32 v16, v80, v63
	v_fmac_f32_e32 v32, v76, v47
	v_fma_f32 v64, -v80, v15, v64
	v_fma_f32 v48, -v76, v31, v48
	v_fmac_f32_e32 v16, v78, v15
	v_fmac_f32_e32 v32, v74, v31
	v_fmac_f32_e32 v65, v78, v64
	v_fmac_f32_e32 v49, v74, v48
	v_fmac_f32_e32 v17, v80, v64
	v_fmac_f32_e32 v33, v76, v48
	v_fma_f32 v65, -v80, v16, v65
	v_fma_f32 v49, -v76, v32, v49
	v_fmac_f32_e32 v17, v78, v16
	v_fmac_f32_e32 v33, v74, v32
	v_mov_b32_e32 v156, v65
	v_mov_b32_e32 v157, v17
	v_mov_b32_e32 v158, v65
	v_mov_b32_e32 v159, v17
	s_nop 1
	v_permlane32_swap_b32_e32 v156, v158
	v_permlane32_swap_b32_e32 v157, v159
	v_pk_fma_f32 v[164:165], v[166:167], v[152:153], v[156:157] op_sel_hi:[1,0,1]
	v_pk_fma_f32 v[164:165], v[166:167], v[152:153], v[164:165] op_sel:[1,1,0] op_sel_hi:[0,1,1] neg_lo:[0,1,0]
	v_cndmask_b32_e32 v164, v166, v164, vcc
	v_cndmask_b32_e32 v165, v167, v165, vcc
	v_mov_b32_e32 v156, v49
	v_mov_b32_e32 v157, v33
	v_mov_b32_e32 v158, v49
	v_mov_b32_e32 v159, v33
	s_nop 1
	v_permlane32_swap_b32_e32 v156, v158
	v_permlane32_swap_b32_e32 v157, v159
	v_pk_fma_f32 v[170:171], v[150:151], v[154:155], v[156:157] op_sel_hi:[1,0,1]
	v_pk_fma_f32 v[170:171], v[150:151], v[154:155], v[170:171] op_sel:[1,1,0] op_sel_hi:[0,1,1] neg_lo:[0,1,0]
	v_cndmask_b32_e32 v170, v150, v170, vcc
	v_cndmask_b32_e32 v171, v151, v171, vcc
	v_pk_mul_f32 v[168:169], v[164:165], v[70:71] op_sel:[0,1] op_sel_hi:[1,1]
	v_pk_mul_f32 v[172:173], v[170:171], v[66:67] op_sel:[0,1] op_sel_hi:[1,1]
	v_pk_fma_f32 v[168:169], v[164:165], v[72:73], v[168:169] op_sel:[1,1,0] op_sel_hi:[0,1,1] neg_lo:[0,1,0]
	v_pk_fma_f32 v[172:173], v[170:171], v[68:69], v[172:173] op_sel:[1,1,0] op_sel_hi:[0,1,1] neg_lo:[0,1,0]
	v_pk_fma_f32 v[50:51], v[78:79], v[164:165], v[50:51] op_sel_hi:[1,0,1]
	v_pk_fma_f32 v[34:35], v[74:75], v[170:171], v[34:35] op_sel_hi:[1,0,1]
	v_pk_fma_f32 v[52:53], v[70:71], v[164:165], v[52:53] op_sel_hi:[1,0,1]
	v_pk_fma_f32 v[36:37], v[66:67], v[170:171], v[36:37] op_sel_hi:[1,0,1]
	v_pk_fma_f32 v[2:3], v[80:81], v[164:165], v[2:3] op_sel_hi:[1,0,1]
	v_pk_fma_f32 v[18:19], v[76:77], v[170:171], v[18:19] op_sel_hi:[1,0,1]
	v_pk_fma_f32 v[4:5], v[72:73], v[164:165], v[4:5] op_sel_hi:[1,0,1]
	v_pk_fma_f32 v[20:21], v[68:69], v[170:171], v[20:21] op_sel_hi:[1,0,1]
	v_pk_fma_f32 v[50:51], v[80:81], v[164:165], v[50:51] op_sel:[0,1,0] op_sel_hi:[1,1,1] neg_lo:[0,1,0] neg_hi:[0,1,0]
	v_pk_fma_f32 v[34:35], v[76:77], v[170:171], v[34:35] op_sel:[0,1,0] op_sel_hi:[1,1,1] neg_lo:[0,1,0] neg_hi:[0,1,0]
	v_pk_fma_f32 v[52:53], v[72:73], v[164:165], v[52:53] op_sel:[0,1,0] op_sel_hi:[1,1,1] neg_lo:[0,1,0] neg_hi:[0,1,0]
	v_pk_fma_f32 v[36:37], v[68:69], v[170:171], v[36:37] op_sel:[0,1,0] op_sel_hi:[1,1,1] neg_lo:[0,1,0] neg_hi:[0,1,0]
	v_pk_fma_f32 v[2:3], v[78:79], v[164:165], v[2:3] op_sel:[0,1,0] op_sel_hi:[1,1,1]
	v_pk_fma_f32 v[18:19], v[74:75], v[170:171], v[18:19] op_sel:[0,1,0] op_sel_hi:[1,1,1]
	v_pk_fma_f32 v[4:5], v[70:71], v[164:165], v[4:5] op_sel:[0,1,0] op_sel_hi:[1,1,1]
	v_pk_fma_f32 v[20:21], v[66:67], v[170:171], v[20:21] op_sel:[0,1,0] op_sel_hi:[1,1,1]
	v_pk_mul_f32 v[164:165], v[168:169], v[70:71] op_sel:[0,1] op_sel_hi:[1,1]
	v_pk_mul_f32 v[170:171], v[172:173], v[66:67] op_sel:[0,1] op_sel_hi:[1,1]
	v_pk_fma_f32 v[164:165], v[168:169], v[72:73], v[164:165] op_sel:[1,1,0] op_sel_hi:[0,1,1] neg_lo:[0,1,0]
	v_pk_fma_f32 v[170:171], v[172:173], v[68:69], v[170:171] op_sel:[1,1,0] op_sel_hi:[0,1,1] neg_lo:[0,1,0]
	v_pk_fma_f32 v[54:55], v[78:79], v[168:169], v[54:55] op_sel_hi:[1,0,1]
	v_pk_fma_f32 v[38:39], v[74:75], v[172:173], v[38:39] op_sel_hi:[1,0,1]
	v_pk_fma_f32 v[56:57], v[70:71], v[168:169], v[56:57] op_sel_hi:[1,0,1]
	v_pk_fma_f32 v[40:41], v[66:67], v[172:173], v[40:41] op_sel_hi:[1,0,1]
	v_pk_fma_f32 v[6:7], v[80:81], v[168:169], v[6:7] op_sel_hi:[1,0,1]
	v_pk_fma_f32 v[22:23], v[76:77], v[172:173], v[22:23] op_sel_hi:[1,0,1]
	v_pk_fma_f32 v[8:9], v[72:73], v[168:169], v[8:9] op_sel_hi:[1,0,1]
	v_pk_fma_f32 v[24:25], v[68:69], v[172:173], v[24:25] op_sel_hi:[1,0,1]
	v_pk_fma_f32 v[54:55], v[80:81], v[168:169], v[54:55] op_sel:[0,1,0] op_sel_hi:[1,1,1] neg_lo:[0,1,0] neg_hi:[0,1,0]
	v_pk_fma_f32 v[38:39], v[76:77], v[172:173], v[38:39] op_sel:[0,1,0] op_sel_hi:[1,1,1] neg_lo:[0,1,0] neg_hi:[0,1,0]
	v_pk_fma_f32 v[56:57], v[72:73], v[168:169], v[56:57] op_sel:[0,1,0] op_sel_hi:[1,1,1] neg_lo:[0,1,0] neg_hi:[0,1,0]
	v_pk_fma_f32 v[40:41], v[68:69], v[172:173], v[40:41] op_sel:[0,1,0] op_sel_hi:[1,1,1] neg_lo:[0,1,0] neg_hi:[0,1,0]
	v_pk_fma_f32 v[6:7], v[78:79], v[168:169], v[6:7] op_sel:[0,1,0] op_sel_hi:[1,1,1]
	v_pk_fma_f32 v[22:23], v[74:75], v[172:173], v[22:23] op_sel:[0,1,0] op_sel_hi:[1,1,1]
	v_pk_fma_f32 v[8:9], v[70:71], v[168:169], v[8:9] op_sel:[0,1,0] op_sel_hi:[1,1,1]
	v_pk_fma_f32 v[24:25], v[66:67], v[172:173], v[24:25] op_sel:[0,1,0] op_sel_hi:[1,1,1]
	v_pk_mul_f32 v[168:169], v[164:165], v[70:71] op_sel:[0,1] op_sel_hi:[1,1]
	v_pk_mul_f32 v[172:173], v[170:171], v[66:67] op_sel:[0,1] op_sel_hi:[1,1]
	v_pk_fma_f32 v[168:169], v[164:165], v[72:73], v[168:169] op_sel:[1,1,0] op_sel_hi:[0,1,1] neg_lo:[0,1,0]
	v_pk_fma_f32 v[172:173], v[170:171], v[68:69], v[172:173] op_sel:[1,1,0] op_sel_hi:[0,1,1] neg_lo:[0,1,0]
	v_pk_fma_f32 v[58:59], v[78:79], v[164:165], v[58:59] op_sel_hi:[1,0,1]
	v_pk_fma_f32 v[42:43], v[74:75], v[170:171], v[42:43] op_sel_hi:[1,0,1]
	v_pk_fma_f32 v[60:61], v[70:71], v[164:165], v[60:61] op_sel_hi:[1,0,1]
	v_pk_fma_f32 v[44:45], v[66:67], v[170:171], v[44:45] op_sel_hi:[1,0,1]
	v_pk_fma_f32 v[10:11], v[80:81], v[164:165], v[10:11] op_sel_hi:[1,0,1]
	v_pk_fma_f32 v[26:27], v[76:77], v[170:171], v[26:27] op_sel_hi:[1,0,1]
	v_pk_fma_f32 v[12:13], v[72:73], v[164:165], v[12:13] op_sel_hi:[1,0,1]
	v_pk_fma_f32 v[28:29], v[68:69], v[170:171], v[28:29] op_sel_hi:[1,0,1]
	v_pk_fma_f32 v[58:59], v[80:81], v[164:165], v[58:59] op_sel:[0,1,0] op_sel_hi:[1,1,1] neg_lo:[0,1,0] neg_hi:[0,1,0]
	v_pk_fma_f32 v[42:43], v[76:77], v[170:171], v[42:43] op_sel:[0,1,0] op_sel_hi:[1,1,1] neg_lo:[0,1,0] neg_hi:[0,1,0]
	v_pk_fma_f32 v[60:61], v[72:73], v[164:165], v[60:61] op_sel:[0,1,0] op_sel_hi:[1,1,1] neg_lo:[0,1,0] neg_hi:[0,1,0]
	v_pk_fma_f32 v[44:45], v[68:69], v[170:171], v[44:45] op_sel:[0,1,0] op_sel_hi:[1,1,1] neg_lo:[0,1,0] neg_hi:[0,1,0]
	v_pk_fma_f32 v[10:11], v[78:79], v[164:165], v[10:11] op_sel:[0,1,0] op_sel_hi:[1,1,1]
	v_pk_fma_f32 v[26:27], v[74:75], v[170:171], v[26:27] op_sel:[0,1,0] op_sel_hi:[1,1,1]
	v_pk_fma_f32 v[12:13], v[70:71], v[164:165], v[12:13] op_sel:[0,1,0] op_sel_hi:[1,1,1]
	v_pk_fma_f32 v[28:29], v[66:67], v[170:171], v[28:29] op_sel:[0,1,0] op_sel_hi:[1,1,1]
	v_pk_fma_f32 v[62:63], v[78:79], v[168:169], v[62:63] op_sel_hi:[1,0,1]
	v_pk_fma_f32 v[46:47], v[74:75], v[172:173], v[46:47] op_sel_hi:[1,0,1]
	v_pk_fma_f32 v[64:65], v[70:71], v[168:169], v[64:65] op_sel_hi:[1,0,1]
	v_pk_fma_f32 v[48:49], v[66:67], v[172:173], v[48:49] op_sel_hi:[1,0,1]
	v_pk_fma_f32 v[14:15], v[80:81], v[168:169], v[14:15] op_sel_hi:[1,0,1]
	v_pk_fma_f32 v[30:31], v[76:77], v[172:173], v[30:31] op_sel_hi:[1,0,1]
	v_pk_fma_f32 v[16:17], v[72:73], v[168:169], v[16:17] op_sel_hi:[1,0,1]
	v_pk_fma_f32 v[32:33], v[68:69], v[172:173], v[32:33] op_sel_hi:[1,0,1]
	v_pk_fma_f32 v[62:63], v[80:81], v[168:169], v[62:63] op_sel:[0,1,0] op_sel_hi:[1,1,1] neg_lo:[0,1,0] neg_hi:[0,1,0]
	v_pk_fma_f32 v[46:47], v[76:77], v[172:173], v[46:47] op_sel:[0,1,0] op_sel_hi:[1,1,1] neg_lo:[0,1,0] neg_hi:[0,1,0]
	v_pk_fma_f32 v[64:65], v[72:73], v[168:169], v[64:65] op_sel:[0,1,0] op_sel_hi:[1,1,1] neg_lo:[0,1,0] neg_hi:[0,1,0]
	v_pk_fma_f32 v[48:49], v[68:69], v[172:173], v[48:49] op_sel:[0,1,0] op_sel_hi:[1,1,1] neg_lo:[0,1,0] neg_hi:[0,1,0]
	v_pk_fma_f32 v[14:15], v[78:79], v[168:169], v[14:15] op_sel:[0,1,0] op_sel_hi:[1,1,1]
	v_pk_fma_f32 v[30:31], v[74:75], v[172:173], v[30:31] op_sel:[0,1,0] op_sel_hi:[1,1,1]
	v_pk_fma_f32 v[16:17], v[70:71], v[168:169], v[16:17] op_sel:[0,1,0] op_sel_hi:[1,1,1]
	v_pk_fma_f32 v[32:33], v[66:67], v[172:173], v[32:33] op_sel:[0,1,0] op_sel_hi:[1,1,1]
	v_mov_b32_e32 v156, v65
	v_mov_b32_e32 v157, v17
	v_mov_b32_e32 v166, v65
	v_mov_b32_e32 v167, v17
	s_nop 1
	v_permlane32_swap_b32_e32 v156, v166
	v_permlane32_swap_b32_e32 v157, v167
	v_mov_b32_e32 v156, v49
	v_mov_b32_e32 v157, v33
	v_mov_b32_e32 v150, v49
	v_mov_b32_e32 v151, v33
	s_nop 1
	v_permlane32_swap_b32_e32 v156, v150
	v_permlane32_swap_b32_e32 v157, v151
	v_cvt_pk_bf16_f32 v1, v50, v2
	ds_write_b32 v174, v1
	v_cvt_pk_bf16_f32 v146, v34, v18
	ds_write_b32 v174, v146 offset:128
	v_cvt_pk_bf16_f32 v178, v51, v3
	ds_write_b32 v174, v178 offset:272
	v_cvt_pk_bf16_f32 v1, v35, v19
	ds_write_b32 v174, v1 offset:400
	v_cvt_pk_bf16_f32 v146, v52, v4
	ds_write_b32 v174, v146 offset:544
	v_cvt_pk_bf16_f32 v178, v36, v20
	ds_write_b32 v174, v178 offset:672
	v_cvt_pk_bf16_f32 v1, v53, v5
	ds_write_b32 v174, v1 offset:816
	v_cvt_pk_bf16_f32 v146, v37, v21
	ds_write_b32 v174, v146 offset:944
	v_cvt_pk_bf16_f32 v178, v54, v6
	ds_write_b32 v174, v178 offset:1088
	v_cvt_pk_bf16_f32 v1, v38, v22
	ds_write_b32 v174, v1 offset:1216
	v_cvt_pk_bf16_f32 v146, v55, v7
	ds_write_b32 v174, v146 offset:1360
	v_cvt_pk_bf16_f32 v178, v39, v23
	ds_write_b32 v174, v178 offset:1488
	v_cvt_pk_bf16_f32 v1, v56, v8
	ds_write_b32 v174, v1 offset:1632
	v_cvt_pk_bf16_f32 v146, v40, v24
	ds_write_b32 v174, v146 offset:1760
	v_cvt_pk_bf16_f32 v178, v57, v9
	ds_write_b32 v174, v178 offset:1904
	v_cvt_pk_bf16_f32 v1, v41, v25
	ds_write_b32 v174, v1 offset:2032
	v_cvt_pk_bf16_f32 v146, v58, v10
	ds_write_b32 v174, v146 offset:2176
	v_cvt_pk_bf16_f32 v178, v42, v26
	ds_write_b32 v174, v178 offset:2304
	v_cvt_pk_bf16_f32 v1, v59, v11
	ds_write_b32 v174, v1 offset:2448
	v_cvt_pk_bf16_f32 v146, v43, v27
	ds_write_b32 v174, v146 offset:2576
	v_cvt_pk_bf16_f32 v178, v60, v12
	ds_write_b32 v174, v178 offset:2720
	v_cvt_pk_bf16_f32 v1, v44, v28
	ds_write_b32 v174, v1 offset:2848
	v_cvt_pk_bf16_f32 v146, v61, v13
	ds_write_b32 v174, v146 offset:2992
	v_cvt_pk_bf16_f32 v178, v45, v29
	ds_write_b32 v174, v178 offset:3120
	v_cvt_pk_bf16_f32 v1, v62, v14
	ds_write_b32 v174, v1 offset:3264
	v_cvt_pk_bf16_f32 v146, v46, v30
	ds_write_b32 v174, v146 offset:3392
	v_cvt_pk_bf16_f32 v178, v63, v15
	ds_write_b32 v174, v178 offset:3536
	v_cvt_pk_bf16_f32 v1, v47, v31
	ds_write_b32 v174, v1 offset:3664
	v_cvt_pk_bf16_f32 v146, v64, v16
	ds_write_b32 v174, v146 offset:3808
	v_cvt_pk_bf16_f32 v178, v48, v32
	ds_write_b32 v174, v178 offset:3936
	v_cvt_pk_bf16_f32 v1, v65, v17
	ds_write_b32 v174, v1 offset:4080
	v_cvt_pk_bf16_f32 v146, v49, v33
	ds_write_b32 v174, v146 offset:4208
	s_waitcnt lgkmcnt(0)
	ds_read_b128 v[2:5], v175
	ds_read_b128 v[6:9], v175 offset:64
	ds_read_b128 v[10:13], v175 offset:128
	ds_read_b128 v[14:17], v175 offset:192
	ds_read_b128 v[18:21], v175 offset:4352
	ds_read_b128 v[22:25], v175 offset:4416
	ds_read_b128 v[26:29], v175 offset:4480
	ds_read_b128 v[30:33], v175 offset:4544
	s_waitcnt vmcnt(0)
	s_waitcnt lgkmcnt(7)
	v_mfma_f32_16x16x32_bf16 v[34:37], v[94:97], v[2:5], 0
	s_waitcnt lgkmcnt(6)
	v_mfma_f32_16x16x32_bf16 v[34:37], v[90:93], v[6:9], v[34:37]
	s_waitcnt lgkmcnt(5)
	v_mfma_f32_16x16x32_bf16 v[34:37], v[86:89], v[10:13], v[34:37]
	s_waitcnt lgkmcnt(4)
	v_mfma_f32_16x16x32_bf16 v[34:37], v[82:85], v[14:17], v[34:37]
	s_waitcnt lgkmcnt(3)
	v_mfma_f32_16x16x32_bf16 v[38:41], v[94:97], v[18:21], 0
	s_waitcnt lgkmcnt(2)
	v_mfma_f32_16x16x32_bf16 v[38:41], v[90:93], v[22:25], v[38:41]
	s_waitcnt lgkmcnt(1)
	v_mfma_f32_16x16x32_bf16 v[38:41], v[86:89], v[26:29], v[38:41]
	s_waitcnt lgkmcnt(0)
	v_mfma_f32_16x16x32_bf16 v[38:41], v[82:85], v[30:33], v[38:41]
	s_add_u32 s6, s6, 0x8000
	s_addc_u32 s7, s7, 0
	v_lshlrev_b32_e32 v42, 16, v160
	v_and_b32_e32 v43, 0xffff0000, v160
	v_lshlrev_b32_e32 v44, 16, v161
	v_and_b32_e32 v45, 0xffff0000, v161
	v_lshlrev_b32_e32 v46, 16, v162
	v_and_b32_e32 v47, 0xffff0000, v162
	v_lshlrev_b32_e32 v48, 16, v163
	v_and_b32_e32 v49, 0xffff0000, v163
	s_nop 1
	v_mov_b32_e32 v156, 0x3d372713
	v_mov_b32_e32 v158, 0xbfcc422a
	v_mov_b32_e32 v164, 0x3fb8aa3b
	v_mov_b32_e32 v168, 1.0
	v_pk_fma_f32 v[50:51], v[98:99], v[42:43], v[34:35]
	v_pk_fma_f32 v[52:53], v[100:101], v[44:45], v[36:37]
	v_pk_fma_f32 v[54:55], v[98:99], v[46:47], v[38:39]
	v_pk_fma_f32 v[56:57], v[100:101], v[48:49], v[40:41]
	v_pk_mul_f32 v[2:3], v[50:51], v[156:157] op_sel_hi:[1,0]
	v_pk_mul_f32 v[4:5], v[52:53], v[156:157] op_sel_hi:[1,0]
	v_pk_mul_f32 v[6:7], v[54:55], v[156:157] op_sel_hi:[1,0]
	v_pk_mul_f32 v[8:9], v[56:57], v[156:157] op_sel_hi:[1,0]
	v_pk_mul_f32 v[2:3], v[50:51], v[2:3]
	v_pk_mul_f32 v[4:5], v[52:53], v[4:5]
	v_pk_mul_f32 v[6:7], v[54:55], v[6:7]
	v_pk_mul_f32 v[8:9], v[56:57], v[8:9]
	v_pk_fma_f32 v[2:3], v[50:51], v[2:3], v[50:51]
	v_pk_fma_f32 v[4:5], v[52:53], v[4:5], v[52:53]
	v_pk_fma_f32 v[6:7], v[54:55], v[6:7], v[54:55]
	v_pk_fma_f32 v[8:9], v[56:57], v[8:9], v[56:57]
	v_pk_mul_f32 v[2:3], v[2:3], v[158:159] op_sel_hi:[1,0]
	v_pk_mul_f32 v[4:5], v[4:5], v[158:159] op_sel_hi:[1,0]
	v_pk_mul_f32 v[6:7], v[6:7], v[158:159] op_sel_hi:[1,0]
	v_pk_mul_f32 v[8:9], v[8:9], v[158:159] op_sel_hi:[1,0]
	v_pk_mul_f32 v[2:3], v[2:3], v[164:165] op_sel_hi:[1,0]
	v_pk_mul_f32 v[4:5], v[4:5], v[164:165] op_sel_hi:[1,0]
	v_pk_mul_f32 v[6:7], v[6:7], v[164:165] op_sel_hi:[1,0]
	v_pk_mul_f32 v[8:9], v[8:9], v[164:165] op_sel_hi:[1,0]
	v_exp_f32_e32 v2, v2
	v_exp_f32_e32 v3, v3
	v_exp_f32_e32 v4, v4
	v_exp_f32_e32 v5, v5
	v_exp_f32_e32 v6, v6
	v_exp_f32_e32 v7, v7
	v_exp_f32_e32 v8, v8
	v_exp_f32_e32 v9, v9
	v_pk_add_f32 v[2:3], v[2:3], v[168:169] op_sel_hi:[1,0]
	v_pk_add_f32 v[4:5], v[4:5], v[168:169] op_sel_hi:[1,0]
	v_pk_add_f32 v[6:7], v[6:7], v[168:169] op_sel_hi:[1,0]
	v_pk_add_f32 v[8:9], v[8:9], v[168:169] op_sel_hi:[1,0]
	v_rcp_f32_e32 v2, v2
	v_rcp_f32_e32 v3, v3
	v_rcp_f32_e32 v4, v4
	v_rcp_f32_e32 v5, v5
	v_rcp_f32_e32 v6, v6
	v_rcp_f32_e32 v7, v7
	v_rcp_f32_e32 v8, v8
	v_rcp_f32_e32 v9, v9
	v_pk_mul_f32 v[50:51], v[50:51], v[2:3]
	v_pk_mul_f32 v[52:53], v[52:53], v[4:5]
	v_pk_mul_f32 v[54:55], v[54:55], v[6:7]
	v_pk_mul_f32 v[56:57], v[56:57], v[8:9]
	v_cvt_pk_bf16_f32 v10, v50, v51
	v_cvt_pk_bf16_f32 v11, v52, v53
	v_cvt_pk_bf16_f32 v12, v54, v55
	v_cvt_pk_bf16_f32 v13, v56, v57
	global_store_dwordx2 v176, v[10:11], s[10:11]
	global_store_dwordx2 v177, v[12:13], s[10:11]
	s_add_u32 s10, s10, 0x8000
	s_addc_u32 s11, s11, 0
	s_nop 0
	v_mfma_f32_32x32x16_bf16 v[50:65], v[130:133], v[114:117], 0
	v_mfma_f32_32x32x16_bf16 v[2:17], v[130:133], v[110:113], 0
	v_mfma_f32_32x32x16_bf16 v[34:49], v[130:133], v[106:109], 0
	v_mfma_f32_32x32x16_bf16 v[18:33], v[130:133], v[102:105], 0
	global_load_dwordx2 v[160:161], v176, s[6:7]
	global_load_dwordx2 v[162:163], v177, s[6:7]
	s_nop 9
	v_fmac_f32_e32 v51, v78, v50
	v_fmac_f32_e32 v35, v74, v34
	v_fmac_f32_e32 v3, v80, v50
	v_fmac_f32_e32 v19, v76, v34
	v_fma_f32 v51, -v80, v2, v51
	v_fma_f32 v35, -v76, v18, v35
	v_fmac_f32_e32 v3, v78, v2
	v_fmac_f32_e32 v19, v74, v18
	v_fmac_f32_e32 v52, v78, v51
	v_fmac_f32_e32 v36, v74, v35
	v_fmac_f32_e32 v4, v80, v51
	v_fmac_f32_e32 v20, v76, v35
	v_fma_f32 v52, -v80, v3, v52
	v_fma_f32 v36, -v76, v19, v36
	v_fmac_f32_e32 v4, v78, v3
	v_fmac_f32_e32 v20, v74, v19
	v_fmac_f32_e32 v53, v78, v52
	v_fmac_f32_e32 v37, v74, v36
	v_fmac_f32_e32 v5, v80, v52
	v_fmac_f32_e32 v21, v76, v36
	v_fma_f32 v53, -v80, v4, v53
	v_fma_f32 v37, -v76, v20, v37
	v_fmac_f32_e32 v5, v78, v4
	v_fmac_f32_e32 v21, v74, v20
	v_fmac_f32_e32 v54, v78, v53
	v_fmac_f32_e32 v38, v74, v37
	v_fmac_f32_e32 v6, v80, v53
	v_fmac_f32_e32 v22, v76, v37
	v_fma_f32 v54, -v80, v5, v54
	v_fma_f32 v38, -v76, v21, v38
	v_fmac_f32_e32 v6, v78, v5
	v_fmac_f32_e32 v22, v74, v21
	v_fmac_f32_e32 v55, v78, v54
	v_fmac_f32_e32 v39, v74, v38
	v_fmac_f32_e32 v7, v80, v54
	v_fmac_f32_e32 v23, v76, v38
	v_fma_f32 v55, -v80, v6, v55
	v_fma_f32 v39, -v76, v22, v39
	v_fmac_f32_e32 v7, v78, v6
	v_fmac_f32_e32 v23, v74, v22
	v_fmac_f32_e32 v56, v78, v55
	v_fmac_f32_e32 v40, v74, v39
	v_fmac_f32_e32 v8, v80, v55
	v_fmac_f32_e32 v24, v76, v39
	v_fma_f32 v56, -v80, v7, v56
	v_fma_f32 v40, -v76, v23, v40
	v_fmac_f32_e32 v8, v78, v7
	v_fmac_f32_e32 v24, v74, v23
	v_fmac_f32_e32 v57, v78, v56
	v_fmac_f32_e32 v41, v74, v40
	v_fmac_f32_e32 v9, v80, v56
	v_fmac_f32_e32 v25, v76, v40
	v_fma_f32 v57, -v80, v8, v57
	v_fma_f32 v41, -v76, v24, v41
	v_fmac_f32_e32 v9, v78, v8
	v_fmac_f32_e32 v25, v74, v24
	v_fmac_f32_e32 v58, v78, v57
	v_fmac_f32_e32 v42, v74, v41
	v_fmac_f32_e32 v10, v80, v57
	v_fmac_f32_e32 v26, v76, v41
	v_fma_f32 v58, -v80, v9, v58
	v_fma_f32 v42, -v76, v25, v42
	v_fmac_f32_e32 v10, v78, v9
	v_fmac_f32_e32 v26, v74, v25
	v_fmac_f32_e32 v59, v78, v58
	v_fmac_f32_e32 v43, v74, v42
	v_fmac_f32_e32 v11, v80, v58
	v_fmac_f32_e32 v27, v76, v42
	v_fma_f32 v59, -v80, v10, v59
	v_fma_f32 v43, -v76, v26, v43
	v_fmac_f32_e32 v11, v78, v10
	v_fmac_f32_e32 v27, v74, v26
	v_fmac_f32_e32 v60, v78, v59
	v_fmac_f32_e32 v44, v74, v43
	v_fmac_f32_e32 v12, v80, v59
	v_fmac_f32_e32 v28, v76, v43
	v_fma_f32 v60, -v80, v11, v60
	v_fma_f32 v44, -v76, v27, v44
	v_fmac_f32_e32 v12, v78, v11
	v_fmac_f32_e32 v28, v74, v27
	v_fmac_f32_e32 v61, v78, v60
	v_fmac_f32_e32 v45, v74, v44
	v_fmac_f32_e32 v13, v80, v60
	v_fmac_f32_e32 v29, v76, v44
	v_fma_f32 v61, -v80, v12, v61
	v_fma_f32 v45, -v76, v28, v45
	v_fmac_f32_e32 v13, v78, v12
	v_fmac_f32_e32 v29, v74, v28
	v_fmac_f32_e32 v62, v78, v61
	v_fmac_f32_e32 v46, v74, v45
	v_fmac_f32_e32 v14, v80, v61
	v_fmac_f32_e32 v30, v76, v45
	v_fma_f32 v62, -v80, v13, v62
	v_fma_f32 v46, -v76, v29, v46
	v_fmac_f32_e32 v14, v78, v13
	v_fmac_f32_e32 v30, v74, v29
	v_fmac_f32_e32 v63, v78, v62
	v_fmac_f32_e32 v47, v74, v46
	v_fmac_f32_e32 v15, v80, v62
	v_fmac_f32_e32 v31, v76, v46
	v_fma_f32 v63, -v80, v14, v63
	v_fma_f32 v47, -v76, v30, v47
	v_fmac_f32_e32 v15, v78, v14
	v_fmac_f32_e32 v31, v74, v30
	v_fmac_f32_e32 v64, v78, v63
	v_fmac_f32_e32 v48, v74, v47
	v_fmac_f32_e32 v16, v80, v63
	v_fmac_f32_e32 v32, v76, v47
	v_fma_f32 v64, -v80, v15, v64
	v_fma_f32 v48, -v76, v31, v48
	v_fmac_f32_e32 v16, v78, v15
	v_fmac_f32_e32 v32, v74, v31
	v_fmac_f32_e32 v65, v78, v64
	v_fmac_f32_e32 v49, v74, v48
	v_fmac_f32_e32 v17, v80, v64
	v_fmac_f32_e32 v33, v76, v48
	v_fma_f32 v65, -v80, v16, v65
	v_fma_f32 v49, -v76, v32, v49
	v_fmac_f32_e32 v17, v78, v16
	v_fmac_f32_e32 v33, v74, v32
	v_mov_b32_e32 v156, v65
	v_mov_b32_e32 v157, v17
	v_mov_b32_e32 v158, v65
	v_mov_b32_e32 v159, v17
	s_nop 1
	v_permlane32_swap_b32_e32 v156, v158
	v_permlane32_swap_b32_e32 v157, v159
	v_pk_fma_f32 v[164:165], v[166:167], v[152:153], v[156:157] op_sel_hi:[1,0,1]
	v_pk_fma_f32 v[164:165], v[166:167], v[152:153], v[164:165] op_sel:[1,1,0] op_sel_hi:[0,1,1] neg_lo:[0,1,0]
	v_cndmask_b32_e32 v164, v166, v164, vcc
	v_cndmask_b32_e32 v165, v167, v165, vcc
	v_mov_b32_e32 v156, v49
	v_mov_b32_e32 v157, v33
	v_mov_b32_e32 v158, v49
	v_mov_b32_e32 v159, v33
	s_nop 1
	v_permlane32_swap_b32_e32 v156, v158
	v_permlane32_swap_b32_e32 v157, v159
	v_pk_fma_f32 v[170:171], v[150:151], v[154:155], v[156:157] op_sel_hi:[1,0,1]
	v_pk_fma_f32 v[170:171], v[150:151], v[154:155], v[170:171] op_sel:[1,1,0] op_sel_hi:[0,1,1] neg_lo:[0,1,0]
	v_cndmask_b32_e32 v170, v150, v170, vcc
	v_cndmask_b32_e32 v171, v151, v171, vcc
	v_pk_mul_f32 v[168:169], v[164:165], v[70:71] op_sel:[0,1] op_sel_hi:[1,1]
	v_pk_mul_f32 v[172:173], v[170:171], v[66:67] op_sel:[0,1] op_sel_hi:[1,1]
	v_pk_fma_f32 v[168:169], v[164:165], v[72:73], v[168:169] op_sel:[1,1,0] op_sel_hi:[0,1,1] neg_lo:[0,1,0]
	v_pk_fma_f32 v[172:173], v[170:171], v[68:69], v[172:173] op_sel:[1,1,0] op_sel_hi:[0,1,1] neg_lo:[0,1,0]
	v_pk_fma_f32 v[50:51], v[78:79], v[164:165], v[50:51] op_sel_hi:[1,0,1]
	v_pk_fma_f32 v[34:35], v[74:75], v[170:171], v[34:35] op_sel_hi:[1,0,1]
	v_pk_fma_f32 v[52:53], v[70:71], v[164:165], v[52:53] op_sel_hi:[1,0,1]
	v_pk_fma_f32 v[36:37], v[66:67], v[170:171], v[36:37] op_sel_hi:[1,0,1]
	v_pk_fma_f32 v[2:3], v[80:81], v[164:165], v[2:3] op_sel_hi:[1,0,1]
	v_pk_fma_f32 v[18:19], v[76:77], v[170:171], v[18:19] op_sel_hi:[1,0,1]
	v_pk_fma_f32 v[4:5], v[72:73], v[164:165], v[4:5] op_sel_hi:[1,0,1]
	v_pk_fma_f32 v[20:21], v[68:69], v[170:171], v[20:21] op_sel_hi:[1,0,1]
	v_pk_fma_f32 v[50:51], v[80:81], v[164:165], v[50:51] op_sel:[0,1,0] op_sel_hi:[1,1,1] neg_lo:[0,1,0] neg_hi:[0,1,0]
	v_pk_fma_f32 v[34:35], v[76:77], v[170:171], v[34:35] op_sel:[0,1,0] op_sel_hi:[1,1,1] neg_lo:[0,1,0] neg_hi:[0,1,0]
	v_pk_fma_f32 v[52:53], v[72:73], v[164:165], v[52:53] op_sel:[0,1,0] op_sel_hi:[1,1,1] neg_lo:[0,1,0] neg_hi:[0,1,0]
	v_pk_fma_f32 v[36:37], v[68:69], v[170:171], v[36:37] op_sel:[0,1,0] op_sel_hi:[1,1,1] neg_lo:[0,1,0] neg_hi:[0,1,0]
	v_pk_fma_f32 v[2:3], v[78:79], v[164:165], v[2:3] op_sel:[0,1,0] op_sel_hi:[1,1,1]
	v_pk_fma_f32 v[18:19], v[74:75], v[170:171], v[18:19] op_sel:[0,1,0] op_sel_hi:[1,1,1]
	v_pk_fma_f32 v[4:5], v[70:71], v[164:165], v[4:5] op_sel:[0,1,0] op_sel_hi:[1,1,1]
	v_pk_fma_f32 v[20:21], v[66:67], v[170:171], v[20:21] op_sel:[0,1,0] op_sel_hi:[1,1,1]
	v_pk_mul_f32 v[164:165], v[168:169], v[70:71] op_sel:[0,1] op_sel_hi:[1,1]
	v_pk_mul_f32 v[170:171], v[172:173], v[66:67] op_sel:[0,1] op_sel_hi:[1,1]
	v_pk_fma_f32 v[164:165], v[168:169], v[72:73], v[164:165] op_sel:[1,1,0] op_sel_hi:[0,1,1] neg_lo:[0,1,0]
	v_pk_fma_f32 v[170:171], v[172:173], v[68:69], v[170:171] op_sel:[1,1,0] op_sel_hi:[0,1,1] neg_lo:[0,1,0]
	v_pk_fma_f32 v[54:55], v[78:79], v[168:169], v[54:55] op_sel_hi:[1,0,1]
	v_pk_fma_f32 v[38:39], v[74:75], v[172:173], v[38:39] op_sel_hi:[1,0,1]
	v_pk_fma_f32 v[56:57], v[70:71], v[168:169], v[56:57] op_sel_hi:[1,0,1]
	v_pk_fma_f32 v[40:41], v[66:67], v[172:173], v[40:41] op_sel_hi:[1,0,1]
	v_pk_fma_f32 v[6:7], v[80:81], v[168:169], v[6:7] op_sel_hi:[1,0,1]
	v_pk_fma_f32 v[22:23], v[76:77], v[172:173], v[22:23] op_sel_hi:[1,0,1]
	v_pk_fma_f32 v[8:9], v[72:73], v[168:169], v[8:9] op_sel_hi:[1,0,1]
	v_pk_fma_f32 v[24:25], v[68:69], v[172:173], v[24:25] op_sel_hi:[1,0,1]
	v_pk_fma_f32 v[54:55], v[80:81], v[168:169], v[54:55] op_sel:[0,1,0] op_sel_hi:[1,1,1] neg_lo:[0,1,0] neg_hi:[0,1,0]
	v_pk_fma_f32 v[38:39], v[76:77], v[172:173], v[38:39] op_sel:[0,1,0] op_sel_hi:[1,1,1] neg_lo:[0,1,0] neg_hi:[0,1,0]
	v_pk_fma_f32 v[56:57], v[72:73], v[168:169], v[56:57] op_sel:[0,1,0] op_sel_hi:[1,1,1] neg_lo:[0,1,0] neg_hi:[0,1,0]
	v_pk_fma_f32 v[40:41], v[68:69], v[172:173], v[40:41] op_sel:[0,1,0] op_sel_hi:[1,1,1] neg_lo:[0,1,0] neg_hi:[0,1,0]
	v_pk_fma_f32 v[6:7], v[78:79], v[168:169], v[6:7] op_sel:[0,1,0] op_sel_hi:[1,1,1]
	v_pk_fma_f32 v[22:23], v[74:75], v[172:173], v[22:23] op_sel:[0,1,0] op_sel_hi:[1,1,1]
	v_pk_fma_f32 v[8:9], v[70:71], v[168:169], v[8:9] op_sel:[0,1,0] op_sel_hi:[1,1,1]
	v_pk_fma_f32 v[24:25], v[66:67], v[172:173], v[24:25] op_sel:[0,1,0] op_sel_hi:[1,1,1]
	v_pk_mul_f32 v[168:169], v[164:165], v[70:71] op_sel:[0,1] op_sel_hi:[1,1]
	v_pk_mul_f32 v[172:173], v[170:171], v[66:67] op_sel:[0,1] op_sel_hi:[1,1]
	v_pk_fma_f32 v[168:169], v[164:165], v[72:73], v[168:169] op_sel:[1,1,0] op_sel_hi:[0,1,1] neg_lo:[0,1,0]
	v_pk_fma_f32 v[172:173], v[170:171], v[68:69], v[172:173] op_sel:[1,1,0] op_sel_hi:[0,1,1] neg_lo:[0,1,0]
	v_pk_fma_f32 v[58:59], v[78:79], v[164:165], v[58:59] op_sel_hi:[1,0,1]
	v_pk_fma_f32 v[42:43], v[74:75], v[170:171], v[42:43] op_sel_hi:[1,0,1]
	v_pk_fma_f32 v[60:61], v[70:71], v[164:165], v[60:61] op_sel_hi:[1,0,1]
	v_pk_fma_f32 v[44:45], v[66:67], v[170:171], v[44:45] op_sel_hi:[1,0,1]
	v_pk_fma_f32 v[10:11], v[80:81], v[164:165], v[10:11] op_sel_hi:[1,0,1]
	v_pk_fma_f32 v[26:27], v[76:77], v[170:171], v[26:27] op_sel_hi:[1,0,1]
	v_pk_fma_f32 v[12:13], v[72:73], v[164:165], v[12:13] op_sel_hi:[1,0,1]
	v_pk_fma_f32 v[28:29], v[68:69], v[170:171], v[28:29] op_sel_hi:[1,0,1]
	v_pk_fma_f32 v[58:59], v[80:81], v[164:165], v[58:59] op_sel:[0,1,0] op_sel_hi:[1,1,1] neg_lo:[0,1,0] neg_hi:[0,1,0]
	v_pk_fma_f32 v[42:43], v[76:77], v[170:171], v[42:43] op_sel:[0,1,0] op_sel_hi:[1,1,1] neg_lo:[0,1,0] neg_hi:[0,1,0]
	v_pk_fma_f32 v[60:61], v[72:73], v[164:165], v[60:61] op_sel:[0,1,0] op_sel_hi:[1,1,1] neg_lo:[0,1,0] neg_hi:[0,1,0]
	v_pk_fma_f32 v[44:45], v[68:69], v[170:171], v[44:45] op_sel:[0,1,0] op_sel_hi:[1,1,1] neg_lo:[0,1,0] neg_hi:[0,1,0]
	v_pk_fma_f32 v[10:11], v[78:79], v[164:165], v[10:11] op_sel:[0,1,0] op_sel_hi:[1,1,1]
	v_pk_fma_f32 v[26:27], v[74:75], v[170:171], v[26:27] op_sel:[0,1,0] op_sel_hi:[1,1,1]
	v_pk_fma_f32 v[12:13], v[70:71], v[164:165], v[12:13] op_sel:[0,1,0] op_sel_hi:[1,1,1]
	v_pk_fma_f32 v[28:29], v[66:67], v[170:171], v[28:29] op_sel:[0,1,0] op_sel_hi:[1,1,1]
	v_pk_fma_f32 v[62:63], v[78:79], v[168:169], v[62:63] op_sel_hi:[1,0,1]
	v_pk_fma_f32 v[46:47], v[74:75], v[172:173], v[46:47] op_sel_hi:[1,0,1]
	v_pk_fma_f32 v[64:65], v[70:71], v[168:169], v[64:65] op_sel_hi:[1,0,1]
	v_pk_fma_f32 v[48:49], v[66:67], v[172:173], v[48:49] op_sel_hi:[1,0,1]
	v_pk_fma_f32 v[14:15], v[80:81], v[168:169], v[14:15] op_sel_hi:[1,0,1]
	v_pk_fma_f32 v[30:31], v[76:77], v[172:173], v[30:31] op_sel_hi:[1,0,1]
	v_pk_fma_f32 v[16:17], v[72:73], v[168:169], v[16:17] op_sel_hi:[1,0,1]
	v_pk_fma_f32 v[32:33], v[68:69], v[172:173], v[32:33] op_sel_hi:[1,0,1]
	v_pk_fma_f32 v[62:63], v[80:81], v[168:169], v[62:63] op_sel:[0,1,0] op_sel_hi:[1,1,1] neg_lo:[0,1,0] neg_hi:[0,1,0]
	v_pk_fma_f32 v[46:47], v[76:77], v[172:173], v[46:47] op_sel:[0,1,0] op_sel_hi:[1,1,1] neg_lo:[0,1,0] neg_hi:[0,1,0]
	v_pk_fma_f32 v[64:65], v[72:73], v[168:169], v[64:65] op_sel:[0,1,0] op_sel_hi:[1,1,1] neg_lo:[0,1,0] neg_hi:[0,1,0]
	v_pk_fma_f32 v[48:49], v[68:69], v[172:173], v[48:49] op_sel:[0,1,0] op_sel_hi:[1,1,1] neg_lo:[0,1,0] neg_hi:[0,1,0]
	v_pk_fma_f32 v[14:15], v[78:79], v[168:169], v[14:15] op_sel:[0,1,0] op_sel_hi:[1,1,1]
	v_pk_fma_f32 v[30:31], v[74:75], v[172:173], v[30:31] op_sel:[0,1,0] op_sel_hi:[1,1,1]
	v_pk_fma_f32 v[16:17], v[70:71], v[168:169], v[16:17] op_sel:[0,1,0] op_sel_hi:[1,1,1]
	v_pk_fma_f32 v[32:33], v[66:67], v[172:173], v[32:33] op_sel:[0,1,0] op_sel_hi:[1,1,1]
	v_mov_b32_e32 v156, v65
	v_mov_b32_e32 v157, v17
	v_mov_b32_e32 v166, v65
	v_mov_b32_e32 v167, v17
	s_nop 1
	v_permlane32_swap_b32_e32 v156, v166
	v_permlane32_swap_b32_e32 v157, v167
	v_mov_b32_e32 v156, v49
	v_mov_b32_e32 v157, v33
	v_mov_b32_e32 v150, v49
	v_mov_b32_e32 v151, v33
	s_nop 1
	v_permlane32_swap_b32_e32 v156, v150
	v_permlane32_swap_b32_e32 v157, v151
	v_cvt_pk_bf16_f32 v1, v50, v2
	ds_write_b32 v174, v1
	v_cvt_pk_bf16_f32 v146, v34, v18
	ds_write_b32 v174, v146 offset:128
	v_cvt_pk_bf16_f32 v178, v51, v3
	ds_write_b32 v174, v178 offset:272
	v_cvt_pk_bf16_f32 v1, v35, v19
	ds_write_b32 v174, v1 offset:400
	v_cvt_pk_bf16_f32 v146, v52, v4
	ds_write_b32 v174, v146 offset:544
	v_cvt_pk_bf16_f32 v178, v36, v20
	ds_write_b32 v174, v178 offset:672
	v_cvt_pk_bf16_f32 v1, v53, v5
	ds_write_b32 v174, v1 offset:816
	v_cvt_pk_bf16_f32 v146, v37, v21
	ds_write_b32 v174, v146 offset:944
	v_cvt_pk_bf16_f32 v178, v54, v6
	ds_write_b32 v174, v178 offset:1088
	v_cvt_pk_bf16_f32 v1, v38, v22
	ds_write_b32 v174, v1 offset:1216
	v_cvt_pk_bf16_f32 v146, v55, v7
	ds_write_b32 v174, v146 offset:1360
	v_cvt_pk_bf16_f32 v178, v39, v23
	ds_write_b32 v174, v178 offset:1488
	v_cvt_pk_bf16_f32 v1, v56, v8
	ds_write_b32 v174, v1 offset:1632
	v_cvt_pk_bf16_f32 v146, v40, v24
	ds_write_b32 v174, v146 offset:1760
	v_cvt_pk_bf16_f32 v178, v57, v9
	ds_write_b32 v174, v178 offset:1904
	v_cvt_pk_bf16_f32 v1, v41, v25
	ds_write_b32 v174, v1 offset:2032
	v_cvt_pk_bf16_f32 v146, v58, v10
	ds_write_b32 v174, v146 offset:2176
	v_cvt_pk_bf16_f32 v178, v42, v26
	ds_write_b32 v174, v178 offset:2304
	v_cvt_pk_bf16_f32 v1, v59, v11
	ds_write_b32 v174, v1 offset:2448
	v_cvt_pk_bf16_f32 v146, v43, v27
	ds_write_b32 v174, v146 offset:2576
	v_cvt_pk_bf16_f32 v178, v60, v12
	ds_write_b32 v174, v178 offset:2720
	v_cvt_pk_bf16_f32 v1, v44, v28
	ds_write_b32 v174, v1 offset:2848
	v_cvt_pk_bf16_f32 v146, v61, v13
	ds_write_b32 v174, v146 offset:2992
	v_cvt_pk_bf16_f32 v178, v45, v29
	ds_write_b32 v174, v178 offset:3120
	v_cvt_pk_bf16_f32 v1, v62, v14
	ds_write_b32 v174, v1 offset:3264
	v_cvt_pk_bf16_f32 v146, v46, v30
	ds_write_b32 v174, v146 offset:3392
	v_cvt_pk_bf16_f32 v178, v63, v15
	ds_write_b32 v174, v178 offset:3536
	v_cvt_pk_bf16_f32 v1, v47, v31
	ds_write_b32 v174, v1 offset:3664
	v_cvt_pk_bf16_f32 v146, v64, v16
	ds_write_b32 v174, v146 offset:3808
	v_cvt_pk_bf16_f32 v178, v48, v32
	ds_write_b32 v174, v178 offset:3936
	v_cvt_pk_bf16_f32 v1, v65, v17
	ds_write_b32 v174, v1 offset:4080
	v_cvt_pk_bf16_f32 v146, v49, v33
	ds_write_b32 v174, v146 offset:4208
	s_waitcnt lgkmcnt(0)
	ds_read_b128 v[2:5], v175
	ds_read_b128 v[6:9], v175 offset:64
	ds_read_b128 v[10:13], v175 offset:128
	ds_read_b128 v[14:17], v175 offset:192
	ds_read_b128 v[18:21], v175 offset:4352
	ds_read_b128 v[22:25], v175 offset:4416
	ds_read_b128 v[26:29], v175 offset:4480
	ds_read_b128 v[30:33], v175 offset:4544
	s_waitcnt vmcnt(0)
	s_waitcnt lgkmcnt(7)
	v_mfma_f32_16x16x32_bf16 v[34:37], v[94:97], v[2:5], 0
	s_waitcnt lgkmcnt(6)
	v_mfma_f32_16x16x32_bf16 v[34:37], v[90:93], v[6:9], v[34:37]
	s_waitcnt lgkmcnt(5)
	v_mfma_f32_16x16x32_bf16 v[34:37], v[86:89], v[10:13], v[34:37]
	s_waitcnt lgkmcnt(4)
	v_mfma_f32_16x16x32_bf16 v[34:37], v[82:85], v[14:17], v[34:37]
	s_waitcnt lgkmcnt(3)
	v_mfma_f32_16x16x32_bf16 v[38:41], v[94:97], v[18:21], 0
	s_waitcnt lgkmcnt(2)
	v_mfma_f32_16x16x32_bf16 v[38:41], v[90:93], v[22:25], v[38:41]
	s_waitcnt lgkmcnt(1)
	v_mfma_f32_16x16x32_bf16 v[38:41], v[86:89], v[26:29], v[38:41]
	s_waitcnt lgkmcnt(0)
	v_mfma_f32_16x16x32_bf16 v[38:41], v[82:85], v[30:33], v[38:41]
	s_add_u32 s6, s6, 0x8000
	s_addc_u32 s7, s7, 0
	v_lshlrev_b32_e32 v42, 16, v160
	v_and_b32_e32 v43, 0xffff0000, v160
	v_lshlrev_b32_e32 v44, 16, v161
	v_and_b32_e32 v45, 0xffff0000, v161
	v_lshlrev_b32_e32 v46, 16, v162
	v_and_b32_e32 v47, 0xffff0000, v162
	v_lshlrev_b32_e32 v48, 16, v163
	v_and_b32_e32 v49, 0xffff0000, v163
	s_nop 1
	v_mov_b32_e32 v156, 0x3d372713
	v_mov_b32_e32 v158, 0xbfcc422a
	v_mov_b32_e32 v164, 0x3fb8aa3b
	v_mov_b32_e32 v168, 1.0
	v_pk_fma_f32 v[50:51], v[98:99], v[42:43], v[34:35]
	v_pk_fma_f32 v[52:53], v[100:101], v[44:45], v[36:37]
	v_pk_fma_f32 v[54:55], v[98:99], v[46:47], v[38:39]
	v_pk_fma_f32 v[56:57], v[100:101], v[48:49], v[40:41]
	v_pk_mul_f32 v[2:3], v[50:51], v[156:157] op_sel_hi:[1,0]
	v_pk_mul_f32 v[4:5], v[52:53], v[156:157] op_sel_hi:[1,0]
	v_pk_mul_f32 v[6:7], v[54:55], v[156:157] op_sel_hi:[1,0]
	v_pk_mul_f32 v[8:9], v[56:57], v[156:157] op_sel_hi:[1,0]
	v_pk_mul_f32 v[2:3], v[50:51], v[2:3]
	v_pk_mul_f32 v[4:5], v[52:53], v[4:5]
	v_pk_mul_f32 v[6:7], v[54:55], v[6:7]
	v_pk_mul_f32 v[8:9], v[56:57], v[8:9]
	v_pk_fma_f32 v[2:3], v[50:51], v[2:3], v[50:51]
	v_pk_fma_f32 v[4:5], v[52:53], v[4:5], v[52:53]
	v_pk_fma_f32 v[6:7], v[54:55], v[6:7], v[54:55]
	v_pk_fma_f32 v[8:9], v[56:57], v[8:9], v[56:57]
	v_pk_mul_f32 v[2:3], v[2:3], v[158:159] op_sel_hi:[1,0]
	v_pk_mul_f32 v[4:5], v[4:5], v[158:159] op_sel_hi:[1,0]
	v_pk_mul_f32 v[6:7], v[6:7], v[158:159] op_sel_hi:[1,0]
	v_pk_mul_f32 v[8:9], v[8:9], v[158:159] op_sel_hi:[1,0]
	v_pk_mul_f32 v[2:3], v[2:3], v[164:165] op_sel_hi:[1,0]
	v_pk_mul_f32 v[4:5], v[4:5], v[164:165] op_sel_hi:[1,0]
	v_pk_mul_f32 v[6:7], v[6:7], v[164:165] op_sel_hi:[1,0]
	v_pk_mul_f32 v[8:9], v[8:9], v[164:165] op_sel_hi:[1,0]
	v_exp_f32_e32 v2, v2
	v_exp_f32_e32 v3, v3
	v_exp_f32_e32 v4, v4
	v_exp_f32_e32 v5, v5
	v_exp_f32_e32 v6, v6
	v_exp_f32_e32 v7, v7
	v_exp_f32_e32 v8, v8
	v_exp_f32_e32 v9, v9
	v_pk_add_f32 v[2:3], v[2:3], v[168:169] op_sel_hi:[1,0]
	v_pk_add_f32 v[4:5], v[4:5], v[168:169] op_sel_hi:[1,0]
	v_pk_add_f32 v[6:7], v[6:7], v[168:169] op_sel_hi:[1,0]
	v_pk_add_f32 v[8:9], v[8:9], v[168:169] op_sel_hi:[1,0]
	v_rcp_f32_e32 v2, v2
	v_rcp_f32_e32 v3, v3
	v_rcp_f32_e32 v4, v4
	v_rcp_f32_e32 v5, v5
	v_rcp_f32_e32 v6, v6
	v_rcp_f32_e32 v7, v7
	v_rcp_f32_e32 v8, v8
	v_rcp_f32_e32 v9, v9
	v_pk_mul_f32 v[50:51], v[50:51], v[2:3]
	v_pk_mul_f32 v[52:53], v[52:53], v[4:5]
	v_pk_mul_f32 v[54:55], v[54:55], v[6:7]
	v_pk_mul_f32 v[56:57], v[56:57], v[8:9]
	v_cvt_pk_bf16_f32 v10, v50, v51
	v_cvt_pk_bf16_f32 v11, v52, v53
	v_cvt_pk_bf16_f32 v12, v54, v55
	v_cvt_pk_bf16_f32 v13, v56, v57
	global_store_dwordx2 v176, v[10:11], s[10:11]
	global_store_dwordx2 v177, v[12:13], s[10:11]
	s_add_u32 s10, s10, 0x8000
	s_addc_u32 s11, s11, 0
	s_nop 0
	v_mfma_f32_32x32x16_bf16 v[50:65], v[126:129], v[114:117], 0
	v_mfma_f32_32x32x16_bf16 v[2:17], v[126:129], v[110:113], 0
	v_mfma_f32_32x32x16_bf16 v[34:49], v[126:129], v[106:109], 0
	v_mfma_f32_32x32x16_bf16 v[18:33], v[126:129], v[102:105], 0
	global_load_dwordx2 v[160:161], v176, s[6:7]
	global_load_dwordx2 v[162:163], v177, s[6:7]
	s_nop 9
	v_fmac_f32_e32 v51, v78, v50
	v_fmac_f32_e32 v35, v74, v34
	v_fmac_f32_e32 v3, v80, v50
	v_fmac_f32_e32 v19, v76, v34
	v_fma_f32 v51, -v80, v2, v51
	v_fma_f32 v35, -v76, v18, v35
	v_fmac_f32_e32 v3, v78, v2
	v_fmac_f32_e32 v19, v74, v18
	v_fmac_f32_e32 v52, v78, v51
	v_fmac_f32_e32 v36, v74, v35
	v_fmac_f32_e32 v4, v80, v51
	v_fmac_f32_e32 v20, v76, v35
	v_fma_f32 v52, -v80, v3, v52
	v_fma_f32 v36, -v76, v19, v36
	v_fmac_f32_e32 v4, v78, v3
	v_fmac_f32_e32 v20, v74, v19
	v_fmac_f32_e32 v53, v78, v52
	v_fmac_f32_e32 v37, v74, v36
	v_fmac_f32_e32 v5, v80, v52
	v_fmac_f32_e32 v21, v76, v36
	v_fma_f32 v53, -v80, v4, v53
	v_fma_f32 v37, -v76, v20, v37
	v_fmac_f32_e32 v5, v78, v4
	v_fmac_f32_e32 v21, v74, v20
	v_fmac_f32_e32 v54, v78, v53
	v_fmac_f32_e32 v38, v74, v37
	v_fmac_f32_e32 v6, v80, v53
	v_fmac_f32_e32 v22, v76, v37
	v_fma_f32 v54, -v80, v5, v54
	v_fma_f32 v38, -v76, v21, v38
	v_fmac_f32_e32 v6, v78, v5
	v_fmac_f32_e32 v22, v74, v21
	v_fmac_f32_e32 v55, v78, v54
	v_fmac_f32_e32 v39, v74, v38
	v_fmac_f32_e32 v7, v80, v54
	v_fmac_f32_e32 v23, v76, v38
	v_fma_f32 v55, -v80, v6, v55
	v_fma_f32 v39, -v76, v22, v39
	v_fmac_f32_e32 v7, v78, v6
	v_fmac_f32_e32 v23, v74, v22
	v_fmac_f32_e32 v56, v78, v55
	v_fmac_f32_e32 v40, v74, v39
	v_fmac_f32_e32 v8, v80, v55
	v_fmac_f32_e32 v24, v76, v39
	v_fma_f32 v56, -v80, v7, v56
	v_fma_f32 v40, -v76, v23, v40
	v_fmac_f32_e32 v8, v78, v7
	v_fmac_f32_e32 v24, v74, v23
	v_fmac_f32_e32 v57, v78, v56
	v_fmac_f32_e32 v41, v74, v40
	v_fmac_f32_e32 v9, v80, v56
	v_fmac_f32_e32 v25, v76, v40
	v_fma_f32 v57, -v80, v8, v57
	v_fma_f32 v41, -v76, v24, v41
	v_fmac_f32_e32 v9, v78, v8
	v_fmac_f32_e32 v25, v74, v24
	v_fmac_f32_e32 v58, v78, v57
	v_fmac_f32_e32 v42, v74, v41
	v_fmac_f32_e32 v10, v80, v57
	v_fmac_f32_e32 v26, v76, v41
	v_fma_f32 v58, -v80, v9, v58
	v_fma_f32 v42, -v76, v25, v42
	v_fmac_f32_e32 v10, v78, v9
	v_fmac_f32_e32 v26, v74, v25
	v_fmac_f32_e32 v59, v78, v58
	v_fmac_f32_e32 v43, v74, v42
	v_fmac_f32_e32 v11, v80, v58
	v_fmac_f32_e32 v27, v76, v42
	v_fma_f32 v59, -v80, v10, v59
	v_fma_f32 v43, -v76, v26, v43
	v_fmac_f32_e32 v11, v78, v10
	v_fmac_f32_e32 v27, v74, v26
	v_fmac_f32_e32 v60, v78, v59
	v_fmac_f32_e32 v44, v74, v43
	v_fmac_f32_e32 v12, v80, v59
	v_fmac_f32_e32 v28, v76, v43
	v_fma_f32 v60, -v80, v11, v60
	v_fma_f32 v44, -v76, v27, v44
	v_fmac_f32_e32 v12, v78, v11
	v_fmac_f32_e32 v28, v74, v27
	v_fmac_f32_e32 v61, v78, v60
	v_fmac_f32_e32 v45, v74, v44
	v_fmac_f32_e32 v13, v80, v60
	v_fmac_f32_e32 v29, v76, v44
	v_fma_f32 v61, -v80, v12, v61
	v_fma_f32 v45, -v76, v28, v45
	v_fmac_f32_e32 v13, v78, v12
	v_fmac_f32_e32 v29, v74, v28
	v_fmac_f32_e32 v62, v78, v61
	v_fmac_f32_e32 v46, v74, v45
	v_fmac_f32_e32 v14, v80, v61
	v_fmac_f32_e32 v30, v76, v45
	v_fma_f32 v62, -v80, v13, v62
	v_fma_f32 v46, -v76, v29, v46
	v_fmac_f32_e32 v14, v78, v13
	v_fmac_f32_e32 v30, v74, v29
	v_fmac_f32_e32 v63, v78, v62
	v_fmac_f32_e32 v47, v74, v46
	v_fmac_f32_e32 v15, v80, v62
	v_fmac_f32_e32 v31, v76, v46
	v_fma_f32 v63, -v80, v14, v63
	v_fma_f32 v47, -v76, v30, v47
	v_fmac_f32_e32 v15, v78, v14
	v_fmac_f32_e32 v31, v74, v30
	v_fmac_f32_e32 v64, v78, v63
	v_fmac_f32_e32 v48, v74, v47
	v_fmac_f32_e32 v16, v80, v63
	v_fmac_f32_e32 v32, v76, v47
	v_fma_f32 v64, -v80, v15, v64
	v_fma_f32 v48, -v76, v31, v48
	v_fmac_f32_e32 v16, v78, v15
	v_fmac_f32_e32 v32, v74, v31
	v_fmac_f32_e32 v65, v78, v64
	v_fmac_f32_e32 v49, v74, v48
	v_fmac_f32_e32 v17, v80, v64
	v_fmac_f32_e32 v33, v76, v48
	v_fma_f32 v65, -v80, v16, v65
	v_fma_f32 v49, -v76, v32, v49
	v_fmac_f32_e32 v17, v78, v16
	v_fmac_f32_e32 v33, v74, v32
	v_mov_b32_e32 v156, v65
	v_mov_b32_e32 v157, v17
	v_mov_b32_e32 v158, v65
	v_mov_b32_e32 v159, v17
	s_nop 1
	v_permlane32_swap_b32_e32 v156, v158
	v_permlane32_swap_b32_e32 v157, v159
	v_pk_fma_f32 v[164:165], v[166:167], v[152:153], v[156:157] op_sel_hi:[1,0,1]
	v_pk_fma_f32 v[164:165], v[166:167], v[152:153], v[164:165] op_sel:[1,1,0] op_sel_hi:[0,1,1] neg_lo:[0,1,0]
	v_cndmask_b32_e32 v164, v166, v164, vcc
	v_cndmask_b32_e32 v165, v167, v165, vcc
	v_mov_b32_e32 v156, v49
	v_mov_b32_e32 v157, v33
	v_mov_b32_e32 v158, v49
	v_mov_b32_e32 v159, v33
	s_nop 1
	v_permlane32_swap_b32_e32 v156, v158
	v_permlane32_swap_b32_e32 v157, v159
	v_pk_fma_f32 v[170:171], v[150:151], v[154:155], v[156:157] op_sel_hi:[1,0,1]
	v_pk_fma_f32 v[170:171], v[150:151], v[154:155], v[170:171] op_sel:[1,1,0] op_sel_hi:[0,1,1] neg_lo:[0,1,0]
	v_cndmask_b32_e32 v170, v150, v170, vcc
	v_cndmask_b32_e32 v171, v151, v171, vcc
	v_pk_mul_f32 v[168:169], v[164:165], v[70:71] op_sel:[0,1] op_sel_hi:[1,1]
	v_pk_mul_f32 v[172:173], v[170:171], v[66:67] op_sel:[0,1] op_sel_hi:[1,1]
	v_pk_fma_f32 v[168:169], v[164:165], v[72:73], v[168:169] op_sel:[1,1,0] op_sel_hi:[0,1,1] neg_lo:[0,1,0]
	v_pk_fma_f32 v[172:173], v[170:171], v[68:69], v[172:173] op_sel:[1,1,0] op_sel_hi:[0,1,1] neg_lo:[0,1,0]
	v_pk_fma_f32 v[50:51], v[78:79], v[164:165], v[50:51] op_sel_hi:[1,0,1]
	v_pk_fma_f32 v[34:35], v[74:75], v[170:171], v[34:35] op_sel_hi:[1,0,1]
	v_pk_fma_f32 v[52:53], v[70:71], v[164:165], v[52:53] op_sel_hi:[1,0,1]
	v_pk_fma_f32 v[36:37], v[66:67], v[170:171], v[36:37] op_sel_hi:[1,0,1]
	v_pk_fma_f32 v[2:3], v[80:81], v[164:165], v[2:3] op_sel_hi:[1,0,1]
	v_pk_fma_f32 v[18:19], v[76:77], v[170:171], v[18:19] op_sel_hi:[1,0,1]
	v_pk_fma_f32 v[4:5], v[72:73], v[164:165], v[4:5] op_sel_hi:[1,0,1]
	v_pk_fma_f32 v[20:21], v[68:69], v[170:171], v[20:21] op_sel_hi:[1,0,1]
	v_pk_fma_f32 v[50:51], v[80:81], v[164:165], v[50:51] op_sel:[0,1,0] op_sel_hi:[1,1,1] neg_lo:[0,1,0] neg_hi:[0,1,0]
	v_pk_fma_f32 v[34:35], v[76:77], v[170:171], v[34:35] op_sel:[0,1,0] op_sel_hi:[1,1,1] neg_lo:[0,1,0] neg_hi:[0,1,0]
	v_pk_fma_f32 v[52:53], v[72:73], v[164:165], v[52:53] op_sel:[0,1,0] op_sel_hi:[1,1,1] neg_lo:[0,1,0] neg_hi:[0,1,0]
	v_pk_fma_f32 v[36:37], v[68:69], v[170:171], v[36:37] op_sel:[0,1,0] op_sel_hi:[1,1,1] neg_lo:[0,1,0] neg_hi:[0,1,0]
	v_pk_fma_f32 v[2:3], v[78:79], v[164:165], v[2:3] op_sel:[0,1,0] op_sel_hi:[1,1,1]
	v_pk_fma_f32 v[18:19], v[74:75], v[170:171], v[18:19] op_sel:[0,1,0] op_sel_hi:[1,1,1]
	v_pk_fma_f32 v[4:5], v[70:71], v[164:165], v[4:5] op_sel:[0,1,0] op_sel_hi:[1,1,1]
	v_pk_fma_f32 v[20:21], v[66:67], v[170:171], v[20:21] op_sel:[0,1,0] op_sel_hi:[1,1,1]
	v_pk_mul_f32 v[164:165], v[168:169], v[70:71] op_sel:[0,1] op_sel_hi:[1,1]
	v_pk_mul_f32 v[170:171], v[172:173], v[66:67] op_sel:[0,1] op_sel_hi:[1,1]
	v_pk_fma_f32 v[164:165], v[168:169], v[72:73], v[164:165] op_sel:[1,1,0] op_sel_hi:[0,1,1] neg_lo:[0,1,0]
	v_pk_fma_f32 v[170:171], v[172:173], v[68:69], v[170:171] op_sel:[1,1,0] op_sel_hi:[0,1,1] neg_lo:[0,1,0]
	v_pk_fma_f32 v[54:55], v[78:79], v[168:169], v[54:55] op_sel_hi:[1,0,1]
	v_pk_fma_f32 v[38:39], v[74:75], v[172:173], v[38:39] op_sel_hi:[1,0,1]
	v_pk_fma_f32 v[56:57], v[70:71], v[168:169], v[56:57] op_sel_hi:[1,0,1]
	v_pk_fma_f32 v[40:41], v[66:67], v[172:173], v[40:41] op_sel_hi:[1,0,1]
	v_pk_fma_f32 v[6:7], v[80:81], v[168:169], v[6:7] op_sel_hi:[1,0,1]
	v_pk_fma_f32 v[22:23], v[76:77], v[172:173], v[22:23] op_sel_hi:[1,0,1]
	v_pk_fma_f32 v[8:9], v[72:73], v[168:169], v[8:9] op_sel_hi:[1,0,1]
	v_pk_fma_f32 v[24:25], v[68:69], v[172:173], v[24:25] op_sel_hi:[1,0,1]
	v_pk_fma_f32 v[54:55], v[80:81], v[168:169], v[54:55] op_sel:[0,1,0] op_sel_hi:[1,1,1] neg_lo:[0,1,0] neg_hi:[0,1,0]
	v_pk_fma_f32 v[38:39], v[76:77], v[172:173], v[38:39] op_sel:[0,1,0] op_sel_hi:[1,1,1] neg_lo:[0,1,0] neg_hi:[0,1,0]
	v_pk_fma_f32 v[56:57], v[72:73], v[168:169], v[56:57] op_sel:[0,1,0] op_sel_hi:[1,1,1] neg_lo:[0,1,0] neg_hi:[0,1,0]
	v_pk_fma_f32 v[40:41], v[68:69], v[172:173], v[40:41] op_sel:[0,1,0] op_sel_hi:[1,1,1] neg_lo:[0,1,0] neg_hi:[0,1,0]
	v_pk_fma_f32 v[6:7], v[78:79], v[168:169], v[6:7] op_sel:[0,1,0] op_sel_hi:[1,1,1]
	v_pk_fma_f32 v[22:23], v[74:75], v[172:173], v[22:23] op_sel:[0,1,0] op_sel_hi:[1,1,1]
	v_pk_fma_f32 v[8:9], v[70:71], v[168:169], v[8:9] op_sel:[0,1,0] op_sel_hi:[1,1,1]
	v_pk_fma_f32 v[24:25], v[66:67], v[172:173], v[24:25] op_sel:[0,1,0] op_sel_hi:[1,1,1]
	v_pk_mul_f32 v[168:169], v[164:165], v[70:71] op_sel:[0,1] op_sel_hi:[1,1]
	v_pk_mul_f32 v[172:173], v[170:171], v[66:67] op_sel:[0,1] op_sel_hi:[1,1]
	v_pk_fma_f32 v[168:169], v[164:165], v[72:73], v[168:169] op_sel:[1,1,0] op_sel_hi:[0,1,1] neg_lo:[0,1,0]
	v_pk_fma_f32 v[172:173], v[170:171], v[68:69], v[172:173] op_sel:[1,1,0] op_sel_hi:[0,1,1] neg_lo:[0,1,0]
	v_pk_fma_f32 v[58:59], v[78:79], v[164:165], v[58:59] op_sel_hi:[1,0,1]
	v_pk_fma_f32 v[42:43], v[74:75], v[170:171], v[42:43] op_sel_hi:[1,0,1]
	v_pk_fma_f32 v[60:61], v[70:71], v[164:165], v[60:61] op_sel_hi:[1,0,1]
	v_pk_fma_f32 v[44:45], v[66:67], v[170:171], v[44:45] op_sel_hi:[1,0,1]
	v_pk_fma_f32 v[10:11], v[80:81], v[164:165], v[10:11] op_sel_hi:[1,0,1]
	v_pk_fma_f32 v[26:27], v[76:77], v[170:171], v[26:27] op_sel_hi:[1,0,1]
	v_pk_fma_f32 v[12:13], v[72:73], v[164:165], v[12:13] op_sel_hi:[1,0,1]
	v_pk_fma_f32 v[28:29], v[68:69], v[170:171], v[28:29] op_sel_hi:[1,0,1]
	v_pk_fma_f32 v[58:59], v[80:81], v[164:165], v[58:59] op_sel:[0,1,0] op_sel_hi:[1,1,1] neg_lo:[0,1,0] neg_hi:[0,1,0]
	v_pk_fma_f32 v[42:43], v[76:77], v[170:171], v[42:43] op_sel:[0,1,0] op_sel_hi:[1,1,1] neg_lo:[0,1,0] neg_hi:[0,1,0]
	v_pk_fma_f32 v[60:61], v[72:73], v[164:165], v[60:61] op_sel:[0,1,0] op_sel_hi:[1,1,1] neg_lo:[0,1,0] neg_hi:[0,1,0]
	v_pk_fma_f32 v[44:45], v[68:69], v[170:171], v[44:45] op_sel:[0,1,0] op_sel_hi:[1,1,1] neg_lo:[0,1,0] neg_hi:[0,1,0]
	v_pk_fma_f32 v[10:11], v[78:79], v[164:165], v[10:11] op_sel:[0,1,0] op_sel_hi:[1,1,1]
	v_pk_fma_f32 v[26:27], v[74:75], v[170:171], v[26:27] op_sel:[0,1,0] op_sel_hi:[1,1,1]
	v_pk_fma_f32 v[12:13], v[70:71], v[164:165], v[12:13] op_sel:[0,1,0] op_sel_hi:[1,1,1]
	v_pk_fma_f32 v[28:29], v[66:67], v[170:171], v[28:29] op_sel:[0,1,0] op_sel_hi:[1,1,1]
	v_pk_fma_f32 v[62:63], v[78:79], v[168:169], v[62:63] op_sel_hi:[1,0,1]
	v_pk_fma_f32 v[46:47], v[74:75], v[172:173], v[46:47] op_sel_hi:[1,0,1]
	v_pk_fma_f32 v[64:65], v[70:71], v[168:169], v[64:65] op_sel_hi:[1,0,1]
	v_pk_fma_f32 v[48:49], v[66:67], v[172:173], v[48:49] op_sel_hi:[1,0,1]
	v_pk_fma_f32 v[14:15], v[80:81], v[168:169], v[14:15] op_sel_hi:[1,0,1]
	v_pk_fma_f32 v[30:31], v[76:77], v[172:173], v[30:31] op_sel_hi:[1,0,1]
	v_pk_fma_f32 v[16:17], v[72:73], v[168:169], v[16:17] op_sel_hi:[1,0,1]
	v_pk_fma_f32 v[32:33], v[68:69], v[172:173], v[32:33] op_sel_hi:[1,0,1]
	v_pk_fma_f32 v[62:63], v[80:81], v[168:169], v[62:63] op_sel:[0,1,0] op_sel_hi:[1,1,1] neg_lo:[0,1,0] neg_hi:[0,1,0]
	v_pk_fma_f32 v[46:47], v[76:77], v[172:173], v[46:47] op_sel:[0,1,0] op_sel_hi:[1,1,1] neg_lo:[0,1,0] neg_hi:[0,1,0]
	v_pk_fma_f32 v[64:65], v[72:73], v[168:169], v[64:65] op_sel:[0,1,0] op_sel_hi:[1,1,1] neg_lo:[0,1,0] neg_hi:[0,1,0]
	v_pk_fma_f32 v[48:49], v[68:69], v[172:173], v[48:49] op_sel:[0,1,0] op_sel_hi:[1,1,1] neg_lo:[0,1,0] neg_hi:[0,1,0]
	v_pk_fma_f32 v[14:15], v[78:79], v[168:169], v[14:15] op_sel:[0,1,0] op_sel_hi:[1,1,1]
	v_pk_fma_f32 v[30:31], v[74:75], v[172:173], v[30:31] op_sel:[0,1,0] op_sel_hi:[1,1,1]
	v_pk_fma_f32 v[16:17], v[70:71], v[168:169], v[16:17] op_sel:[0,1,0] op_sel_hi:[1,1,1]
	v_pk_fma_f32 v[32:33], v[66:67], v[172:173], v[32:33] op_sel:[0,1,0] op_sel_hi:[1,1,1]
	v_mov_b32_e32 v156, v65
	v_mov_b32_e32 v157, v17
	v_mov_b32_e32 v166, v65
	v_mov_b32_e32 v167, v17
	s_nop 1
	v_permlane32_swap_b32_e32 v156, v166
	v_permlane32_swap_b32_e32 v157, v167
	v_mov_b32_e32 v156, v49
	v_mov_b32_e32 v157, v33
	v_mov_b32_e32 v150, v49
	v_mov_b32_e32 v151, v33
	s_nop 1
	v_permlane32_swap_b32_e32 v156, v150
	v_permlane32_swap_b32_e32 v157, v151
	v_cvt_pk_bf16_f32 v1, v50, v2
	ds_write_b32 v174, v1
	v_cvt_pk_bf16_f32 v146, v34, v18
	ds_write_b32 v174, v146 offset:128
	v_cvt_pk_bf16_f32 v178, v51, v3
	ds_write_b32 v174, v178 offset:272
	v_cvt_pk_bf16_f32 v1, v35, v19
	ds_write_b32 v174, v1 offset:400
	v_cvt_pk_bf16_f32 v146, v52, v4
	ds_write_b32 v174, v146 offset:544
	v_cvt_pk_bf16_f32 v178, v36, v20
	ds_write_b32 v174, v178 offset:672
	v_cvt_pk_bf16_f32 v1, v53, v5
	ds_write_b32 v174, v1 offset:816
	v_cvt_pk_bf16_f32 v146, v37, v21
	ds_write_b32 v174, v146 offset:944
	v_cvt_pk_bf16_f32 v178, v54, v6
	ds_write_b32 v174, v178 offset:1088
	v_cvt_pk_bf16_f32 v1, v38, v22
	ds_write_b32 v174, v1 offset:1216
	v_cvt_pk_bf16_f32 v146, v55, v7
	ds_write_b32 v174, v146 offset:1360
	v_cvt_pk_bf16_f32 v178, v39, v23
	ds_write_b32 v174, v178 offset:1488
	v_cvt_pk_bf16_f32 v1, v56, v8
	ds_write_b32 v174, v1 offset:1632
	v_cvt_pk_bf16_f32 v146, v40, v24
	ds_write_b32 v174, v146 offset:1760
	v_cvt_pk_bf16_f32 v178, v57, v9
	ds_write_b32 v174, v178 offset:1904
	v_cvt_pk_bf16_f32 v1, v41, v25
	ds_write_b32 v174, v1 offset:2032
	v_cvt_pk_bf16_f32 v146, v58, v10
	ds_write_b32 v174, v146 offset:2176
	v_cvt_pk_bf16_f32 v178, v42, v26
	ds_write_b32 v174, v178 offset:2304
	v_cvt_pk_bf16_f32 v1, v59, v11
	ds_write_b32 v174, v1 offset:2448
	v_cvt_pk_bf16_f32 v146, v43, v27
	ds_write_b32 v174, v146 offset:2576
	v_cvt_pk_bf16_f32 v178, v60, v12
	ds_write_b32 v174, v178 offset:2720
	v_cvt_pk_bf16_f32 v1, v44, v28
	ds_write_b32 v174, v1 offset:2848
	v_cvt_pk_bf16_f32 v146, v61, v13
	ds_write_b32 v174, v146 offset:2992
	v_cvt_pk_bf16_f32 v178, v45, v29
	ds_write_b32 v174, v178 offset:3120
	v_cvt_pk_bf16_f32 v1, v62, v14
	ds_write_b32 v174, v1 offset:3264
	v_cvt_pk_bf16_f32 v146, v46, v30
	ds_write_b32 v174, v146 offset:3392
	v_cvt_pk_bf16_f32 v178, v63, v15
	ds_write_b32 v174, v178 offset:3536
	v_cvt_pk_bf16_f32 v1, v47, v31
	ds_write_b32 v174, v1 offset:3664
	v_cvt_pk_bf16_f32 v146, v64, v16
	ds_write_b32 v174, v146 offset:3808
	v_cvt_pk_bf16_f32 v178, v48, v32
	ds_write_b32 v174, v178 offset:3936
	v_cvt_pk_bf16_f32 v1, v65, v17
	ds_write_b32 v174, v1 offset:4080
	v_cvt_pk_bf16_f32 v146, v49, v33
	ds_write_b32 v174, v146 offset:4208
	s_waitcnt lgkmcnt(0)
	ds_read_b128 v[2:5], v175
	ds_read_b128 v[6:9], v175 offset:64
	ds_read_b128 v[10:13], v175 offset:128
	ds_read_b128 v[14:17], v175 offset:192
	ds_read_b128 v[18:21], v175 offset:4352
	ds_read_b128 v[22:25], v175 offset:4416
	ds_read_b128 v[26:29], v175 offset:4480
	ds_read_b128 v[30:33], v175 offset:4544
	s_waitcnt vmcnt(0)
	s_waitcnt lgkmcnt(7)
	v_mfma_f32_16x16x32_bf16 v[34:37], v[94:97], v[2:5], 0
	s_waitcnt lgkmcnt(6)
	v_mfma_f32_16x16x32_bf16 v[34:37], v[90:93], v[6:9], v[34:37]
	s_waitcnt lgkmcnt(5)
	v_mfma_f32_16x16x32_bf16 v[34:37], v[86:89], v[10:13], v[34:37]
	s_waitcnt lgkmcnt(4)
	v_mfma_f32_16x16x32_bf16 v[34:37], v[82:85], v[14:17], v[34:37]
	s_waitcnt lgkmcnt(3)
	v_mfma_f32_16x16x32_bf16 v[38:41], v[94:97], v[18:21], 0
	s_waitcnt lgkmcnt(2)
	v_mfma_f32_16x16x32_bf16 v[38:41], v[90:93], v[22:25], v[38:41]
	s_waitcnt lgkmcnt(1)
	v_mfma_f32_16x16x32_bf16 v[38:41], v[86:89], v[26:29], v[38:41]
	s_waitcnt lgkmcnt(0)
	v_mfma_f32_16x16x32_bf16 v[38:41], v[82:85], v[30:33], v[38:41]
	s_add_u32 s6, s6, 0x8000
	s_addc_u32 s7, s7, 0
	v_lshlrev_b32_e32 v42, 16, v160
	v_and_b32_e32 v43, 0xffff0000, v160
	v_lshlrev_b32_e32 v44, 16, v161
	v_and_b32_e32 v45, 0xffff0000, v161
	v_lshlrev_b32_e32 v46, 16, v162
	v_and_b32_e32 v47, 0xffff0000, v162
	v_lshlrev_b32_e32 v48, 16, v163
	v_and_b32_e32 v49, 0xffff0000, v163
	s_nop 1
	v_mov_b32_e32 v156, 0x3d372713
	v_mov_b32_e32 v158, 0xbfcc422a
	v_mov_b32_e32 v164, 0x3fb8aa3b
	v_mov_b32_e32 v168, 1.0
	v_pk_fma_f32 v[50:51], v[98:99], v[42:43], v[34:35]
	v_pk_fma_f32 v[52:53], v[100:101], v[44:45], v[36:37]
	v_pk_fma_f32 v[54:55], v[98:99], v[46:47], v[38:39]
	v_pk_fma_f32 v[56:57], v[100:101], v[48:49], v[40:41]
	v_pk_mul_f32 v[2:3], v[50:51], v[156:157] op_sel_hi:[1,0]
	v_pk_mul_f32 v[4:5], v[52:53], v[156:157] op_sel_hi:[1,0]
	v_pk_mul_f32 v[6:7], v[54:55], v[156:157] op_sel_hi:[1,0]
	v_pk_mul_f32 v[8:9], v[56:57], v[156:157] op_sel_hi:[1,0]
	v_pk_mul_f32 v[2:3], v[50:51], v[2:3]
	v_pk_mul_f32 v[4:5], v[52:53], v[4:5]
	v_pk_mul_f32 v[6:7], v[54:55], v[6:7]
	v_pk_mul_f32 v[8:9], v[56:57], v[8:9]
	v_pk_fma_f32 v[2:3], v[50:51], v[2:3], v[50:51]
	v_pk_fma_f32 v[4:5], v[52:53], v[4:5], v[52:53]
	v_pk_fma_f32 v[6:7], v[54:55], v[6:7], v[54:55]
	v_pk_fma_f32 v[8:9], v[56:57], v[8:9], v[56:57]
	v_pk_mul_f32 v[2:3], v[2:3], v[158:159] op_sel_hi:[1,0]
	v_pk_mul_f32 v[4:5], v[4:5], v[158:159] op_sel_hi:[1,0]
	v_pk_mul_f32 v[6:7], v[6:7], v[158:159] op_sel_hi:[1,0]
	v_pk_mul_f32 v[8:9], v[8:9], v[158:159] op_sel_hi:[1,0]
	v_pk_mul_f32 v[2:3], v[2:3], v[164:165] op_sel_hi:[1,0]
	v_pk_mul_f32 v[4:5], v[4:5], v[164:165] op_sel_hi:[1,0]
	v_pk_mul_f32 v[6:7], v[6:7], v[164:165] op_sel_hi:[1,0]
	v_pk_mul_f32 v[8:9], v[8:9], v[164:165] op_sel_hi:[1,0]
	v_exp_f32_e32 v2, v2
	v_exp_f32_e32 v3, v3
	v_exp_f32_e32 v4, v4
	v_exp_f32_e32 v5, v5
	v_exp_f32_e32 v6, v6
	v_exp_f32_e32 v7, v7
	v_exp_f32_e32 v8, v8
	v_exp_f32_e32 v9, v9
	v_pk_add_f32 v[2:3], v[2:3], v[168:169] op_sel_hi:[1,0]
	v_pk_add_f32 v[4:5], v[4:5], v[168:169] op_sel_hi:[1,0]
	v_pk_add_f32 v[6:7], v[6:7], v[168:169] op_sel_hi:[1,0]
	v_pk_add_f32 v[8:9], v[8:9], v[168:169] op_sel_hi:[1,0]
	v_rcp_f32_e32 v2, v2
	v_rcp_f32_e32 v3, v3
	v_rcp_f32_e32 v4, v4
	v_rcp_f32_e32 v5, v5
	v_rcp_f32_e32 v6, v6
	v_rcp_f32_e32 v7, v7
	v_rcp_f32_e32 v8, v8
	v_rcp_f32_e32 v9, v9
	v_pk_mul_f32 v[50:51], v[50:51], v[2:3]
	v_pk_mul_f32 v[52:53], v[52:53], v[4:5]
	v_pk_mul_f32 v[54:55], v[54:55], v[6:7]
	v_pk_mul_f32 v[56:57], v[56:57], v[8:9]
	v_cvt_pk_bf16_f32 v10, v50, v51
	v_cvt_pk_bf16_f32 v11, v52, v53
	v_cvt_pk_bf16_f32 v12, v54, v55
	v_cvt_pk_bf16_f32 v13, v56, v57
	global_store_dwordx2 v176, v[10:11], s[10:11]
	global_store_dwordx2 v177, v[12:13], s[10:11]
	s_add_u32 s10, s10, 0x8000
	s_addc_u32 s11, s11, 0
	s_nop 0
	v_mfma_f32_32x32x16_bf16 v[50:65], v[122:125], v[114:117], 0
	v_mfma_f32_32x32x16_bf16 v[2:17], v[122:125], v[110:113], 0
	v_mfma_f32_32x32x16_bf16 v[34:49], v[122:125], v[106:109], 0
	v_mfma_f32_32x32x16_bf16 v[18:33], v[122:125], v[102:105], 0
	global_load_dwordx2 v[160:161], v176, s[6:7]
	global_load_dwordx2 v[162:163], v177, s[6:7]
	s_nop 9
	v_fmac_f32_e32 v51, v78, v50
	v_fmac_f32_e32 v35, v74, v34
	v_fmac_f32_e32 v3, v80, v50
	v_fmac_f32_e32 v19, v76, v34
	v_fma_f32 v51, -v80, v2, v51
	v_fma_f32 v35, -v76, v18, v35
	v_fmac_f32_e32 v3, v78, v2
	v_fmac_f32_e32 v19, v74, v18
	v_fmac_f32_e32 v52, v78, v51
	v_fmac_f32_e32 v36, v74, v35
	v_fmac_f32_e32 v4, v80, v51
	v_fmac_f32_e32 v20, v76, v35
	v_fma_f32 v52, -v80, v3, v52
	v_fma_f32 v36, -v76, v19, v36
	v_fmac_f32_e32 v4, v78, v3
	v_fmac_f32_e32 v20, v74, v19
	v_fmac_f32_e32 v53, v78, v52
	v_fmac_f32_e32 v37, v74, v36
	v_fmac_f32_e32 v5, v80, v52
	v_fmac_f32_e32 v21, v76, v36
	v_fma_f32 v53, -v80, v4, v53
	v_fma_f32 v37, -v76, v20, v37
	v_fmac_f32_e32 v5, v78, v4
	v_fmac_f32_e32 v21, v74, v20
	v_fmac_f32_e32 v54, v78, v53
	v_fmac_f32_e32 v38, v74, v37
	v_fmac_f32_e32 v6, v80, v53
	v_fmac_f32_e32 v22, v76, v37
	v_fma_f32 v54, -v80, v5, v54
	v_fma_f32 v38, -v76, v21, v38
	v_fmac_f32_e32 v6, v78, v5
	v_fmac_f32_e32 v22, v74, v21
	v_fmac_f32_e32 v55, v78, v54
	v_fmac_f32_e32 v39, v74, v38
	v_fmac_f32_e32 v7, v80, v54
	v_fmac_f32_e32 v23, v76, v38
	v_fma_f32 v55, -v80, v6, v55
	v_fma_f32 v39, -v76, v22, v39
	v_fmac_f32_e32 v7, v78, v6
	v_fmac_f32_e32 v23, v74, v22
	v_fmac_f32_e32 v56, v78, v55
	v_fmac_f32_e32 v40, v74, v39
	v_fmac_f32_e32 v8, v80, v55
	v_fmac_f32_e32 v24, v76, v39
	v_fma_f32 v56, -v80, v7, v56
	v_fma_f32 v40, -v76, v23, v40
	v_fmac_f32_e32 v8, v78, v7
	v_fmac_f32_e32 v24, v74, v23
	v_fmac_f32_e32 v57, v78, v56
	v_fmac_f32_e32 v41, v74, v40
	v_fmac_f32_e32 v9, v80, v56
	v_fmac_f32_e32 v25, v76, v40
	v_fma_f32 v57, -v80, v8, v57
	v_fma_f32 v41, -v76, v24, v41
	v_fmac_f32_e32 v9, v78, v8
	v_fmac_f32_e32 v25, v74, v24
	v_fmac_f32_e32 v58, v78, v57
	v_fmac_f32_e32 v42, v74, v41
	v_fmac_f32_e32 v10, v80, v57
	v_fmac_f32_e32 v26, v76, v41
	v_fma_f32 v58, -v80, v9, v58
	v_fma_f32 v42, -v76, v25, v42
	v_fmac_f32_e32 v10, v78, v9
	v_fmac_f32_e32 v26, v74, v25
	v_fmac_f32_e32 v59, v78, v58
	v_fmac_f32_e32 v43, v74, v42
	v_fmac_f32_e32 v11, v80, v58
	v_fmac_f32_e32 v27, v76, v42
	v_fma_f32 v59, -v80, v10, v59
	v_fma_f32 v43, -v76, v26, v43
	v_fmac_f32_e32 v11, v78, v10
	v_fmac_f32_e32 v27, v74, v26
	v_fmac_f32_e32 v60, v78, v59
	v_fmac_f32_e32 v44, v74, v43
	v_fmac_f32_e32 v12, v80, v59
	v_fmac_f32_e32 v28, v76, v43
	v_fma_f32 v60, -v80, v11, v60
	v_fma_f32 v44, -v76, v27, v44
	v_fmac_f32_e32 v12, v78, v11
	v_fmac_f32_e32 v28, v74, v27
	v_fmac_f32_e32 v61, v78, v60
	v_fmac_f32_e32 v45, v74, v44
	v_fmac_f32_e32 v13, v80, v60
	v_fmac_f32_e32 v29, v76, v44
	v_fma_f32 v61, -v80, v12, v61
	v_fma_f32 v45, -v76, v28, v45
	v_fmac_f32_e32 v13, v78, v12
	v_fmac_f32_e32 v29, v74, v28
	v_fmac_f32_e32 v62, v78, v61
	v_fmac_f32_e32 v46, v74, v45
	v_fmac_f32_e32 v14, v80, v61
	v_fmac_f32_e32 v30, v76, v45
	v_fma_f32 v62, -v80, v13, v62
	v_fma_f32 v46, -v76, v29, v46
	v_fmac_f32_e32 v14, v78, v13
	v_fmac_f32_e32 v30, v74, v29
	v_fmac_f32_e32 v63, v78, v62
	v_fmac_f32_e32 v47, v74, v46
	v_fmac_f32_e32 v15, v80, v62
	v_fmac_f32_e32 v31, v76, v46
	v_fma_f32 v63, -v80, v14, v63
	v_fma_f32 v47, -v76, v30, v47
	v_fmac_f32_e32 v15, v78, v14
	v_fmac_f32_e32 v31, v74, v30
	v_fmac_f32_e32 v64, v78, v63
	v_fmac_f32_e32 v48, v74, v47
	v_fmac_f32_e32 v16, v80, v63
	v_fmac_f32_e32 v32, v76, v47
	v_fma_f32 v64, -v80, v15, v64
	v_fma_f32 v48, -v76, v31, v48
	v_fmac_f32_e32 v16, v78, v15
	v_fmac_f32_e32 v32, v74, v31
	v_fmac_f32_e32 v65, v78, v64
	v_fmac_f32_e32 v49, v74, v48
	v_fmac_f32_e32 v17, v80, v64
	v_fmac_f32_e32 v33, v76, v48
	v_fma_f32 v65, -v80, v16, v65
	v_fma_f32 v49, -v76, v32, v49
	v_fmac_f32_e32 v17, v78, v16
	v_fmac_f32_e32 v33, v74, v32
	v_mov_b32_e32 v156, v65
	v_mov_b32_e32 v157, v17
	v_mov_b32_e32 v158, v65
	v_mov_b32_e32 v159, v17
	s_nop 1
	v_permlane32_swap_b32_e32 v156, v158
	v_permlane32_swap_b32_e32 v157, v159
	v_pk_fma_f32 v[164:165], v[166:167], v[152:153], v[156:157] op_sel_hi:[1,0,1]
	v_pk_fma_f32 v[164:165], v[166:167], v[152:153], v[164:165] op_sel:[1,1,0] op_sel_hi:[0,1,1] neg_lo:[0,1,0]
	v_cndmask_b32_e32 v164, v166, v164, vcc
	v_cndmask_b32_e32 v165, v167, v165, vcc
	v_mov_b32_e32 v156, v49
	v_mov_b32_e32 v157, v33
	v_mov_b32_e32 v158, v49
	v_mov_b32_e32 v159, v33
	s_nop 1
	v_permlane32_swap_b32_e32 v156, v158
	v_permlane32_swap_b32_e32 v157, v159
	v_pk_fma_f32 v[170:171], v[150:151], v[154:155], v[156:157] op_sel_hi:[1,0,1]
	v_pk_fma_f32 v[170:171], v[150:151], v[154:155], v[170:171] op_sel:[1,1,0] op_sel_hi:[0,1,1] neg_lo:[0,1,0]
	v_cndmask_b32_e32 v170, v150, v170, vcc
	v_cndmask_b32_e32 v171, v151, v171, vcc
	v_pk_mul_f32 v[168:169], v[164:165], v[70:71] op_sel:[0,1] op_sel_hi:[1,1]
	v_pk_mul_f32 v[172:173], v[170:171], v[66:67] op_sel:[0,1] op_sel_hi:[1,1]
	v_pk_fma_f32 v[168:169], v[164:165], v[72:73], v[168:169] op_sel:[1,1,0] op_sel_hi:[0,1,1] neg_lo:[0,1,0]
	v_pk_fma_f32 v[172:173], v[170:171], v[68:69], v[172:173] op_sel:[1,1,0] op_sel_hi:[0,1,1] neg_lo:[0,1,0]
	v_pk_fma_f32 v[50:51], v[78:79], v[164:165], v[50:51] op_sel_hi:[1,0,1]
	v_pk_fma_f32 v[34:35], v[74:75], v[170:171], v[34:35] op_sel_hi:[1,0,1]
	v_pk_fma_f32 v[52:53], v[70:71], v[164:165], v[52:53] op_sel_hi:[1,0,1]
	v_pk_fma_f32 v[36:37], v[66:67], v[170:171], v[36:37] op_sel_hi:[1,0,1]
	v_pk_fma_f32 v[2:3], v[80:81], v[164:165], v[2:3] op_sel_hi:[1,0,1]
	v_pk_fma_f32 v[18:19], v[76:77], v[170:171], v[18:19] op_sel_hi:[1,0,1]
	v_pk_fma_f32 v[4:5], v[72:73], v[164:165], v[4:5] op_sel_hi:[1,0,1]
	v_pk_fma_f32 v[20:21], v[68:69], v[170:171], v[20:21] op_sel_hi:[1,0,1]
	v_pk_fma_f32 v[50:51], v[80:81], v[164:165], v[50:51] op_sel:[0,1,0] op_sel_hi:[1,1,1] neg_lo:[0,1,0] neg_hi:[0,1,0]
	v_pk_fma_f32 v[34:35], v[76:77], v[170:171], v[34:35] op_sel:[0,1,0] op_sel_hi:[1,1,1] neg_lo:[0,1,0] neg_hi:[0,1,0]
	v_pk_fma_f32 v[52:53], v[72:73], v[164:165], v[52:53] op_sel:[0,1,0] op_sel_hi:[1,1,1] neg_lo:[0,1,0] neg_hi:[0,1,0]
	v_pk_fma_f32 v[36:37], v[68:69], v[170:171], v[36:37] op_sel:[0,1,0] op_sel_hi:[1,1,1] neg_lo:[0,1,0] neg_hi:[0,1,0]
	v_pk_fma_f32 v[2:3], v[78:79], v[164:165], v[2:3] op_sel:[0,1,0] op_sel_hi:[1,1,1]
	v_pk_fma_f32 v[18:19], v[74:75], v[170:171], v[18:19] op_sel:[0,1,0] op_sel_hi:[1,1,1]
	v_pk_fma_f32 v[4:5], v[70:71], v[164:165], v[4:5] op_sel:[0,1,0] op_sel_hi:[1,1,1]
	v_pk_fma_f32 v[20:21], v[66:67], v[170:171], v[20:21] op_sel:[0,1,0] op_sel_hi:[1,1,1]
	v_pk_mul_f32 v[164:165], v[168:169], v[70:71] op_sel:[0,1] op_sel_hi:[1,1]
	v_pk_mul_f32 v[170:171], v[172:173], v[66:67] op_sel:[0,1] op_sel_hi:[1,1]
	v_pk_fma_f32 v[164:165], v[168:169], v[72:73], v[164:165] op_sel:[1,1,0] op_sel_hi:[0,1,1] neg_lo:[0,1,0]
	v_pk_fma_f32 v[170:171], v[172:173], v[68:69], v[170:171] op_sel:[1,1,0] op_sel_hi:[0,1,1] neg_lo:[0,1,0]
	v_pk_fma_f32 v[54:55], v[78:79], v[168:169], v[54:55] op_sel_hi:[1,0,1]
	v_pk_fma_f32 v[38:39], v[74:75], v[172:173], v[38:39] op_sel_hi:[1,0,1]
	v_pk_fma_f32 v[56:57], v[70:71], v[168:169], v[56:57] op_sel_hi:[1,0,1]
	v_pk_fma_f32 v[40:41], v[66:67], v[172:173], v[40:41] op_sel_hi:[1,0,1]
	v_pk_fma_f32 v[6:7], v[80:81], v[168:169], v[6:7] op_sel_hi:[1,0,1]
	v_pk_fma_f32 v[22:23], v[76:77], v[172:173], v[22:23] op_sel_hi:[1,0,1]
	v_pk_fma_f32 v[8:9], v[72:73], v[168:169], v[8:9] op_sel_hi:[1,0,1]
	v_pk_fma_f32 v[24:25], v[68:69], v[172:173], v[24:25] op_sel_hi:[1,0,1]
	v_pk_fma_f32 v[54:55], v[80:81], v[168:169], v[54:55] op_sel:[0,1,0] op_sel_hi:[1,1,1] neg_lo:[0,1,0] neg_hi:[0,1,0]
	v_pk_fma_f32 v[38:39], v[76:77], v[172:173], v[38:39] op_sel:[0,1,0] op_sel_hi:[1,1,1] neg_lo:[0,1,0] neg_hi:[0,1,0]
	v_pk_fma_f32 v[56:57], v[72:73], v[168:169], v[56:57] op_sel:[0,1,0] op_sel_hi:[1,1,1] neg_lo:[0,1,0] neg_hi:[0,1,0]
	v_pk_fma_f32 v[40:41], v[68:69], v[172:173], v[40:41] op_sel:[0,1,0] op_sel_hi:[1,1,1] neg_lo:[0,1,0] neg_hi:[0,1,0]
	v_pk_fma_f32 v[6:7], v[78:79], v[168:169], v[6:7] op_sel:[0,1,0] op_sel_hi:[1,1,1]
	v_pk_fma_f32 v[22:23], v[74:75], v[172:173], v[22:23] op_sel:[0,1,0] op_sel_hi:[1,1,1]
	v_pk_fma_f32 v[8:9], v[70:71], v[168:169], v[8:9] op_sel:[0,1,0] op_sel_hi:[1,1,1]
	v_pk_fma_f32 v[24:25], v[66:67], v[172:173], v[24:25] op_sel:[0,1,0] op_sel_hi:[1,1,1]
	v_pk_mul_f32 v[168:169], v[164:165], v[70:71] op_sel:[0,1] op_sel_hi:[1,1]
	v_pk_mul_f32 v[172:173], v[170:171], v[66:67] op_sel:[0,1] op_sel_hi:[1,1]
	v_pk_fma_f32 v[168:169], v[164:165], v[72:73], v[168:169] op_sel:[1,1,0] op_sel_hi:[0,1,1] neg_lo:[0,1,0]
	v_pk_fma_f32 v[172:173], v[170:171], v[68:69], v[172:173] op_sel:[1,1,0] op_sel_hi:[0,1,1] neg_lo:[0,1,0]
	v_pk_fma_f32 v[58:59], v[78:79], v[164:165], v[58:59] op_sel_hi:[1,0,1]
	v_pk_fma_f32 v[42:43], v[74:75], v[170:171], v[42:43] op_sel_hi:[1,0,1]
	v_pk_fma_f32 v[60:61], v[70:71], v[164:165], v[60:61] op_sel_hi:[1,0,1]
	v_pk_fma_f32 v[44:45], v[66:67], v[170:171], v[44:45] op_sel_hi:[1,0,1]
	v_pk_fma_f32 v[10:11], v[80:81], v[164:165], v[10:11] op_sel_hi:[1,0,1]
	v_pk_fma_f32 v[26:27], v[76:77], v[170:171], v[26:27] op_sel_hi:[1,0,1]
	v_pk_fma_f32 v[12:13], v[72:73], v[164:165], v[12:13] op_sel_hi:[1,0,1]
	v_pk_fma_f32 v[28:29], v[68:69], v[170:171], v[28:29] op_sel_hi:[1,0,1]
	v_pk_fma_f32 v[58:59], v[80:81], v[164:165], v[58:59] op_sel:[0,1,0] op_sel_hi:[1,1,1] neg_lo:[0,1,0] neg_hi:[0,1,0]
	v_pk_fma_f32 v[42:43], v[76:77], v[170:171], v[42:43] op_sel:[0,1,0] op_sel_hi:[1,1,1] neg_lo:[0,1,0] neg_hi:[0,1,0]
	v_pk_fma_f32 v[60:61], v[72:73], v[164:165], v[60:61] op_sel:[0,1,0] op_sel_hi:[1,1,1] neg_lo:[0,1,0] neg_hi:[0,1,0]
	v_pk_fma_f32 v[44:45], v[68:69], v[170:171], v[44:45] op_sel:[0,1,0] op_sel_hi:[1,1,1] neg_lo:[0,1,0] neg_hi:[0,1,0]
	v_pk_fma_f32 v[10:11], v[78:79], v[164:165], v[10:11] op_sel:[0,1,0] op_sel_hi:[1,1,1]
	v_pk_fma_f32 v[26:27], v[74:75], v[170:171], v[26:27] op_sel:[0,1,0] op_sel_hi:[1,1,1]
	v_pk_fma_f32 v[12:13], v[70:71], v[164:165], v[12:13] op_sel:[0,1,0] op_sel_hi:[1,1,1]
	v_pk_fma_f32 v[28:29], v[66:67], v[170:171], v[28:29] op_sel:[0,1,0] op_sel_hi:[1,1,1]
	v_pk_fma_f32 v[62:63], v[78:79], v[168:169], v[62:63] op_sel_hi:[1,0,1]
	v_pk_fma_f32 v[46:47], v[74:75], v[172:173], v[46:47] op_sel_hi:[1,0,1]
	v_pk_fma_f32 v[64:65], v[70:71], v[168:169], v[64:65] op_sel_hi:[1,0,1]
	v_pk_fma_f32 v[48:49], v[66:67], v[172:173], v[48:49] op_sel_hi:[1,0,1]
	v_pk_fma_f32 v[14:15], v[80:81], v[168:169], v[14:15] op_sel_hi:[1,0,1]
	v_pk_fma_f32 v[30:31], v[76:77], v[172:173], v[30:31] op_sel_hi:[1,0,1]
	v_pk_fma_f32 v[16:17], v[72:73], v[168:169], v[16:17] op_sel_hi:[1,0,1]
	v_pk_fma_f32 v[32:33], v[68:69], v[172:173], v[32:33] op_sel_hi:[1,0,1]
	v_pk_fma_f32 v[62:63], v[80:81], v[168:169], v[62:63] op_sel:[0,1,0] op_sel_hi:[1,1,1] neg_lo:[0,1,0] neg_hi:[0,1,0]
	v_pk_fma_f32 v[46:47], v[76:77], v[172:173], v[46:47] op_sel:[0,1,0] op_sel_hi:[1,1,1] neg_lo:[0,1,0] neg_hi:[0,1,0]
	v_pk_fma_f32 v[64:65], v[72:73], v[168:169], v[64:65] op_sel:[0,1,0] op_sel_hi:[1,1,1] neg_lo:[0,1,0] neg_hi:[0,1,0]
	v_pk_fma_f32 v[48:49], v[68:69], v[172:173], v[48:49] op_sel:[0,1,0] op_sel_hi:[1,1,1] neg_lo:[0,1,0] neg_hi:[0,1,0]
	v_pk_fma_f32 v[14:15], v[78:79], v[168:169], v[14:15] op_sel:[0,1,0] op_sel_hi:[1,1,1]
	v_pk_fma_f32 v[30:31], v[74:75], v[172:173], v[30:31] op_sel:[0,1,0] op_sel_hi:[1,1,1]
	v_pk_fma_f32 v[16:17], v[70:71], v[168:169], v[16:17] op_sel:[0,1,0] op_sel_hi:[1,1,1]
	v_pk_fma_f32 v[32:33], v[66:67], v[172:173], v[32:33] op_sel:[0,1,0] op_sel_hi:[1,1,1]
	v_mov_b32_e32 v156, v65
	v_mov_b32_e32 v157, v17
	v_mov_b32_e32 v166, v65
	v_mov_b32_e32 v167, v17
	s_nop 1
	v_permlane32_swap_b32_e32 v156, v166
	v_permlane32_swap_b32_e32 v157, v167
	v_mov_b32_e32 v156, v49
	v_mov_b32_e32 v157, v33
	v_mov_b32_e32 v150, v49
	v_mov_b32_e32 v151, v33
	s_nop 1
	v_permlane32_swap_b32_e32 v156, v150
	v_permlane32_swap_b32_e32 v157, v151
	v_cvt_pk_bf16_f32 v1, v50, v2
	ds_write_b32 v174, v1
	v_cvt_pk_bf16_f32 v146, v34, v18
	ds_write_b32 v174, v146 offset:128
	v_cvt_pk_bf16_f32 v178, v51, v3
	ds_write_b32 v174, v178 offset:272
	v_cvt_pk_bf16_f32 v1, v35, v19
	ds_write_b32 v174, v1 offset:400
	v_cvt_pk_bf16_f32 v146, v52, v4
	ds_write_b32 v174, v146 offset:544
	v_cvt_pk_bf16_f32 v178, v36, v20
	ds_write_b32 v174, v178 offset:672
	v_cvt_pk_bf16_f32 v1, v53, v5
	ds_write_b32 v174, v1 offset:816
	v_cvt_pk_bf16_f32 v146, v37, v21
	ds_write_b32 v174, v146 offset:944
	v_cvt_pk_bf16_f32 v178, v54, v6
	ds_write_b32 v174, v178 offset:1088
	v_cvt_pk_bf16_f32 v1, v38, v22
	ds_write_b32 v174, v1 offset:1216
	v_cvt_pk_bf16_f32 v146, v55, v7
	ds_write_b32 v174, v146 offset:1360
	v_cvt_pk_bf16_f32 v178, v39, v23
	ds_write_b32 v174, v178 offset:1488
	v_cvt_pk_bf16_f32 v1, v56, v8
	ds_write_b32 v174, v1 offset:1632
	v_cvt_pk_bf16_f32 v146, v40, v24
	ds_write_b32 v174, v146 offset:1760
	v_cvt_pk_bf16_f32 v178, v57, v9
	ds_write_b32 v174, v178 offset:1904
	v_cvt_pk_bf16_f32 v1, v41, v25
	ds_write_b32 v174, v1 offset:2032
	v_cvt_pk_bf16_f32 v146, v58, v10
	ds_write_b32 v174, v146 offset:2176
	v_cvt_pk_bf16_f32 v178, v42, v26
	ds_write_b32 v174, v178 offset:2304
	v_cvt_pk_bf16_f32 v1, v59, v11
	ds_write_b32 v174, v1 offset:2448
	v_cvt_pk_bf16_f32 v146, v43, v27
	ds_write_b32 v174, v146 offset:2576
	v_cvt_pk_bf16_f32 v178, v60, v12
	ds_write_b32 v174, v178 offset:2720
	v_cvt_pk_bf16_f32 v1, v44, v28
	ds_write_b32 v174, v1 offset:2848
	v_cvt_pk_bf16_f32 v146, v61, v13
	ds_write_b32 v174, v146 offset:2992
	v_cvt_pk_bf16_f32 v178, v45, v29
	ds_write_b32 v174, v178 offset:3120
	v_cvt_pk_bf16_f32 v1, v62, v14
	ds_write_b32 v174, v1 offset:3264
	v_cvt_pk_bf16_f32 v146, v46, v30
	ds_write_b32 v174, v146 offset:3392
	v_cvt_pk_bf16_f32 v178, v63, v15
	ds_write_b32 v174, v178 offset:3536
	v_cvt_pk_bf16_f32 v1, v47, v31
	ds_write_b32 v174, v1 offset:3664
	v_cvt_pk_bf16_f32 v146, v64, v16
	ds_write_b32 v174, v146 offset:3808
	v_cvt_pk_bf16_f32 v178, v48, v32
	ds_write_b32 v174, v178 offset:3936
	v_cvt_pk_bf16_f32 v1, v65, v17
	ds_write_b32 v174, v1 offset:4080
	v_cvt_pk_bf16_f32 v146, v49, v33
	ds_write_b32 v174, v146 offset:4208
	s_waitcnt lgkmcnt(0)
	ds_read_b128 v[2:5], v175
	ds_read_b128 v[6:9], v175 offset:64
	ds_read_b128 v[10:13], v175 offset:128
	ds_read_b128 v[14:17], v175 offset:192
	ds_read_b128 v[18:21], v175 offset:4352
	ds_read_b128 v[22:25], v175 offset:4416
	ds_read_b128 v[26:29], v175 offset:4480
	ds_read_b128 v[30:33], v175 offset:4544
	s_waitcnt vmcnt(0)
	s_waitcnt lgkmcnt(7)
	v_mfma_f32_16x16x32_bf16 v[34:37], v[94:97], v[2:5], 0
	s_waitcnt lgkmcnt(6)
	v_mfma_f32_16x16x32_bf16 v[34:37], v[90:93], v[6:9], v[34:37]
	s_waitcnt lgkmcnt(5)
	v_mfma_f32_16x16x32_bf16 v[34:37], v[86:89], v[10:13], v[34:37]
	s_waitcnt lgkmcnt(4)
	v_mfma_f32_16x16x32_bf16 v[34:37], v[82:85], v[14:17], v[34:37]
	s_waitcnt lgkmcnt(3)
	v_mfma_f32_16x16x32_bf16 v[38:41], v[94:97], v[18:21], 0
	s_waitcnt lgkmcnt(2)
	v_mfma_f32_16x16x32_bf16 v[38:41], v[90:93], v[22:25], v[38:41]
	s_waitcnt lgkmcnt(1)
	v_mfma_f32_16x16x32_bf16 v[38:41], v[86:89], v[26:29], v[38:41]
	s_waitcnt lgkmcnt(0)
	v_mfma_f32_16x16x32_bf16 v[38:41], v[82:85], v[30:33], v[38:41]
	s_add_u32 s6, s6, 0x8000
	s_addc_u32 s7, s7, 0
	v_lshlrev_b32_e32 v42, 16, v160
	v_and_b32_e32 v43, 0xffff0000, v160
	v_lshlrev_b32_e32 v44, 16, v161
	v_and_b32_e32 v45, 0xffff0000, v161
	v_lshlrev_b32_e32 v46, 16, v162
	v_and_b32_e32 v47, 0xffff0000, v162
	v_lshlrev_b32_e32 v48, 16, v163
	v_and_b32_e32 v49, 0xffff0000, v163
	s_nop 1
	v_mov_b32_e32 v156, 0x3d372713
	v_mov_b32_e32 v158, 0xbfcc422a
	v_mov_b32_e32 v164, 0x3fb8aa3b
	v_mov_b32_e32 v168, 1.0
	v_pk_fma_f32 v[50:51], v[98:99], v[42:43], v[34:35]
	v_pk_fma_f32 v[52:53], v[100:101], v[44:45], v[36:37]
	v_pk_fma_f32 v[54:55], v[98:99], v[46:47], v[38:39]
	v_pk_fma_f32 v[56:57], v[100:101], v[48:49], v[40:41]
	v_pk_mul_f32 v[2:3], v[50:51], v[156:157] op_sel_hi:[1,0]
	v_pk_mul_f32 v[4:5], v[52:53], v[156:157] op_sel_hi:[1,0]
	v_pk_mul_f32 v[6:7], v[54:55], v[156:157] op_sel_hi:[1,0]
	v_pk_mul_f32 v[8:9], v[56:57], v[156:157] op_sel_hi:[1,0]
	v_pk_mul_f32 v[2:3], v[50:51], v[2:3]
	v_pk_mul_f32 v[4:5], v[52:53], v[4:5]
	v_pk_mul_f32 v[6:7], v[54:55], v[6:7]
	v_pk_mul_f32 v[8:9], v[56:57], v[8:9]
	v_pk_fma_f32 v[2:3], v[50:51], v[2:3], v[50:51]
	v_pk_fma_f32 v[4:5], v[52:53], v[4:5], v[52:53]
	v_pk_fma_f32 v[6:7], v[54:55], v[6:7], v[54:55]
	v_pk_fma_f32 v[8:9], v[56:57], v[8:9], v[56:57]
	v_pk_mul_f32 v[2:3], v[2:3], v[158:159] op_sel_hi:[1,0]
	v_pk_mul_f32 v[4:5], v[4:5], v[158:159] op_sel_hi:[1,0]
	v_pk_mul_f32 v[6:7], v[6:7], v[158:159] op_sel_hi:[1,0]
	v_pk_mul_f32 v[8:9], v[8:9], v[158:159] op_sel_hi:[1,0]
	v_pk_mul_f32 v[2:3], v[2:3], v[164:165] op_sel_hi:[1,0]
	v_pk_mul_f32 v[4:5], v[4:5], v[164:165] op_sel_hi:[1,0]
	v_pk_mul_f32 v[6:7], v[6:7], v[164:165] op_sel_hi:[1,0]
	v_pk_mul_f32 v[8:9], v[8:9], v[164:165] op_sel_hi:[1,0]
	v_exp_f32_e32 v2, v2
	v_exp_f32_e32 v3, v3
	v_exp_f32_e32 v4, v4
	v_exp_f32_e32 v5, v5
	v_exp_f32_e32 v6, v6
	v_exp_f32_e32 v7, v7
	v_exp_f32_e32 v8, v8
	v_exp_f32_e32 v9, v9
	v_pk_add_f32 v[2:3], v[2:3], v[168:169] op_sel_hi:[1,0]
	v_pk_add_f32 v[4:5], v[4:5], v[168:169] op_sel_hi:[1,0]
	v_pk_add_f32 v[6:7], v[6:7], v[168:169] op_sel_hi:[1,0]
	v_pk_add_f32 v[8:9], v[8:9], v[168:169] op_sel_hi:[1,0]
	v_rcp_f32_e32 v2, v2
	v_rcp_f32_e32 v3, v3
	v_rcp_f32_e32 v4, v4
	v_rcp_f32_e32 v5, v5
	v_rcp_f32_e32 v6, v6
	v_rcp_f32_e32 v7, v7
	v_rcp_f32_e32 v8, v8
	v_rcp_f32_e32 v9, v9
	v_pk_mul_f32 v[50:51], v[50:51], v[2:3]
	v_pk_mul_f32 v[52:53], v[52:53], v[4:5]
	v_pk_mul_f32 v[54:55], v[54:55], v[6:7]
	v_pk_mul_f32 v[56:57], v[56:57], v[8:9]
	v_cvt_pk_bf16_f32 v10, v50, v51
	v_cvt_pk_bf16_f32 v11, v52, v53
	v_cvt_pk_bf16_f32 v12, v54, v55
	v_cvt_pk_bf16_f32 v13, v56, v57
	global_store_dwordx2 v176, v[10:11], s[10:11]
	global_store_dwordx2 v177, v[12:13], s[10:11]
	s_add_u32 s10, s10, 0x8000
	s_addc_u32 s11, s11, 0
	s_nop 0
	v_mfma_f32_32x32x16_bf16 v[50:65], v[118:121], v[114:117], 0
	v_mfma_f32_32x32x16_bf16 v[2:17], v[118:121], v[110:113], 0
	v_mfma_f32_32x32x16_bf16 v[34:49], v[118:121], v[106:109], 0
	v_mfma_f32_32x32x16_bf16 v[18:33], v[118:121], v[102:105], 0
	global_load_dwordx2 v[160:161], v176, s[6:7]
	global_load_dwordx2 v[162:163], v177, s[6:7]
	s_cmp_lg_u32 s3, 0
	s_cbranch_scc1 .Lp2_noclaim
	s_add_u32 s98, s72, 0x8100
	s_addc_u32 s99, s73, 0
	s_mov_b64 s[4:5], exec
	s_mov_b64 exec, 1
	v_mov_b32_e32 v178, 1
	s_nop 0
	global_atomic_add v149, v147, v178, s[98:99] sc0
	s_mov_b64 exec, s[4:5]
.Lp2_noclaim:
	s_nop 9
	v_fmac_f32_e32 v51, v78, v50
	v_fmac_f32_e32 v35, v74, v34
	v_fmac_f32_e32 v3, v80, v50
	v_fmac_f32_e32 v19, v76, v34
	v_fma_f32 v51, -v80, v2, v51
	v_fma_f32 v35, -v76, v18, v35
	v_fmac_f32_e32 v3, v78, v2
	v_fmac_f32_e32 v19, v74, v18
	v_fmac_f32_e32 v52, v78, v51
	v_fmac_f32_e32 v36, v74, v35
	v_fmac_f32_e32 v4, v80, v51
	v_fmac_f32_e32 v20, v76, v35
	v_fma_f32 v52, -v80, v3, v52
	v_fma_f32 v36, -v76, v19, v36
	v_fmac_f32_e32 v4, v78, v3
	v_fmac_f32_e32 v20, v74, v19
	v_fmac_f32_e32 v53, v78, v52
	v_fmac_f32_e32 v37, v74, v36
	v_fmac_f32_e32 v5, v80, v52
	v_fmac_f32_e32 v21, v76, v36
	v_fma_f32 v53, -v80, v4, v53
	v_fma_f32 v37, -v76, v20, v37
	v_fmac_f32_e32 v5, v78, v4
	v_fmac_f32_e32 v21, v74, v20
	v_fmac_f32_e32 v54, v78, v53
	v_fmac_f32_e32 v38, v74, v37
	v_fmac_f32_e32 v6, v80, v53
	v_fmac_f32_e32 v22, v76, v37
	v_fma_f32 v54, -v80, v5, v54
	v_fma_f32 v38, -v76, v21, v38
	v_fmac_f32_e32 v6, v78, v5
	v_fmac_f32_e32 v22, v74, v21
	v_fmac_f32_e32 v55, v78, v54
	v_fmac_f32_e32 v39, v74, v38
	v_fmac_f32_e32 v7, v80, v54
	v_fmac_f32_e32 v23, v76, v38
	v_fma_f32 v55, -v80, v6, v55
	v_fma_f32 v39, -v76, v22, v39
	v_fmac_f32_e32 v7, v78, v6
	v_fmac_f32_e32 v23, v74, v22
	v_fmac_f32_e32 v56, v78, v55
	v_fmac_f32_e32 v40, v74, v39
	v_fmac_f32_e32 v8, v80, v55
	v_fmac_f32_e32 v24, v76, v39
	v_fma_f32 v56, -v80, v7, v56
	v_fma_f32 v40, -v76, v23, v40
	v_fmac_f32_e32 v8, v78, v7
	v_fmac_f32_e32 v24, v74, v23
	v_fmac_f32_e32 v57, v78, v56
	v_fmac_f32_e32 v41, v74, v40
	v_fmac_f32_e32 v9, v80, v56
	v_fmac_f32_e32 v25, v76, v40
	v_fma_f32 v57, -v80, v8, v57
	v_fma_f32 v41, -v76, v24, v41
	v_fmac_f32_e32 v9, v78, v8
	v_fmac_f32_e32 v25, v74, v24
	v_fmac_f32_e32 v58, v78, v57
	v_fmac_f32_e32 v42, v74, v41
	v_fmac_f32_e32 v10, v80, v57
	v_fmac_f32_e32 v26, v76, v41
	v_fma_f32 v58, -v80, v9, v58
	v_fma_f32 v42, -v76, v25, v42
	v_fmac_f32_e32 v10, v78, v9
	v_fmac_f32_e32 v26, v74, v25
	v_fmac_f32_e32 v59, v78, v58
	v_fmac_f32_e32 v43, v74, v42
	v_fmac_f32_e32 v11, v80, v58
	v_fmac_f32_e32 v27, v76, v42
	v_fma_f32 v59, -v80, v10, v59
	v_fma_f32 v43, -v76, v26, v43
	v_fmac_f32_e32 v11, v78, v10
	v_fmac_f32_e32 v27, v74, v26
	v_fmac_f32_e32 v60, v78, v59
	v_fmac_f32_e32 v44, v74, v43
	v_fmac_f32_e32 v12, v80, v59
	v_fmac_f32_e32 v28, v76, v43
	v_fma_f32 v60, -v80, v11, v60
	v_fma_f32 v44, -v76, v27, v44
	v_fmac_f32_e32 v12, v78, v11
	v_fmac_f32_e32 v28, v74, v27
	v_fmac_f32_e32 v61, v78, v60
	v_fmac_f32_e32 v45, v74, v44
	v_fmac_f32_e32 v13, v80, v60
	v_fmac_f32_e32 v29, v76, v44
	v_fma_f32 v61, -v80, v12, v61
	v_fma_f32 v45, -v76, v28, v45
	v_fmac_f32_e32 v13, v78, v12
	v_fmac_f32_e32 v29, v74, v28
	v_fmac_f32_e32 v62, v78, v61
	v_fmac_f32_e32 v46, v74, v45
	v_fmac_f32_e32 v14, v80, v61
	v_fmac_f32_e32 v30, v76, v45
	v_fma_f32 v62, -v80, v13, v62
	v_fma_f32 v46, -v76, v29, v46
	v_fmac_f32_e32 v14, v78, v13
	v_fmac_f32_e32 v30, v74, v29
	v_fmac_f32_e32 v63, v78, v62
	v_fmac_f32_e32 v47, v74, v46
	v_fmac_f32_e32 v15, v80, v62
	v_fmac_f32_e32 v31, v76, v46
	v_fma_f32 v63, -v80, v14, v63
	v_fma_f32 v47, -v76, v30, v47
	v_fmac_f32_e32 v15, v78, v14
	v_fmac_f32_e32 v31, v74, v30
	v_fmac_f32_e32 v64, v78, v63
	v_fmac_f32_e32 v48, v74, v47
	v_fmac_f32_e32 v16, v80, v63
	v_fmac_f32_e32 v32, v76, v47
	v_fma_f32 v64, -v80, v15, v64
	v_fma_f32 v48, -v76, v31, v48
	v_fmac_f32_e32 v16, v78, v15
	v_fmac_f32_e32 v32, v74, v31
	v_fmac_f32_e32 v65, v78, v64
	v_fmac_f32_e32 v49, v74, v48
	v_fmac_f32_e32 v17, v80, v64
	v_fmac_f32_e32 v33, v76, v48
	v_fma_f32 v65, -v80, v16, v65
	v_fma_f32 v49, -v76, v32, v49
	v_fmac_f32_e32 v17, v78, v16
	v_fmac_f32_e32 v33, v74, v32
	v_mov_b32_e32 v156, v65
	v_mov_b32_e32 v157, v17
	v_mov_b32_e32 v158, v65
	v_mov_b32_e32 v159, v17
	s_nop 1
	v_permlane32_swap_b32_e32 v156, v158
	v_permlane32_swap_b32_e32 v157, v159
	v_pk_fma_f32 v[164:165], v[166:167], v[152:153], v[156:157] op_sel_hi:[1,0,1]
	v_pk_fma_f32 v[164:165], v[166:167], v[152:153], v[164:165] op_sel:[1,1,0] op_sel_hi:[0,1,1] neg_lo:[0,1,0]
	v_cndmask_b32_e32 v164, v166, v164, vcc
	v_cndmask_b32_e32 v165, v167, v165, vcc
	v_mov_b32_e32 v156, v49
	v_mov_b32_e32 v157, v33
	v_mov_b32_e32 v158, v49
	v_mov_b32_e32 v159, v33
	s_nop 1
	v_permlane32_swap_b32_e32 v156, v158
	v_permlane32_swap_b32_e32 v157, v159
	v_pk_fma_f32 v[170:171], v[150:151], v[154:155], v[156:157] op_sel_hi:[1,0,1]
	v_pk_fma_f32 v[170:171], v[150:151], v[154:155], v[170:171] op_sel:[1,1,0] op_sel_hi:[0,1,1] neg_lo:[0,1,0]
	v_cndmask_b32_e32 v170, v150, v170, vcc
	v_cndmask_b32_e32 v171, v151, v171, vcc
	v_pk_mul_f32 v[168:169], v[164:165], v[70:71] op_sel:[0,1] op_sel_hi:[1,1]
	v_pk_mul_f32 v[172:173], v[170:171], v[66:67] op_sel:[0,1] op_sel_hi:[1,1]
	v_pk_fma_f32 v[168:169], v[164:165], v[72:73], v[168:169] op_sel:[1,1,0] op_sel_hi:[0,1,1] neg_lo:[0,1,0]
	v_pk_fma_f32 v[172:173], v[170:171], v[68:69], v[172:173] op_sel:[1,1,0] op_sel_hi:[0,1,1] neg_lo:[0,1,0]
	v_pk_fma_f32 v[50:51], v[78:79], v[164:165], v[50:51] op_sel_hi:[1,0,1]
	v_pk_fma_f32 v[34:35], v[74:75], v[170:171], v[34:35] op_sel_hi:[1,0,1]
	v_pk_fma_f32 v[52:53], v[70:71], v[164:165], v[52:53] op_sel_hi:[1,0,1]
	v_pk_fma_f32 v[36:37], v[66:67], v[170:171], v[36:37] op_sel_hi:[1,0,1]
	v_pk_fma_f32 v[2:3], v[80:81], v[164:165], v[2:3] op_sel_hi:[1,0,1]
	v_pk_fma_f32 v[18:19], v[76:77], v[170:171], v[18:19] op_sel_hi:[1,0,1]
	v_pk_fma_f32 v[4:5], v[72:73], v[164:165], v[4:5] op_sel_hi:[1,0,1]
	v_pk_fma_f32 v[20:21], v[68:69], v[170:171], v[20:21] op_sel_hi:[1,0,1]
	v_pk_fma_f32 v[50:51], v[80:81], v[164:165], v[50:51] op_sel:[0,1,0] op_sel_hi:[1,1,1] neg_lo:[0,1,0] neg_hi:[0,1,0]
	v_pk_fma_f32 v[34:35], v[76:77], v[170:171], v[34:35] op_sel:[0,1,0] op_sel_hi:[1,1,1] neg_lo:[0,1,0] neg_hi:[0,1,0]
	v_pk_fma_f32 v[52:53], v[72:73], v[164:165], v[52:53] op_sel:[0,1,0] op_sel_hi:[1,1,1] neg_lo:[0,1,0] neg_hi:[0,1,0]
	v_pk_fma_f32 v[36:37], v[68:69], v[170:171], v[36:37] op_sel:[0,1,0] op_sel_hi:[1,1,1] neg_lo:[0,1,0] neg_hi:[0,1,0]
	v_pk_fma_f32 v[2:3], v[78:79], v[164:165], v[2:3] op_sel:[0,1,0] op_sel_hi:[1,1,1]
	v_pk_fma_f32 v[18:19], v[74:75], v[170:171], v[18:19] op_sel:[0,1,0] op_sel_hi:[1,1,1]
	v_pk_fma_f32 v[4:5], v[70:71], v[164:165], v[4:5] op_sel:[0,1,0] op_sel_hi:[1,1,1]
	v_pk_fma_f32 v[20:21], v[66:67], v[170:171], v[20:21] op_sel:[0,1,0] op_sel_hi:[1,1,1]
	v_pk_mul_f32 v[164:165], v[168:169], v[70:71] op_sel:[0,1] op_sel_hi:[1,1]
	v_pk_mul_f32 v[170:171], v[172:173], v[66:67] op_sel:[0,1] op_sel_hi:[1,1]
	v_pk_fma_f32 v[164:165], v[168:169], v[72:73], v[164:165] op_sel:[1,1,0] op_sel_hi:[0,1,1] neg_lo:[0,1,0]
	v_pk_fma_f32 v[170:171], v[172:173], v[68:69], v[170:171] op_sel:[1,1,0] op_sel_hi:[0,1,1] neg_lo:[0,1,0]
	v_pk_fma_f32 v[54:55], v[78:79], v[168:169], v[54:55] op_sel_hi:[1,0,1]
	v_pk_fma_f32 v[38:39], v[74:75], v[172:173], v[38:39] op_sel_hi:[1,0,1]
	v_pk_fma_f32 v[56:57], v[70:71], v[168:169], v[56:57] op_sel_hi:[1,0,1]
	v_pk_fma_f32 v[40:41], v[66:67], v[172:173], v[40:41] op_sel_hi:[1,0,1]
	v_pk_fma_f32 v[6:7], v[80:81], v[168:169], v[6:7] op_sel_hi:[1,0,1]
	v_pk_fma_f32 v[22:23], v[76:77], v[172:173], v[22:23] op_sel_hi:[1,0,1]
	v_pk_fma_f32 v[8:9], v[72:73], v[168:169], v[8:9] op_sel_hi:[1,0,1]
	v_pk_fma_f32 v[24:25], v[68:69], v[172:173], v[24:25] op_sel_hi:[1,0,1]
	v_pk_fma_f32 v[54:55], v[80:81], v[168:169], v[54:55] op_sel:[0,1,0] op_sel_hi:[1,1,1] neg_lo:[0,1,0] neg_hi:[0,1,0]
	v_pk_fma_f32 v[38:39], v[76:77], v[172:173], v[38:39] op_sel:[0,1,0] op_sel_hi:[1,1,1] neg_lo:[0,1,0] neg_hi:[0,1,0]
	v_pk_fma_f32 v[56:57], v[72:73], v[168:169], v[56:57] op_sel:[0,1,0] op_sel_hi:[1,1,1] neg_lo:[0,1,0] neg_hi:[0,1,0]
	v_pk_fma_f32 v[40:41], v[68:69], v[172:173], v[40:41] op_sel:[0,1,0] op_sel_hi:[1,1,1] neg_lo:[0,1,0] neg_hi:[0,1,0]
	v_pk_fma_f32 v[6:7], v[78:79], v[168:169], v[6:7] op_sel:[0,1,0] op_sel_hi:[1,1,1]
	v_pk_fma_f32 v[22:23], v[74:75], v[172:173], v[22:23] op_sel:[0,1,0] op_sel_hi:[1,1,1]
	v_pk_fma_f32 v[8:9], v[70:71], v[168:169], v[8:9] op_sel:[0,1,0] op_sel_hi:[1,1,1]
	v_pk_fma_f32 v[24:25], v[66:67], v[172:173], v[24:25] op_sel:[0,1,0] op_sel_hi:[1,1,1]
	v_pk_mul_f32 v[168:169], v[164:165], v[70:71] op_sel:[0,1] op_sel_hi:[1,1]
	v_pk_mul_f32 v[172:173], v[170:171], v[66:67] op_sel:[0,1] op_sel_hi:[1,1]
	v_pk_fma_f32 v[168:169], v[164:165], v[72:73], v[168:169] op_sel:[1,1,0] op_sel_hi:[0,1,1] neg_lo:[0,1,0]
	v_pk_fma_f32 v[172:173], v[170:171], v[68:69], v[172:173] op_sel:[1,1,0] op_sel_hi:[0,1,1] neg_lo:[0,1,0]
	v_pk_fma_f32 v[58:59], v[78:79], v[164:165], v[58:59] op_sel_hi:[1,0,1]
	v_pk_fma_f32 v[42:43], v[74:75], v[170:171], v[42:43] op_sel_hi:[1,0,1]
	v_pk_fma_f32 v[60:61], v[70:71], v[164:165], v[60:61] op_sel_hi:[1,0,1]
	v_pk_fma_f32 v[44:45], v[66:67], v[170:171], v[44:45] op_sel_hi:[1,0,1]
	v_pk_fma_f32 v[10:11], v[80:81], v[164:165], v[10:11] op_sel_hi:[1,0,1]
	v_pk_fma_f32 v[26:27], v[76:77], v[170:171], v[26:27] op_sel_hi:[1,0,1]
	v_pk_fma_f32 v[12:13], v[72:73], v[164:165], v[12:13] op_sel_hi:[1,0,1]
	v_pk_fma_f32 v[28:29], v[68:69], v[170:171], v[28:29] op_sel_hi:[1,0,1]
	v_pk_fma_f32 v[58:59], v[80:81], v[164:165], v[58:59] op_sel:[0,1,0] op_sel_hi:[1,1,1] neg_lo:[0,1,0] neg_hi:[0,1,0]
	v_pk_fma_f32 v[42:43], v[76:77], v[170:171], v[42:43] op_sel:[0,1,0] op_sel_hi:[1,1,1] neg_lo:[0,1,0] neg_hi:[0,1,0]
	v_pk_fma_f32 v[60:61], v[72:73], v[164:165], v[60:61] op_sel:[0,1,0] op_sel_hi:[1,1,1] neg_lo:[0,1,0] neg_hi:[0,1,0]
	v_pk_fma_f32 v[44:45], v[68:69], v[170:171], v[44:45] op_sel:[0,1,0] op_sel_hi:[1,1,1] neg_lo:[0,1,0] neg_hi:[0,1,0]
	v_pk_fma_f32 v[10:11], v[78:79], v[164:165], v[10:11] op_sel:[0,1,0] op_sel_hi:[1,1,1]
	v_pk_fma_f32 v[26:27], v[74:75], v[170:171], v[26:27] op_sel:[0,1,0] op_sel_hi:[1,1,1]
	v_pk_fma_f32 v[12:13], v[70:71], v[164:165], v[12:13] op_sel:[0,1,0] op_sel_hi:[1,1,1]
	v_pk_fma_f32 v[28:29], v[66:67], v[170:171], v[28:29] op_sel:[0,1,0] op_sel_hi:[1,1,1]
	v_pk_fma_f32 v[62:63], v[78:79], v[168:169], v[62:63] op_sel_hi:[1,0,1]
	v_pk_fma_f32 v[46:47], v[74:75], v[172:173], v[46:47] op_sel_hi:[1,0,1]
	v_pk_fma_f32 v[64:65], v[70:71], v[168:169], v[64:65] op_sel_hi:[1,0,1]
	v_pk_fma_f32 v[48:49], v[66:67], v[172:173], v[48:49] op_sel_hi:[1,0,1]
	v_pk_fma_f32 v[14:15], v[80:81], v[168:169], v[14:15] op_sel_hi:[1,0,1]
	v_pk_fma_f32 v[30:31], v[76:77], v[172:173], v[30:31] op_sel_hi:[1,0,1]
	v_pk_fma_f32 v[16:17], v[72:73], v[168:169], v[16:17] op_sel_hi:[1,0,1]
	v_pk_fma_f32 v[32:33], v[68:69], v[172:173], v[32:33] op_sel_hi:[1,0,1]
	v_pk_fma_f32 v[62:63], v[80:81], v[168:169], v[62:63] op_sel:[0,1,0] op_sel_hi:[1,1,1] neg_lo:[0,1,0] neg_hi:[0,1,0]
	v_pk_fma_f32 v[46:47], v[76:77], v[172:173], v[46:47] op_sel:[0,1,0] op_sel_hi:[1,1,1] neg_lo:[0,1,0] neg_hi:[0,1,0]
	v_pk_fma_f32 v[64:65], v[72:73], v[168:169], v[64:65] op_sel:[0,1,0] op_sel_hi:[1,1,1] neg_lo:[0,1,0] neg_hi:[0,1,0]
	v_pk_fma_f32 v[48:49], v[68:69], v[172:173], v[48:49] op_sel:[0,1,0] op_sel_hi:[1,1,1] neg_lo:[0,1,0] neg_hi:[0,1,0]
	v_pk_fma_f32 v[14:15], v[78:79], v[168:169], v[14:15] op_sel:[0,1,0] op_sel_hi:[1,1,1]
	v_pk_fma_f32 v[30:31], v[74:75], v[172:173], v[30:31] op_sel:[0,1,0] op_sel_hi:[1,1,1]
	v_pk_fma_f32 v[16:17], v[70:71], v[168:169], v[16:17] op_sel:[0,1,0] op_sel_hi:[1,1,1]
	v_pk_fma_f32 v[32:33], v[66:67], v[172:173], v[32:33] op_sel:[0,1,0] op_sel_hi:[1,1,1]
	v_mov_b32_e32 v156, v65
	v_mov_b32_e32 v157, v17
	v_mov_b32_e32 v166, v65
	v_mov_b32_e32 v167, v17
	s_nop 1
	v_permlane32_swap_b32_e32 v156, v166
	v_permlane32_swap_b32_e32 v157, v167
	v_mov_b32_e32 v156, v49
	v_mov_b32_e32 v157, v33
	v_mov_b32_e32 v150, v49
	v_mov_b32_e32 v151, v33
	s_nop 1
	v_permlane32_swap_b32_e32 v156, v150
	v_permlane32_swap_b32_e32 v157, v151
	v_cvt_pk_bf16_f32 v1, v50, v2
	ds_write_b32 v174, v1
	v_cvt_pk_bf16_f32 v146, v34, v18
	ds_write_b32 v174, v146 offset:128
	v_cvt_pk_bf16_f32 v178, v51, v3
	ds_write_b32 v174, v178 offset:272
	v_cvt_pk_bf16_f32 v1, v35, v19
	ds_write_b32 v174, v1 offset:400
	v_cvt_pk_bf16_f32 v146, v52, v4
	ds_write_b32 v174, v146 offset:544
	v_cvt_pk_bf16_f32 v178, v36, v20
	ds_write_b32 v174, v178 offset:672
	v_cvt_pk_bf16_f32 v1, v53, v5
	ds_write_b32 v174, v1 offset:816
	v_cvt_pk_bf16_f32 v146, v37, v21
	ds_write_b32 v174, v146 offset:944
	v_cvt_pk_bf16_f32 v178, v54, v6
	ds_write_b32 v174, v178 offset:1088
	v_cvt_pk_bf16_f32 v1, v38, v22
	ds_write_b32 v174, v1 offset:1216
	v_cvt_pk_bf16_f32 v146, v55, v7
	ds_write_b32 v174, v146 offset:1360
	v_cvt_pk_bf16_f32 v178, v39, v23
	ds_write_b32 v174, v178 offset:1488
	v_cvt_pk_bf16_f32 v1, v56, v8
	ds_write_b32 v174, v1 offset:1632
	v_cvt_pk_bf16_f32 v146, v40, v24
	ds_write_b32 v174, v146 offset:1760
	v_cvt_pk_bf16_f32 v178, v57, v9
	ds_write_b32 v174, v178 offset:1904
	v_cvt_pk_bf16_f32 v1, v41, v25
	ds_write_b32 v174, v1 offset:2032
	v_cvt_pk_bf16_f32 v146, v58, v10
	ds_write_b32 v174, v146 offset:2176
	v_cvt_pk_bf16_f32 v178, v42, v26
	ds_write_b32 v174, v178 offset:2304
	v_cvt_pk_bf16_f32 v1, v59, v11
	ds_write_b32 v174, v1 offset:2448
	v_cvt_pk_bf16_f32 v146, v43, v27
	ds_write_b32 v174, v146 offset:2576
	v_cvt_pk_bf16_f32 v178, v60, v12
	ds_write_b32 v174, v178 offset:2720
	v_cvt_pk_bf16_f32 v1, v44, v28
	ds_write_b32 v174, v1 offset:2848
	v_cvt_pk_bf16_f32 v146, v61, v13
	ds_write_b32 v174, v146 offset:2992
	v_cvt_pk_bf16_f32 v178, v45, v29
	ds_write_b32 v174, v178 offset:3120
	v_cvt_pk_bf16_f32 v1, v62, v14
	ds_write_b32 v174, v1 offset:3264
	v_cvt_pk_bf16_f32 v146, v46, v30
	ds_write_b32 v174, v146 offset:3392
	v_cvt_pk_bf16_f32 v178, v63, v15
	ds_write_b32 v174, v178 offset:3536
	v_cvt_pk_bf16_f32 v1, v47, v31
	ds_write_b32 v174, v1 offset:3664
	v_cvt_pk_bf16_f32 v146, v64, v16
	ds_write_b32 v174, v146 offset:3808
	v_cvt_pk_bf16_f32 v178, v48, v32
	ds_write_b32 v174, v178 offset:3936
	v_cvt_pk_bf16_f32 v1, v65, v17
	ds_write_b32 v174, v1 offset:4080
	v_cvt_pk_bf16_f32 v146, v49, v33
	ds_write_b32 v174, v146 offset:4208
	s_waitcnt lgkmcnt(0)
	ds_read_b128 v[2:5], v175
	ds_read_b128 v[6:9], v175 offset:64
	ds_read_b128 v[10:13], v175 offset:128
	ds_read_b128 v[14:17], v175 offset:192
	ds_read_b128 v[18:21], v175 offset:4352
	ds_read_b128 v[22:25], v175 offset:4416
	ds_read_b128 v[26:29], v175 offset:4480
	ds_read_b128 v[30:33], v175 offset:4544
	s_waitcnt vmcnt(0)
	v_readfirstlane_b32 s101, v149
	s_waitcnt lgkmcnt(7)
	v_mfma_f32_16x16x32_bf16 v[34:37], v[94:97], v[2:5], 0
	s_waitcnt lgkmcnt(6)
	v_mfma_f32_16x16x32_bf16 v[34:37], v[90:93], v[6:9], v[34:37]
	s_waitcnt lgkmcnt(5)
	v_mfma_f32_16x16x32_bf16 v[34:37], v[86:89], v[10:13], v[34:37]
	s_waitcnt lgkmcnt(4)
	v_mfma_f32_16x16x32_bf16 v[34:37], v[82:85], v[14:17], v[34:37]
	s_waitcnt lgkmcnt(3)
	v_mfma_f32_16x16x32_bf16 v[38:41], v[94:97], v[18:21], 0
	s_waitcnt lgkmcnt(2)
	v_mfma_f32_16x16x32_bf16 v[38:41], v[90:93], v[22:25], v[38:41]
	s_waitcnt lgkmcnt(1)
	v_mfma_f32_16x16x32_bf16 v[38:41], v[86:89], v[26:29], v[38:41]
	s_waitcnt lgkmcnt(0)
	v_mfma_f32_16x16x32_bf16 v[38:41], v[82:85], v[30:33], v[38:41]
	v_lshlrev_b32_e32 v42, 16, v160
	v_and_b32_e32 v43, 0xffff0000, v160
	v_lshlrev_b32_e32 v44, 16, v161
	v_and_b32_e32 v45, 0xffff0000, v161
	v_lshlrev_b32_e32 v46, 16, v162
	v_and_b32_e32 v47, 0xffff0000, v162
	v_lshlrev_b32_e32 v48, 16, v163
	v_and_b32_e32 v49, 0xffff0000, v163
	s_nop 1
	v_mov_b32_e32 v156, 0x3d372713
	v_mov_b32_e32 v158, 0xbfcc422a
	v_mov_b32_e32 v164, 0x3fb8aa3b
	v_mov_b32_e32 v168, 1.0
	v_pk_fma_f32 v[50:51], v[98:99], v[42:43], v[34:35]
	v_pk_fma_f32 v[52:53], v[100:101], v[44:45], v[36:37]
	v_pk_fma_f32 v[54:55], v[98:99], v[46:47], v[38:39]
	v_pk_fma_f32 v[56:57], v[100:101], v[48:49], v[40:41]
	v_pk_mul_f32 v[2:3], v[50:51], v[156:157] op_sel_hi:[1,0]
	v_pk_mul_f32 v[4:5], v[52:53], v[156:157] op_sel_hi:[1,0]
	v_pk_mul_f32 v[6:7], v[54:55], v[156:157] op_sel_hi:[1,0]
	v_pk_mul_f32 v[8:9], v[56:57], v[156:157] op_sel_hi:[1,0]
	v_pk_mul_f32 v[2:3], v[50:51], v[2:3]
	v_pk_mul_f32 v[4:5], v[52:53], v[4:5]
	v_pk_mul_f32 v[6:7], v[54:55], v[6:7]
	v_pk_mul_f32 v[8:9], v[56:57], v[8:9]
	v_pk_fma_f32 v[2:3], v[50:51], v[2:3], v[50:51]
	v_pk_fma_f32 v[4:5], v[52:53], v[4:5], v[52:53]
	v_pk_fma_f32 v[6:7], v[54:55], v[6:7], v[54:55]
	v_pk_fma_f32 v[8:9], v[56:57], v[8:9], v[56:57]
	v_pk_mul_f32 v[2:3], v[2:3], v[158:159] op_sel_hi:[1,0]
	v_pk_mul_f32 v[4:5], v[4:5], v[158:159] op_sel_hi:[1,0]
	v_pk_mul_f32 v[6:7], v[6:7], v[158:159] op_sel_hi:[1,0]
	v_pk_mul_f32 v[8:9], v[8:9], v[158:159] op_sel_hi:[1,0]
	v_pk_mul_f32 v[2:3], v[2:3], v[164:165] op_sel_hi:[1,0]
	v_pk_mul_f32 v[4:5], v[4:5], v[164:165] op_sel_hi:[1,0]
	v_pk_mul_f32 v[6:7], v[6:7], v[164:165] op_sel_hi:[1,0]
	v_pk_mul_f32 v[8:9], v[8:9], v[164:165] op_sel_hi:[1,0]
	v_exp_f32_e32 v2, v2
	v_exp_f32_e32 v3, v3
	v_exp_f32_e32 v4, v4
	v_exp_f32_e32 v5, v5
	v_exp_f32_e32 v6, v6
	v_exp_f32_e32 v7, v7
	v_exp_f32_e32 v8, v8
	v_exp_f32_e32 v9, v9
	v_pk_add_f32 v[2:3], v[2:3], v[168:169] op_sel_hi:[1,0]
	v_pk_add_f32 v[4:5], v[4:5], v[168:169] op_sel_hi:[1,0]
	v_pk_add_f32 v[6:7], v[6:7], v[168:169] op_sel_hi:[1,0]
	v_pk_add_f32 v[8:9], v[8:9], v[168:169] op_sel_hi:[1,0]
	v_rcp_f32_e32 v2, v2
	v_rcp_f32_e32 v3, v3
	v_rcp_f32_e32 v4, v4
	v_rcp_f32_e32 v5, v5
	v_rcp_f32_e32 v6, v6
	v_rcp_f32_e32 v7, v7
	v_rcp_f32_e32 v8, v8
	v_rcp_f32_e32 v9, v9
	v_pk_mul_f32 v[50:51], v[50:51], v[2:3]
	v_pk_mul_f32 v[52:53], v[52:53], v[4:5]
	v_pk_mul_f32 v[54:55], v[54:55], v[6:7]
	v_pk_mul_f32 v[56:57], v[56:57], v[8:9]
	v_cvt_pk_bf16_f32 v10, v50, v51
	v_cvt_pk_bf16_f32 v11, v52, v53
	v_cvt_pk_bf16_f32 v12, v54, v55
	v_cvt_pk_bf16_f32 v13, v56, v57
	global_store_dwordx2 v176, v[10:11], s[10:11]
	global_store_dwordx2 v177, v[12:13], s[10:11]
	v_readlane_b32 s4, v252, 61
	v_readlane_b32 s5, v252, 62
	v_cmp_gt_u32_e32 vcc, 32, v148
	v_and_b32_e32 v146, 31, v148
	v_mov_b32_e32 v3, v166
	v_mov_b32_e32 v2, v167
	v_mov_b32_e32 v4, v150
	v_mov_b32_e32 v5, v151
	v_lshlrev_b32_e32 v146, 2, v146
	s_and_b64 s[4:5], s[4:5], vcc
	s_cmp_eq_u32 s70, 31
	s_cselect_b64 s[0:1], -1, 0
	s_and_b64 s[4:5], s[0:1], s[4:5]
	s_and_saveexec_b64 s[0:1], s[4:5]
	s_cbranch_execz .LBB0_1057
	s_lshl_b32 s2, s64, 11
	s_or_b32 s4, s30, s2
	s_ashr_i32 s5, s4, 31
	s_lshl_b64 s[4:5], s[4:5], 2
	v_readlane_b32 s8, v252, 4
	v_readlane_b32 s9, v252, 5
	s_add_u32 s4, s8, s4
	s_addc_u32 s5, s9, s5
	v_lshl_add_u64 v[6:7], s[4:5], 0, v[146:147]
	v_add_co_u32_e32 v8, vcc, 0x8400000, v6
	v_readlane_b32 s10, v252, 6
	s_nop 0
	v_addc_co_u32_e32 v9, vcc, 0, v7, vcc
	v_add_co_u32_e32 v6, vcc, 0x8404000, v6
	v_readlane_b32 s11, v252, 7
	s_nop 0
	v_addc_co_u32_e32 v7, vcc, 0, v7, vcc
	global_store_dword v[8:9], v3, off
	global_store_dword v[6:7], v2, off
	global_store_dword v[8:9], v4, off offset:128
	global_store_dword v[6:7], v5, off offset:128
	s_branch .LBB0_1057
.LBB0_1065:
	s_add_u32 s46, s72, 0x8100
	s_addc_u32 s47, s73, 0
	v_mov_b32_e32 v18, v228
	s_mov_b64 s[0:1], exec
	v_readlane_b32 s2, v252, 45
	v_readlane_b32 s3, v252, 46
	s_and_b64 s[2:3], s[0:1], s[2:3]
	v_readlane_b32 s66, v252, 3
	v_readlane_b32 s67, v252, 47
	s_mov_b64 exec, s[2:3]
	s_cbranch_execz .LBB0_1069
	s_mov_b64 s[6:7], exec
	v_mbcnt_lo_u32_b32 v1, s6, 0
	v_mbcnt_hi_u32_b32 v1, s7, v1
	v_cmp_eq_u32_e32 vcc, 0, v1
	s_and_saveexec_b64 s[4:5], vcc
	s_cbranch_execz .LBB0_1068
	v_mov_b32_e32 v2, s101
